# dprep: hand-scheduled forward substitution and causal conv (LDS/global reads requested ahead, counted waits), same op order
# speedup vs baseline: 1.1535x; 1.0635x over previous
.Lhop_1587:
	s_branch .LBB0_1587
.Lhop_982:
	s_branch .LBB0_982

.LBB0_801:
	s_or_b64 exec, exec, s[2:3]
	v_add3_u32 v0, v123, v0, v9
	s_mov_b32 s44, 0
	v_mov_b32_e32 v9, v179
	v_readfirstlane_b32 s58, v186
	v_readfirstlane_b32 s59, v123
	s_sub_i32 s58, s58, s59
	s_max_i32 s58, s58, 0
	s_min_i32 s58, s58, 32
	s_movk_i32 s56, 0xc00
	s_mov_b32 s57, 0
	s_movk_i32 s11, 0xc00
	v_mad_i64_i32 v[10:11], s[48:49], v0, s11, v[106:107]
	global_load_dword v194, v[10:11], off
	v_lshl_add_u64 v[10:11], v[10:11], 0, s[56:57]
	global_load_dword v195, v[10:11], off
	v_lshl_add_u64 v[10:11], v[10:11], 0, s[56:57]
	global_load_dword v196, v[10:11], off
	v_lshl_add_u64 v[10:11], v[10:11], 0, s[56:57]
	global_load_dword v197, v[10:11], off
	v_lshl_add_u64 v[10:11], v[10:11], 0, s[56:57]
	global_load_dword v198, v[10:11], off
	v_lshl_add_u64 v[10:11], v[10:11], 0, s[56:57]
	global_load_dword v199, v[10:11], off
	v_lshl_add_u64 v[10:11], v[10:11], 0, s[56:57]
	global_load_dword v200, v[10:11], off
	v_lshl_add_u64 v[10:11], v[10:11], 0, s[56:57]
	global_load_dword v201, v[10:11], off
	v_lshl_add_u64 v[10:11], v[10:11], 0, s[56:57]
	global_load_dword v202, v[10:11], off
	v_lshl_add_u64 v[10:11], v[10:11], 0, s[56:57]
	global_load_dword v203, v[10:11], off
	v_lshl_add_u64 v[10:11], v[10:11], 0, s[56:57]
	global_load_dword v204, v[10:11], off
	v_lshl_add_u64 v[10:11], v[10:11], 0, s[56:57]
	global_load_dword v205, v[10:11], off
	v_lshl_add_u64 v[10:11], v[10:11], 0, s[56:57]
	global_load_dword v206, v[10:11], off
	v_lshl_add_u64 v[10:11], v[10:11], 0, s[56:57]
	global_load_dword v207, v[10:11], off
	v_lshl_add_u64 v[10:11], v[10:11], 0, s[56:57]
	global_load_dword v208, v[10:11], off
	v_lshl_add_u64 v[10:11], v[10:11], 0, s[56:57]
	global_load_dword v209, v[10:11], off
	v_lshl_add_u64 v[10:11], v[10:11], 0, s[56:57]
	global_load_dword v210, v[10:11], off
	v_lshl_add_u64 v[10:11], v[10:11], 0, s[56:57]
	global_load_dword v226, v[10:11], off
	v_lshl_add_u64 v[10:11], v[10:11], 0, s[56:57]
	global_load_dword v227, v[10:11], off
	v_lshl_add_u64 v[10:11], v[10:11], 0, s[56:57]
	global_load_dword v228, v[10:11], off
	v_lshl_add_u64 v[10:11], v[10:11], 0, s[56:57]
	global_load_dword v229, v[10:11], off
	v_lshl_add_u64 v[10:11], v[10:11], 0, s[56:57]
	global_load_dword v230, v[10:11], off
	v_lshl_add_u64 v[10:11], v[10:11], 0, s[56:57]
	global_load_dword v231, v[10:11], off
	v_lshl_add_u64 v[10:11], v[10:11], 0, s[56:57]
	global_load_dword v232, v[10:11], off
	v_lshl_add_u64 v[10:11], v[10:11], 0, s[56:57]
	global_load_dword v233, v[10:11], off
	v_lshl_add_u64 v[10:11], v[10:11], 0, s[56:57]
	global_load_dword v234, v[10:11], off
	v_lshl_add_u64 v[10:11], v[10:11], 0, s[56:57]
	global_load_dword v235, v[10:11], off
	v_lshl_add_u64 v[10:11], v[10:11], 0, s[56:57]
	global_load_dword v236, v[10:11], off
	v_lshl_add_u64 v[10:11], v[10:11], 0, s[56:57]
	global_load_dword v237, v[10:11], off
	v_lshl_add_u64 v[10:11], v[10:11], 0, s[56:57]
	global_load_dword v238, v[10:11], off
	v_lshl_add_u64 v[10:11], v[10:11], 0, s[56:57]
	global_load_dword v239, v[10:11], off
	v_lshl_add_u64 v[10:11], v[10:11], 0, s[56:57]
	global_load_dword v240, v[10:11], off
	v_lshl_add_u64 v[10:11], v[10:11], 0, s[56:57]
	v_mov_b32_e32 v14, v2
	v_mov_b32_e32 v15, v6
	v_mov_b32_e32 v16, v3
	v_mov_b32_e32 v17, v7
	v_mov_b32_e32 v108, v4
	v_mov_b32_e32 v109, v8
	s_waitcnt vmcnt(31)
	v_lshlrev_b32_e32 v110, 16, v194
	v_and_b32_e32 v111, 0xffff0000, v194
	v_pk_mul_f32 v[112:113], v[100:101], v[16:17]
	v_pk_fma_f32 v[112:113], v[98:99], v[14:15], v[112:113]
	v_pk_fma_f32 v[112:113], v[102:103], v[108:109], v[112:113]
	v_pk_fma_f32 v[112:113], v[104:105], v[110:111], v[112:113]
	s_cmp_gt_u32 s58, 0
	s_cselect_b32 s60, -1, 0
	v_mul_f32_e32 v114, 0xbfb8aa3b, v112
	v_mul_f32_e32 v115, 0xbfb8aa3b, v113
	v_exp_f32_e32 v114, v114
	v_exp_f32_e32 v115, v115
	s_nop 0
	v_add_f32_e32 v114, 1.0, v114
	v_add_f32_e32 v115, 1.0, v115
	v_rcp_f32_e32 v114, v114
	v_rcp_f32_e32 v115, v115
	s_nop 0
	v_pk_mul_f32 v[114:115], v[112:113], v[114:115]
	v_and_b32_e32 v114, s60, v114
	v_and_b32_e32 v115, s60, v115
	ds_write_b64 v9, v[114:115] offset:0
	s_waitcnt vmcnt(30)
	v_lshlrev_b32_e32 v14, 16, v195
	v_and_b32_e32 v15, 0xffff0000, v195
	v_pk_mul_f32 v[112:113], v[100:101], v[108:109]
	v_pk_fma_f32 v[112:113], v[98:99], v[16:17], v[112:113]
	v_pk_fma_f32 v[112:113], v[102:103], v[110:111], v[112:113]
	v_pk_fma_f32 v[112:113], v[104:105], v[14:15], v[112:113]
	s_cmp_gt_u32 s58, 1
	s_cselect_b32 s60, -1, 0
	v_mul_f32_e32 v114, 0xbfb8aa3b, v112
	v_mul_f32_e32 v115, 0xbfb8aa3b, v113
	v_exp_f32_e32 v114, v114
	v_exp_f32_e32 v115, v115
	s_nop 0
	v_add_f32_e32 v114, 1.0, v114
	v_add_f32_e32 v115, 1.0, v115
	v_rcp_f32_e32 v114, v114
	v_rcp_f32_e32 v115, v115
	s_nop 0
	v_pk_mul_f32 v[114:115], v[112:113], v[114:115]
	v_and_b32_e32 v114, s60, v114
	v_and_b32_e32 v115, s60, v115
	ds_write_b64 v9, v[114:115] offset:1552
	s_waitcnt vmcnt(29)
	v_lshlrev_b32_e32 v16, 16, v196
	v_and_b32_e32 v17, 0xffff0000, v196
	v_pk_mul_f32 v[112:113], v[100:101], v[110:111]
	v_pk_fma_f32 v[112:113], v[98:99], v[108:109], v[112:113]
	v_pk_fma_f32 v[112:113], v[102:103], v[14:15], v[112:113]
	v_pk_fma_f32 v[112:113], v[104:105], v[16:17], v[112:113]
	s_cmp_gt_u32 s58, 2
	s_cselect_b32 s60, -1, 0
	v_mul_f32_e32 v114, 0xbfb8aa3b, v112
	v_mul_f32_e32 v115, 0xbfb8aa3b, v113
	v_exp_f32_e32 v114, v114
	v_exp_f32_e32 v115, v115
	s_nop 0
	v_add_f32_e32 v114, 1.0, v114
	v_add_f32_e32 v115, 1.0, v115
	v_rcp_f32_e32 v114, v114
	v_rcp_f32_e32 v115, v115
	s_nop 0
	v_pk_mul_f32 v[114:115], v[112:113], v[114:115]
	v_and_b32_e32 v114, s60, v114
	v_and_b32_e32 v115, s60, v115
	ds_write_b64 v9, v[114:115] offset:3104
	s_waitcnt vmcnt(28)
	v_lshlrev_b32_e32 v108, 16, v197
	v_and_b32_e32 v109, 0xffff0000, v197
	v_pk_mul_f32 v[112:113], v[100:101], v[14:15]
	v_pk_fma_f32 v[112:113], v[98:99], v[110:111], v[112:113]
	v_pk_fma_f32 v[112:113], v[102:103], v[16:17], v[112:113]
	v_pk_fma_f32 v[112:113], v[104:105], v[108:109], v[112:113]
	s_cmp_gt_u32 s58, 3
	s_cselect_b32 s60, -1, 0
	v_mul_f32_e32 v114, 0xbfb8aa3b, v112
	v_mul_f32_e32 v115, 0xbfb8aa3b, v113
	v_exp_f32_e32 v114, v114
	v_exp_f32_e32 v115, v115
	s_nop 0
	v_add_f32_e32 v114, 1.0, v114
	v_add_f32_e32 v115, 1.0, v115
	v_rcp_f32_e32 v114, v114
	v_rcp_f32_e32 v115, v115
	s_nop 0
	v_pk_mul_f32 v[114:115], v[112:113], v[114:115]
	v_and_b32_e32 v114, s60, v114
	v_and_b32_e32 v115, s60, v115
	ds_write_b64 v9, v[114:115] offset:4656
	s_waitcnt vmcnt(27)
	v_lshlrev_b32_e32 v110, 16, v198
	v_and_b32_e32 v111, 0xffff0000, v198
	v_pk_mul_f32 v[112:113], v[100:101], v[16:17]
	v_pk_fma_f32 v[112:113], v[98:99], v[14:15], v[112:113]
	v_pk_fma_f32 v[112:113], v[102:103], v[108:109], v[112:113]
	v_pk_fma_f32 v[112:113], v[104:105], v[110:111], v[112:113]
	s_cmp_gt_u32 s58, 4
	s_cselect_b32 s60, -1, 0
	v_mul_f32_e32 v114, 0xbfb8aa3b, v112
	v_mul_f32_e32 v115, 0xbfb8aa3b, v113
	v_exp_f32_e32 v114, v114
	v_exp_f32_e32 v115, v115
	s_nop 0
	v_add_f32_e32 v114, 1.0, v114
	v_add_f32_e32 v115, 1.0, v115
	v_rcp_f32_e32 v114, v114
	v_rcp_f32_e32 v115, v115
	s_nop 0
	v_pk_mul_f32 v[114:115], v[112:113], v[114:115]
	v_and_b32_e32 v114, s60, v114
	v_and_b32_e32 v115, s60, v115
	ds_write_b64 v9, v[114:115] offset:6208
	s_waitcnt vmcnt(26)
	v_lshlrev_b32_e32 v14, 16, v199
	v_and_b32_e32 v15, 0xffff0000, v199
	v_pk_mul_f32 v[112:113], v[100:101], v[108:109]
	v_pk_fma_f32 v[112:113], v[98:99], v[16:17], v[112:113]
	v_pk_fma_f32 v[112:113], v[102:103], v[110:111], v[112:113]
	v_pk_fma_f32 v[112:113], v[104:105], v[14:15], v[112:113]
	s_cmp_gt_u32 s58, 5
	s_cselect_b32 s60, -1, 0
	v_mul_f32_e32 v114, 0xbfb8aa3b, v112
	v_mul_f32_e32 v115, 0xbfb8aa3b, v113
	v_exp_f32_e32 v114, v114
	v_exp_f32_e32 v115, v115
	s_nop 0
	v_add_f32_e32 v114, 1.0, v114
	v_add_f32_e32 v115, 1.0, v115
	v_rcp_f32_e32 v114, v114
	v_rcp_f32_e32 v115, v115
	s_nop 0
	v_pk_mul_f32 v[114:115], v[112:113], v[114:115]
	v_and_b32_e32 v114, s60, v114
	v_and_b32_e32 v115, s60, v115
	ds_write_b64 v9, v[114:115] offset:7760
	s_waitcnt vmcnt(25)
	v_lshlrev_b32_e32 v16, 16, v200
	v_and_b32_e32 v17, 0xffff0000, v200
	v_pk_mul_f32 v[112:113], v[100:101], v[110:111]
	v_pk_fma_f32 v[112:113], v[98:99], v[108:109], v[112:113]
	v_pk_fma_f32 v[112:113], v[102:103], v[14:15], v[112:113]
	v_pk_fma_f32 v[112:113], v[104:105], v[16:17], v[112:113]
	s_cmp_gt_u32 s58, 6
	s_cselect_b32 s60, -1, 0
	v_mul_f32_e32 v114, 0xbfb8aa3b, v112
	v_mul_f32_e32 v115, 0xbfb8aa3b, v113
	v_exp_f32_e32 v114, v114
	v_exp_f32_e32 v115, v115
	s_nop 0
	v_add_f32_e32 v114, 1.0, v114
	v_add_f32_e32 v115, 1.0, v115
	v_rcp_f32_e32 v114, v114
	v_rcp_f32_e32 v115, v115
	s_nop 0
	v_pk_mul_f32 v[114:115], v[112:113], v[114:115]
	v_and_b32_e32 v114, s60, v114
	v_and_b32_e32 v115, s60, v115
	ds_write_b64 v9, v[114:115] offset:9312
	s_waitcnt vmcnt(24)
	v_lshlrev_b32_e32 v108, 16, v201
	v_and_b32_e32 v109, 0xffff0000, v201
	v_pk_mul_f32 v[112:113], v[100:101], v[14:15]
	v_pk_fma_f32 v[112:113], v[98:99], v[110:111], v[112:113]
	v_pk_fma_f32 v[112:113], v[102:103], v[16:17], v[112:113]
	v_pk_fma_f32 v[112:113], v[104:105], v[108:109], v[112:113]
	s_cmp_gt_u32 s58, 7
	s_cselect_b32 s60, -1, 0
	v_mul_f32_e32 v114, 0xbfb8aa3b, v112
	v_mul_f32_e32 v115, 0xbfb8aa3b, v113
	v_exp_f32_e32 v114, v114
	v_exp_f32_e32 v115, v115
	s_nop 0
	v_add_f32_e32 v114, 1.0, v114
	v_add_f32_e32 v115, 1.0, v115
	v_rcp_f32_e32 v114, v114
	v_rcp_f32_e32 v115, v115
	s_nop 0
	v_pk_mul_f32 v[114:115], v[112:113], v[114:115]
	v_and_b32_e32 v114, s60, v114
	v_and_b32_e32 v115, s60, v115
	ds_write_b64 v9, v[114:115] offset:10864
	s_waitcnt vmcnt(23)
	v_lshlrev_b32_e32 v110, 16, v202
	v_and_b32_e32 v111, 0xffff0000, v202
	v_pk_mul_f32 v[112:113], v[100:101], v[16:17]
	v_pk_fma_f32 v[112:113], v[98:99], v[14:15], v[112:113]
	v_pk_fma_f32 v[112:113], v[102:103], v[108:109], v[112:113]
	v_pk_fma_f32 v[112:113], v[104:105], v[110:111], v[112:113]
	s_cmp_gt_u32 s58, 8
	s_cselect_b32 s60, -1, 0
	v_mul_f32_e32 v114, 0xbfb8aa3b, v112
	v_mul_f32_e32 v115, 0xbfb8aa3b, v113
	v_exp_f32_e32 v114, v114
	v_exp_f32_e32 v115, v115
	s_nop 0
	v_add_f32_e32 v114, 1.0, v114
	v_add_f32_e32 v115, 1.0, v115
	v_rcp_f32_e32 v114, v114
	v_rcp_f32_e32 v115, v115
	s_nop 0
	v_pk_mul_f32 v[114:115], v[112:113], v[114:115]
	v_and_b32_e32 v114, s60, v114
	v_and_b32_e32 v115, s60, v115
	ds_write_b64 v9, v[114:115] offset:12416
	s_waitcnt vmcnt(22)
	v_lshlrev_b32_e32 v14, 16, v203
	v_and_b32_e32 v15, 0xffff0000, v203
	v_pk_mul_f32 v[112:113], v[100:101], v[108:109]
	v_pk_fma_f32 v[112:113], v[98:99], v[16:17], v[112:113]
	v_pk_fma_f32 v[112:113], v[102:103], v[110:111], v[112:113]
	v_pk_fma_f32 v[112:113], v[104:105], v[14:15], v[112:113]
	s_cmp_gt_u32 s58, 9
	s_cselect_b32 s60, -1, 0
	v_mul_f32_e32 v114, 0xbfb8aa3b, v112
	v_mul_f32_e32 v115, 0xbfb8aa3b, v113
	v_exp_f32_e32 v114, v114
	v_exp_f32_e32 v115, v115
	s_nop 0
	v_add_f32_e32 v114, 1.0, v114
	v_add_f32_e32 v115, 1.0, v115
	v_rcp_f32_e32 v114, v114
	v_rcp_f32_e32 v115, v115
	s_nop 0
	v_pk_mul_f32 v[114:115], v[112:113], v[114:115]
	v_and_b32_e32 v114, s60, v114
	v_and_b32_e32 v115, s60, v115
	ds_write_b64 v9, v[114:115] offset:13968
	s_waitcnt vmcnt(21)
	v_lshlrev_b32_e32 v16, 16, v204
	v_and_b32_e32 v17, 0xffff0000, v204
	v_pk_mul_f32 v[112:113], v[100:101], v[110:111]
	v_pk_fma_f32 v[112:113], v[98:99], v[108:109], v[112:113]
	v_pk_fma_f32 v[112:113], v[102:103], v[14:15], v[112:113]
	v_pk_fma_f32 v[112:113], v[104:105], v[16:17], v[112:113]
	s_cmp_gt_u32 s58, 10
	s_cselect_b32 s60, -1, 0
	v_mul_f32_e32 v114, 0xbfb8aa3b, v112
	v_mul_f32_e32 v115, 0xbfb8aa3b, v113
	v_exp_f32_e32 v114, v114
	v_exp_f32_e32 v115, v115
	s_nop 0
	v_add_f32_e32 v114, 1.0, v114
	v_add_f32_e32 v115, 1.0, v115
	v_rcp_f32_e32 v114, v114
	v_rcp_f32_e32 v115, v115
	s_nop 0
	v_pk_mul_f32 v[114:115], v[112:113], v[114:115]
	v_and_b32_e32 v114, s60, v114
	v_and_b32_e32 v115, s60, v115
	ds_write_b64 v9, v[114:115] offset:15520
	s_waitcnt vmcnt(20)
	v_lshlrev_b32_e32 v108, 16, v205
	v_and_b32_e32 v109, 0xffff0000, v205
	v_pk_mul_f32 v[112:113], v[100:101], v[14:15]
	v_pk_fma_f32 v[112:113], v[98:99], v[110:111], v[112:113]
	v_pk_fma_f32 v[112:113], v[102:103], v[16:17], v[112:113]
	v_pk_fma_f32 v[112:113], v[104:105], v[108:109], v[112:113]
	s_cmp_gt_u32 s58, 11
	s_cselect_b32 s60, -1, 0
	v_mul_f32_e32 v114, 0xbfb8aa3b, v112
	v_mul_f32_e32 v115, 0xbfb8aa3b, v113
	v_exp_f32_e32 v114, v114
	v_exp_f32_e32 v115, v115
	s_nop 0
	v_add_f32_e32 v114, 1.0, v114
	v_add_f32_e32 v115, 1.0, v115
	v_rcp_f32_e32 v114, v114
	v_rcp_f32_e32 v115, v115
	s_nop 0
	v_pk_mul_f32 v[114:115], v[112:113], v[114:115]
	v_and_b32_e32 v114, s60, v114
	v_and_b32_e32 v115, s60, v115
	ds_write_b64 v9, v[114:115] offset:17072
	s_waitcnt vmcnt(19)
	v_lshlrev_b32_e32 v110, 16, v206
	v_and_b32_e32 v111, 0xffff0000, v206
	v_pk_mul_f32 v[112:113], v[100:101], v[16:17]
	v_pk_fma_f32 v[112:113], v[98:99], v[14:15], v[112:113]
	v_pk_fma_f32 v[112:113], v[102:103], v[108:109], v[112:113]
	v_pk_fma_f32 v[112:113], v[104:105], v[110:111], v[112:113]
	s_cmp_gt_u32 s58, 12
	s_cselect_b32 s60, -1, 0
	v_mul_f32_e32 v114, 0xbfb8aa3b, v112
	v_mul_f32_e32 v115, 0xbfb8aa3b, v113
	v_exp_f32_e32 v114, v114
	v_exp_f32_e32 v115, v115
	s_nop 0
	v_add_f32_e32 v114, 1.0, v114
	v_add_f32_e32 v115, 1.0, v115
	v_rcp_f32_e32 v114, v114
	v_rcp_f32_e32 v115, v115
	s_nop 0
	v_pk_mul_f32 v[114:115], v[112:113], v[114:115]
	v_and_b32_e32 v114, s60, v114
	v_and_b32_e32 v115, s60, v115
	ds_write_b64 v9, v[114:115] offset:18624
	s_waitcnt vmcnt(18)
	v_lshlrev_b32_e32 v14, 16, v207
	v_and_b32_e32 v15, 0xffff0000, v207
	v_pk_mul_f32 v[112:113], v[100:101], v[108:109]
	v_pk_fma_f32 v[112:113], v[98:99], v[16:17], v[112:113]
	v_pk_fma_f32 v[112:113], v[102:103], v[110:111], v[112:113]
	v_pk_fma_f32 v[112:113], v[104:105], v[14:15], v[112:113]
	s_cmp_gt_u32 s58, 13
	s_cselect_b32 s60, -1, 0
	v_mul_f32_e32 v114, 0xbfb8aa3b, v112
	v_mul_f32_e32 v115, 0xbfb8aa3b, v113
	v_exp_f32_e32 v114, v114
	v_exp_f32_e32 v115, v115
	s_nop 0
	v_add_f32_e32 v114, 1.0, v114
	v_add_f32_e32 v115, 1.0, v115
	v_rcp_f32_e32 v114, v114
	v_rcp_f32_e32 v115, v115
	s_nop 0
	v_pk_mul_f32 v[114:115], v[112:113], v[114:115]
	v_and_b32_e32 v114, s60, v114
	v_and_b32_e32 v115, s60, v115
	ds_write_b64 v9, v[114:115] offset:20176
	s_waitcnt vmcnt(17)
	v_lshlrev_b32_e32 v16, 16, v208
	v_and_b32_e32 v17, 0xffff0000, v208
	v_pk_mul_f32 v[112:113], v[100:101], v[110:111]
	v_pk_fma_f32 v[112:113], v[98:99], v[108:109], v[112:113]
	v_pk_fma_f32 v[112:113], v[102:103], v[14:15], v[112:113]
	v_pk_fma_f32 v[112:113], v[104:105], v[16:17], v[112:113]
	s_cmp_gt_u32 s58, 14
	s_cselect_b32 s60, -1, 0
	v_mul_f32_e32 v114, 0xbfb8aa3b, v112
	v_mul_f32_e32 v115, 0xbfb8aa3b, v113
	v_exp_f32_e32 v114, v114
	v_exp_f32_e32 v115, v115
	s_nop 0
	v_add_f32_e32 v114, 1.0, v114
	v_add_f32_e32 v115, 1.0, v115
	v_rcp_f32_e32 v114, v114
	v_rcp_f32_e32 v115, v115
	s_nop 0
	v_pk_mul_f32 v[114:115], v[112:113], v[114:115]
	v_and_b32_e32 v114, s60, v114
	v_and_b32_e32 v115, s60, v115
	ds_write_b64 v9, v[114:115] offset:21728
	s_waitcnt vmcnt(16)
	v_lshlrev_b32_e32 v108, 16, v209
	v_and_b32_e32 v109, 0xffff0000, v209
	v_pk_mul_f32 v[112:113], v[100:101], v[14:15]
	v_pk_fma_f32 v[112:113], v[98:99], v[110:111], v[112:113]
	v_pk_fma_f32 v[112:113], v[102:103], v[16:17], v[112:113]
	v_pk_fma_f32 v[112:113], v[104:105], v[108:109], v[112:113]
	s_cmp_gt_u32 s58, 15
	s_cselect_b32 s60, -1, 0
	v_mul_f32_e32 v114, 0xbfb8aa3b, v112
	v_mul_f32_e32 v115, 0xbfb8aa3b, v113
	v_exp_f32_e32 v114, v114
	v_exp_f32_e32 v115, v115
	s_nop 0
	v_add_f32_e32 v114, 1.0, v114
	v_add_f32_e32 v115, 1.0, v115
	v_rcp_f32_e32 v114, v114
	v_rcp_f32_e32 v115, v115
	s_nop 0
	v_pk_mul_f32 v[114:115], v[112:113], v[114:115]
	v_and_b32_e32 v114, s60, v114
	v_and_b32_e32 v115, s60, v115
	ds_write_b64 v9, v[114:115] offset:23280
	s_waitcnt vmcnt(15)
	v_lshlrev_b32_e32 v110, 16, v210
	v_and_b32_e32 v111, 0xffff0000, v210
	v_pk_mul_f32 v[112:113], v[100:101], v[16:17]
	v_pk_fma_f32 v[112:113], v[98:99], v[14:15], v[112:113]
	v_pk_fma_f32 v[112:113], v[102:103], v[108:109], v[112:113]
	v_pk_fma_f32 v[112:113], v[104:105], v[110:111], v[112:113]
	s_cmp_gt_u32 s58, 16
	s_cselect_b32 s60, -1, 0
	v_mul_f32_e32 v114, 0xbfb8aa3b, v112
	v_mul_f32_e32 v115, 0xbfb8aa3b, v113
	v_exp_f32_e32 v114, v114
	v_exp_f32_e32 v115, v115
	s_nop 0
	v_add_f32_e32 v114, 1.0, v114
	v_add_f32_e32 v115, 1.0, v115
	v_rcp_f32_e32 v114, v114
	v_rcp_f32_e32 v115, v115
	s_nop 0
	v_pk_mul_f32 v[114:115], v[112:113], v[114:115]
	v_and_b32_e32 v114, s60, v114
	v_and_b32_e32 v115, s60, v115
	ds_write_b64 v9, v[114:115] offset:24832
	s_waitcnt vmcnt(14)
	v_lshlrev_b32_e32 v14, 16, v226
	v_and_b32_e32 v15, 0xffff0000, v226
	v_pk_mul_f32 v[112:113], v[100:101], v[108:109]
	v_pk_fma_f32 v[112:113], v[98:99], v[16:17], v[112:113]
	v_pk_fma_f32 v[112:113], v[102:103], v[110:111], v[112:113]
	v_pk_fma_f32 v[112:113], v[104:105], v[14:15], v[112:113]
	s_cmp_gt_u32 s58, 17
	s_cselect_b32 s60, -1, 0
	v_mul_f32_e32 v114, 0xbfb8aa3b, v112
	v_mul_f32_e32 v115, 0xbfb8aa3b, v113
	v_exp_f32_e32 v114, v114
	v_exp_f32_e32 v115, v115
	s_nop 0
	v_add_f32_e32 v114, 1.0, v114
	v_add_f32_e32 v115, 1.0, v115
	v_rcp_f32_e32 v114, v114
	v_rcp_f32_e32 v115, v115
	s_nop 0
	v_pk_mul_f32 v[114:115], v[112:113], v[114:115]
	v_and_b32_e32 v114, s60, v114
	v_and_b32_e32 v115, s60, v115
	ds_write_b64 v9, v[114:115] offset:26384
	s_waitcnt vmcnt(13)
	v_lshlrev_b32_e32 v16, 16, v227
	v_and_b32_e32 v17, 0xffff0000, v227
	v_pk_mul_f32 v[112:113], v[100:101], v[110:111]
	v_pk_fma_f32 v[112:113], v[98:99], v[108:109], v[112:113]
	v_pk_fma_f32 v[112:113], v[102:103], v[14:15], v[112:113]
	v_pk_fma_f32 v[112:113], v[104:105], v[16:17], v[112:113]
	s_cmp_gt_u32 s58, 18
	s_cselect_b32 s60, -1, 0
	v_mul_f32_e32 v114, 0xbfb8aa3b, v112
	v_mul_f32_e32 v115, 0xbfb8aa3b, v113
	v_exp_f32_e32 v114, v114
	v_exp_f32_e32 v115, v115
	s_nop 0
	v_add_f32_e32 v114, 1.0, v114
	v_add_f32_e32 v115, 1.0, v115
	v_rcp_f32_e32 v114, v114
	v_rcp_f32_e32 v115, v115
	s_nop 0
	v_pk_mul_f32 v[114:115], v[112:113], v[114:115]
	v_and_b32_e32 v114, s60, v114
	v_and_b32_e32 v115, s60, v115
	ds_write_b64 v9, v[114:115] offset:27936
	s_waitcnt vmcnt(12)
	v_lshlrev_b32_e32 v108, 16, v228
	v_and_b32_e32 v109, 0xffff0000, v228
	v_pk_mul_f32 v[112:113], v[100:101], v[14:15]
	v_pk_fma_f32 v[112:113], v[98:99], v[110:111], v[112:113]
	v_pk_fma_f32 v[112:113], v[102:103], v[16:17], v[112:113]
	v_pk_fma_f32 v[112:113], v[104:105], v[108:109], v[112:113]
	s_cmp_gt_u32 s58, 19
	s_cselect_b32 s60, -1, 0
	v_mul_f32_e32 v114, 0xbfb8aa3b, v112
	v_mul_f32_e32 v115, 0xbfb8aa3b, v113
	v_exp_f32_e32 v114, v114
	v_exp_f32_e32 v115, v115
	s_nop 0
	v_add_f32_e32 v114, 1.0, v114
	v_add_f32_e32 v115, 1.0, v115
	v_rcp_f32_e32 v114, v114
	v_rcp_f32_e32 v115, v115
	s_nop 0
	v_pk_mul_f32 v[114:115], v[112:113], v[114:115]
	v_and_b32_e32 v114, s60, v114
	v_and_b32_e32 v115, s60, v115
	ds_write_b64 v9, v[114:115] offset:29488
	s_waitcnt vmcnt(11)
	v_lshlrev_b32_e32 v110, 16, v229
	v_and_b32_e32 v111, 0xffff0000, v229
	v_pk_mul_f32 v[112:113], v[100:101], v[16:17]
	v_pk_fma_f32 v[112:113], v[98:99], v[14:15], v[112:113]
	v_pk_fma_f32 v[112:113], v[102:103], v[108:109], v[112:113]
	v_pk_fma_f32 v[112:113], v[104:105], v[110:111], v[112:113]
	s_cmp_gt_u32 s58, 20
	s_cselect_b32 s60, -1, 0
	v_mul_f32_e32 v114, 0xbfb8aa3b, v112
	v_mul_f32_e32 v115, 0xbfb8aa3b, v113
	v_exp_f32_e32 v114, v114
	v_exp_f32_e32 v115, v115
	s_nop 0
	v_add_f32_e32 v114, 1.0, v114
	v_add_f32_e32 v115, 1.0, v115
	v_rcp_f32_e32 v114, v114
	v_rcp_f32_e32 v115, v115
	s_nop 0
	v_pk_mul_f32 v[114:115], v[112:113], v[114:115]
	v_and_b32_e32 v114, s60, v114
	v_and_b32_e32 v115, s60, v115
	ds_write_b64 v9, v[114:115] offset:31040
	s_waitcnt vmcnt(10)
	v_lshlrev_b32_e32 v14, 16, v230
	v_and_b32_e32 v15, 0xffff0000, v230
	v_pk_mul_f32 v[112:113], v[100:101], v[108:109]
	v_pk_fma_f32 v[112:113], v[98:99], v[16:17], v[112:113]
	v_pk_fma_f32 v[112:113], v[102:103], v[110:111], v[112:113]
	v_pk_fma_f32 v[112:113], v[104:105], v[14:15], v[112:113]
	s_cmp_gt_u32 s58, 21
	s_cselect_b32 s60, -1, 0
	v_mul_f32_e32 v114, 0xbfb8aa3b, v112
	v_mul_f32_e32 v115, 0xbfb8aa3b, v113
	v_exp_f32_e32 v114, v114
	v_exp_f32_e32 v115, v115
	s_nop 0
	v_add_f32_e32 v114, 1.0, v114
	v_add_f32_e32 v115, 1.0, v115
	v_rcp_f32_e32 v114, v114
	v_rcp_f32_e32 v115, v115
	s_nop 0
	v_pk_mul_f32 v[114:115], v[112:113], v[114:115]
	v_and_b32_e32 v114, s60, v114
	v_and_b32_e32 v115, s60, v115
	ds_write_b64 v9, v[114:115] offset:32592
	s_waitcnt vmcnt(9)
	v_lshlrev_b32_e32 v16, 16, v231
	v_and_b32_e32 v17, 0xffff0000, v231
	v_pk_mul_f32 v[112:113], v[100:101], v[110:111]
	v_pk_fma_f32 v[112:113], v[98:99], v[108:109], v[112:113]
	v_pk_fma_f32 v[112:113], v[102:103], v[14:15], v[112:113]
	v_pk_fma_f32 v[112:113], v[104:105], v[16:17], v[112:113]
	s_cmp_gt_u32 s58, 22
	s_cselect_b32 s60, -1, 0
	v_mul_f32_e32 v114, 0xbfb8aa3b, v112
	v_mul_f32_e32 v115, 0xbfb8aa3b, v113
	v_exp_f32_e32 v114, v114
	v_exp_f32_e32 v115, v115
	s_nop 0
	v_add_f32_e32 v114, 1.0, v114
	v_add_f32_e32 v115, 1.0, v115
	v_rcp_f32_e32 v114, v114
	v_rcp_f32_e32 v115, v115
	s_nop 0
	v_pk_mul_f32 v[114:115], v[112:113], v[114:115]
	v_and_b32_e32 v114, s60, v114
	v_and_b32_e32 v115, s60, v115
	ds_write_b64 v9, v[114:115] offset:34144
	s_waitcnt vmcnt(8)
	v_lshlrev_b32_e32 v108, 16, v232
	v_and_b32_e32 v109, 0xffff0000, v232
	v_pk_mul_f32 v[112:113], v[100:101], v[14:15]
	v_pk_fma_f32 v[112:113], v[98:99], v[110:111], v[112:113]
	v_pk_fma_f32 v[112:113], v[102:103], v[16:17], v[112:113]
	v_pk_fma_f32 v[112:113], v[104:105], v[108:109], v[112:113]
	s_cmp_gt_u32 s58, 23
	s_cselect_b32 s60, -1, 0
	v_mul_f32_e32 v114, 0xbfb8aa3b, v112
	v_mul_f32_e32 v115, 0xbfb8aa3b, v113
	v_exp_f32_e32 v114, v114
	v_exp_f32_e32 v115, v115
	s_nop 0
	v_add_f32_e32 v114, 1.0, v114
	v_add_f32_e32 v115, 1.0, v115
	v_rcp_f32_e32 v114, v114
	v_rcp_f32_e32 v115, v115
	s_nop 0
	v_pk_mul_f32 v[114:115], v[112:113], v[114:115]
	v_and_b32_e32 v114, s60, v114
	v_and_b32_e32 v115, s60, v115
	ds_write_b64 v9, v[114:115] offset:35696
	s_waitcnt vmcnt(7)
	v_lshlrev_b32_e32 v110, 16, v233
	v_and_b32_e32 v111, 0xffff0000, v233
	v_pk_mul_f32 v[112:113], v[100:101], v[16:17]
	v_pk_fma_f32 v[112:113], v[98:99], v[14:15], v[112:113]
	v_pk_fma_f32 v[112:113], v[102:103], v[108:109], v[112:113]
	v_pk_fma_f32 v[112:113], v[104:105], v[110:111], v[112:113]
	s_cmp_gt_u32 s58, 24
	s_cselect_b32 s60, -1, 0
	v_mul_f32_e32 v114, 0xbfb8aa3b, v112
	v_mul_f32_e32 v115, 0xbfb8aa3b, v113
	v_exp_f32_e32 v114, v114
	v_exp_f32_e32 v115, v115
	s_nop 0
	v_add_f32_e32 v114, 1.0, v114
	v_add_f32_e32 v115, 1.0, v115
	v_rcp_f32_e32 v114, v114
	v_rcp_f32_e32 v115, v115
	s_nop 0
	v_pk_mul_f32 v[114:115], v[112:113], v[114:115]
	v_and_b32_e32 v114, s60, v114
	v_and_b32_e32 v115, s60, v115
	ds_write_b64 v9, v[114:115] offset:37248
	s_waitcnt vmcnt(6)
	v_lshlrev_b32_e32 v14, 16, v234
	v_and_b32_e32 v15, 0xffff0000, v234
	v_pk_mul_f32 v[112:113], v[100:101], v[108:109]
	v_pk_fma_f32 v[112:113], v[98:99], v[16:17], v[112:113]
	v_pk_fma_f32 v[112:113], v[102:103], v[110:111], v[112:113]
	v_pk_fma_f32 v[112:113], v[104:105], v[14:15], v[112:113]
	s_cmp_gt_u32 s58, 25
	s_cselect_b32 s60, -1, 0
	v_mul_f32_e32 v114, 0xbfb8aa3b, v112
	v_mul_f32_e32 v115, 0xbfb8aa3b, v113
	v_exp_f32_e32 v114, v114
	v_exp_f32_e32 v115, v115
	s_nop 0
	v_add_f32_e32 v114, 1.0, v114
	v_add_f32_e32 v115, 1.0, v115
	v_rcp_f32_e32 v114, v114
	v_rcp_f32_e32 v115, v115
	s_nop 0
	v_pk_mul_f32 v[114:115], v[112:113], v[114:115]
	v_and_b32_e32 v114, s60, v114
	v_and_b32_e32 v115, s60, v115
	ds_write_b64 v9, v[114:115] offset:38800
	s_waitcnt vmcnt(5)
	v_lshlrev_b32_e32 v16, 16, v235
	v_and_b32_e32 v17, 0xffff0000, v235
	v_pk_mul_f32 v[112:113], v[100:101], v[110:111]
	v_pk_fma_f32 v[112:113], v[98:99], v[108:109], v[112:113]
	v_pk_fma_f32 v[112:113], v[102:103], v[14:15], v[112:113]
	v_pk_fma_f32 v[112:113], v[104:105], v[16:17], v[112:113]
	s_cmp_gt_u32 s58, 26
	s_cselect_b32 s60, -1, 0
	v_mul_f32_e32 v114, 0xbfb8aa3b, v112
	v_mul_f32_e32 v115, 0xbfb8aa3b, v113
	v_exp_f32_e32 v114, v114
	v_exp_f32_e32 v115, v115
	s_nop 0
	v_add_f32_e32 v114, 1.0, v114
	v_add_f32_e32 v115, 1.0, v115
	v_rcp_f32_e32 v114, v114
	v_rcp_f32_e32 v115, v115
	s_nop 0
	v_pk_mul_f32 v[114:115], v[112:113], v[114:115]
	v_and_b32_e32 v114, s60, v114
	v_and_b32_e32 v115, s60, v115
	ds_write_b64 v9, v[114:115] offset:40352
	s_waitcnt vmcnt(4)
	v_lshlrev_b32_e32 v108, 16, v236
	v_and_b32_e32 v109, 0xffff0000, v236
	v_pk_mul_f32 v[112:113], v[100:101], v[14:15]
	v_pk_fma_f32 v[112:113], v[98:99], v[110:111], v[112:113]
	v_pk_fma_f32 v[112:113], v[102:103], v[16:17], v[112:113]
	v_pk_fma_f32 v[112:113], v[104:105], v[108:109], v[112:113]
	s_cmp_gt_u32 s58, 27
	s_cselect_b32 s60, -1, 0
	v_mul_f32_e32 v114, 0xbfb8aa3b, v112
	v_mul_f32_e32 v115, 0xbfb8aa3b, v113
	v_exp_f32_e32 v114, v114
	v_exp_f32_e32 v115, v115
	s_nop 0
	v_add_f32_e32 v114, 1.0, v114
	v_add_f32_e32 v115, 1.0, v115
	v_rcp_f32_e32 v114, v114
	v_rcp_f32_e32 v115, v115
	s_nop 0
	v_pk_mul_f32 v[114:115], v[112:113], v[114:115]
	v_and_b32_e32 v114, s60, v114
	v_and_b32_e32 v115, s60, v115
	ds_write_b64 v9, v[114:115] offset:41904
	s_waitcnt vmcnt(3)
	v_lshlrev_b32_e32 v110, 16, v237
	v_and_b32_e32 v111, 0xffff0000, v237
	v_pk_mul_f32 v[112:113], v[100:101], v[16:17]
	v_pk_fma_f32 v[112:113], v[98:99], v[14:15], v[112:113]
	v_pk_fma_f32 v[112:113], v[102:103], v[108:109], v[112:113]
	v_pk_fma_f32 v[112:113], v[104:105], v[110:111], v[112:113]
	s_cmp_gt_u32 s58, 28
	s_cselect_b32 s60, -1, 0
	v_mul_f32_e32 v114, 0xbfb8aa3b, v112
	v_mul_f32_e32 v115, 0xbfb8aa3b, v113
	v_exp_f32_e32 v114, v114
	v_exp_f32_e32 v115, v115
	s_nop 0
	v_add_f32_e32 v114, 1.0, v114
	v_add_f32_e32 v115, 1.0, v115
	v_rcp_f32_e32 v114, v114
	v_rcp_f32_e32 v115, v115
	s_nop 0
	v_pk_mul_f32 v[114:115], v[112:113], v[114:115]
	v_and_b32_e32 v114, s60, v114
	v_and_b32_e32 v115, s60, v115
	ds_write_b64 v9, v[114:115] offset:43456
	s_waitcnt vmcnt(2)
	v_lshlrev_b32_e32 v14, 16, v238
	v_and_b32_e32 v15, 0xffff0000, v238
	v_pk_mul_f32 v[112:113], v[100:101], v[108:109]
	v_pk_fma_f32 v[112:113], v[98:99], v[16:17], v[112:113]
	v_pk_fma_f32 v[112:113], v[102:103], v[110:111], v[112:113]
	v_pk_fma_f32 v[112:113], v[104:105], v[14:15], v[112:113]
	s_cmp_gt_u32 s58, 29
	s_cselect_b32 s60, -1, 0
	v_mul_f32_e32 v114, 0xbfb8aa3b, v112
	v_mul_f32_e32 v115, 0xbfb8aa3b, v113
	v_exp_f32_e32 v114, v114
	v_exp_f32_e32 v115, v115
	s_nop 0
	v_add_f32_e32 v114, 1.0, v114
	v_add_f32_e32 v115, 1.0, v115
	v_rcp_f32_e32 v114, v114
	v_rcp_f32_e32 v115, v115
	s_nop 0
	v_pk_mul_f32 v[114:115], v[112:113], v[114:115]
	v_and_b32_e32 v114, s60, v114
	v_and_b32_e32 v115, s60, v115
	ds_write_b64 v9, v[114:115] offset:45008
	s_waitcnt vmcnt(1)
	v_lshlrev_b32_e32 v16, 16, v239
	v_and_b32_e32 v17, 0xffff0000, v239
	v_pk_mul_f32 v[112:113], v[100:101], v[110:111]
	v_pk_fma_f32 v[112:113], v[98:99], v[108:109], v[112:113]
	v_pk_fma_f32 v[112:113], v[102:103], v[14:15], v[112:113]
	v_pk_fma_f32 v[112:113], v[104:105], v[16:17], v[112:113]
	s_cmp_gt_u32 s58, 30
	s_cselect_b32 s60, -1, 0
	v_mul_f32_e32 v114, 0xbfb8aa3b, v112
	v_mul_f32_e32 v115, 0xbfb8aa3b, v113
	v_exp_f32_e32 v114, v114
	v_exp_f32_e32 v115, v115
	s_nop 0
	v_add_f32_e32 v114, 1.0, v114
	v_add_f32_e32 v115, 1.0, v115
	v_rcp_f32_e32 v114, v114
	v_rcp_f32_e32 v115, v115
	s_nop 0
	v_pk_mul_f32 v[114:115], v[112:113], v[114:115]
	v_and_b32_e32 v114, s60, v114
	v_and_b32_e32 v115, s60, v115
	ds_write_b64 v9, v[114:115] offset:46560
	s_waitcnt vmcnt(0)
	v_lshlrev_b32_e32 v108, 16, v240
	v_and_b32_e32 v109, 0xffff0000, v240
	v_pk_mul_f32 v[112:113], v[100:101], v[14:15]
	v_pk_fma_f32 v[112:113], v[98:99], v[110:111], v[112:113]
	v_pk_fma_f32 v[112:113], v[102:103], v[16:17], v[112:113]
	v_pk_fma_f32 v[112:113], v[104:105], v[108:109], v[112:113]
	s_cmp_gt_u32 s58, 31
	s_cselect_b32 s60, -1, 0
	v_mul_f32_e32 v114, 0xbfb8aa3b, v112
	v_mul_f32_e32 v115, 0xbfb8aa3b, v113
	v_exp_f32_e32 v114, v114
	v_exp_f32_e32 v115, v115
	s_nop 0
	v_add_f32_e32 v114, 1.0, v114
	v_add_f32_e32 v115, 1.0, v115
	v_rcp_f32_e32 v114, v114
	v_rcp_f32_e32 v115, v115
	s_nop 0
	v_pk_mul_f32 v[114:115], v[112:113], v[114:115]
	v_and_b32_e32 v114, s60, v114
	v_and_b32_e32 v115, s60, v115
	ds_write_b64 v9, v[114:115] offset:48112
	s_branch .LBB0_819

.LBB0_967:
	s_or_b64 exec, exec, s[2:3]
	s_waitcnt lgkmcnt(0)
	s_barrier
	s_and_saveexec_b64 s[2:3], s[16:17]
	s_cbranch_execz .LBB0_766
	v_mov_b32_e32 v5, 0x100
	v_cmp_gt_u32_e32 vcc, 0x80, v211
	s_nop 1
	v_cndmask_b32_e32 v5, 0, v5, vcc
	v_add_u32_e32 v0, v211, v5
	v_lshlrev_b32_e32 v0, 2, v0
	v_add_u32_e32 v2, 0xc200, v0
	v_mov_b32_e32 v3, 0x18400
	ds_read_b32 v6, v0 offset:0
	ds_read_b32 v7, v0 offset:1552
	ds_read_b32 v9, v0 offset:3104
	ds_read_b32 v59, v0 offset:4656
	ds_read_b32 v61, v0 offset:6208
	ds_read_b32 v63, v0 offset:7760
	ds_read_b32 v65, v0 offset:9312
	ds_read_b32 v67, v0 offset:10864
	ds_read_b128 v[194:197], v3 offset:0
	ds_read_b128 v[198:201], v3 offset:16
	ds_read_b128 v[202:205], v3 offset:272
	ds_read_b128 v[206:209], v3 offset:288
	ds_read_b128 v[220:223], v3 offset:544
	ds_read_b128 v[226:229], v3 offset:560
	ds_read_b128 v[230:233], v3 offset:832
	s_waitcnt lgkmcnt(5)
	v_fma_f32 v7, -v195, v6, v7
	v_fma_f32 v9, -v196, v6, v9
	v_fma_f32 v59, -v197, v6, v59
	v_fma_f32 v61, -v198, v6, v61
	v_fma_f32 v63, -v199, v6, v63
	v_fma_f32 v65, -v200, v6, v65
	v_fma_f32 v67, -v201, v6, v67
	ds_read_b128 v[234:237], v3 offset:1104
	s_waitcnt lgkmcnt(4)
	v_fma_f32 v9, -v204, v7, v9
	v_fma_f32 v59, -v205, v7, v59
	v_fma_f32 v61, -v206, v7, v61
	v_fma_f32 v63, -v207, v7, v63
	v_fma_f32 v65, -v208, v7, v65
	v_fma_f32 v67, -v209, v7, v67
	ds_read_b128 v[238:241], v3 offset:1376
	s_waitcnt lgkmcnt(3)
	v_fma_f32 v59, -v223, v9, v59
	v_fma_f32 v61, -v226, v9, v61
	v_fma_f32 v63, -v227, v9, v63
	v_fma_f32 v65, -v228, v9, v65
	v_fma_f32 v67, -v229, v9, v67
	ds_read_b128 v[242:245], v3 offset:1648
	s_waitcnt lgkmcnt(3)
	v_fma_f32 v61, -v230, v59, v61
	v_fma_f32 v63, -v231, v59, v63
	v_fma_f32 v65, -v232, v59, v65
	v_fma_f32 v67, -v233, v59, v67
	s_waitcnt lgkmcnt(2)
	v_fma_f32 v63, -v235, v61, v63
	v_fma_f32 v65, -v236, v61, v65
	v_fma_f32 v67, -v237, v61, v67
	s_waitcnt lgkmcnt(1)
	v_fma_f32 v65, -v240, v63, v65
	v_fma_f32 v67, -v241, v63, v67
	s_waitcnt lgkmcnt(0)
	v_fma_f32 v67, -v245, v65, v67
	s_nop 0
	ds_write_b32 v0, v6 offset:0
	ds_write_b32 v0, v7 offset:1552
	ds_write_b32 v0, v9 offset:3104
	ds_write_b32 v0, v59 offset:4656
	ds_write_b32 v0, v61 offset:6208
	ds_write_b32 v0, v63 offset:7760
	ds_write_b32 v0, v65 offset:9312
	ds_write_b32 v0, v67 offset:10864
	ds_read_b32 v6, v0 offset:12416
	ds_read_b32 v7, v0 offset:13968
	ds_read_b32 v9, v0 offset:15520
	ds_read_b32 v59, v0 offset:17072
	ds_read_b32 v61, v0 offset:18624
	ds_read_b32 v63, v0 offset:20176
	ds_read_b32 v65, v0 offset:21728
	ds_read_b32 v67, v0 offset:23280
	ds_read_b32 v69, v0 offset:0
	ds_read_b128 v[10:13], v3 offset:32
	ds_read_b128 v[14:17], v3 offset:48
	s_waitcnt lgkmcnt(0)
	v_fma_f32 v6, -v10, v69, v6
	v_fma_f32 v7, -v11, v69, v7
	v_fma_f32 v9, -v12, v69, v9
	v_fma_f32 v59, -v13, v69, v59
	v_fma_f32 v61, -v14, v69, v61
	v_fma_f32 v63, -v15, v69, v63
	v_fma_f32 v65, -v16, v69, v65
	v_fma_f32 v67, -v17, v69, v67
	ds_read_b32 v71, v0 offset:1552
	ds_read_b128 v[96:99], v3 offset:304
	ds_read_b128 v[100:103], v3 offset:320
	ds_read_b32 v73, v0 offset:3104
	ds_read_b128 v[104:107], v3 offset:576
	ds_read_b128 v[108:111], v3 offset:592
	ds_read_b32 v75, v0 offset:4656
	ds_read_b128 v[112:115], v3 offset:848
	ds_read_b128 v[188:191], v3 offset:864
	ds_read_b32 v69, v0 offset:6208
	ds_read_b128 v[10:13], v3 offset:1120
	ds_read_b128 v[14:17], v3 offset:1136
	s_waitcnt lgkmcnt(9)
	v_fma_f32 v6, -v96, v71, v6
	v_fma_f32 v7, -v97, v71, v7
	v_fma_f32 v9, -v98, v71, v9
	v_fma_f32 v59, -v99, v71, v59
	v_fma_f32 v61, -v100, v71, v61
	v_fma_f32 v63, -v101, v71, v63
	v_fma_f32 v65, -v102, v71, v65
	v_fma_f32 v67, -v103, v71, v67
	ds_read_b32 v71, v0 offset:7760
	ds_read_b128 v[96:99], v3 offset:1392
	ds_read_b128 v[100:103], v3 offset:1408
	s_waitcnt lgkmcnt(9)
	v_fma_f32 v6, -v104, v73, v6
	v_fma_f32 v7, -v105, v73, v7
	v_fma_f32 v9, -v106, v73, v9
	v_fma_f32 v59, -v107, v73, v59
	v_fma_f32 v61, -v108, v73, v61
	v_fma_f32 v63, -v109, v73, v63
	v_fma_f32 v65, -v110, v73, v65
	v_fma_f32 v67, -v111, v73, v67
	ds_read_b32 v73, v0 offset:9312
	ds_read_b128 v[104:107], v3 offset:1664
	ds_read_b128 v[108:111], v3 offset:1680
	s_waitcnt lgkmcnt(9)
	v_fma_f32 v6, -v112, v75, v6
	v_fma_f32 v7, -v113, v75, v7
	v_fma_f32 v9, -v114, v75, v9
	v_fma_f32 v59, -v115, v75, v59
	v_fma_f32 v61, -v188, v75, v61
	v_fma_f32 v63, -v189, v75, v63
	v_fma_f32 v65, -v190, v75, v65
	v_fma_f32 v67, -v191, v75, v67
	ds_read_b32 v75, v0 offset:10864
	ds_read_b128 v[112:115], v3 offset:1936
	ds_read_b128 v[188:191], v3 offset:1952
	s_waitcnt lgkmcnt(9)
	v_fma_f32 v6, -v10, v69, v6
	v_fma_f32 v7, -v11, v69, v7
	v_fma_f32 v9, -v12, v69, v9
	v_fma_f32 v59, -v13, v69, v59
	v_fma_f32 v61, -v14, v69, v61
	v_fma_f32 v63, -v15, v69, v63
	v_fma_f32 v65, -v16, v69, v65
	v_fma_f32 v67, -v17, v69, v67
	ds_read_b128 v[194:197], v3 offset:2208
	ds_read_b128 v[198:201], v3 offset:2224
	s_waitcnt lgkmcnt(8)
	v_fma_f32 v6, -v96, v71, v6
	v_fma_f32 v7, -v97, v71, v7
	v_fma_f32 v9, -v98, v71, v9
	v_fma_f32 v59, -v99, v71, v59
	v_fma_f32 v61, -v100, v71, v61
	v_fma_f32 v63, -v101, v71, v63
	v_fma_f32 v65, -v102, v71, v65
	v_fma_f32 v67, -v103, v71, v67
	ds_read_b128 v[202:205], v3 offset:2480
	ds_read_b128 v[206:209], v3 offset:2496
	s_waitcnt lgkmcnt(7)
	v_fma_f32 v6, -v104, v73, v6
	v_fma_f32 v7, -v105, v73, v7
	v_fma_f32 v9, -v106, v73, v9
	v_fma_f32 v59, -v107, v73, v59
	v_fma_f32 v61, -v108, v73, v61
	v_fma_f32 v63, -v109, v73, v63
	v_fma_f32 v65, -v110, v73, v65
	v_fma_f32 v67, -v111, v73, v67
	ds_read_b128 v[220:223], v3 offset:2752
	ds_read_b128 v[226:229], v3 offset:2768
	s_waitcnt lgkmcnt(6)
	v_fma_f32 v6, -v112, v75, v6
	v_fma_f32 v7, -v113, v75, v7
	v_fma_f32 v9, -v114, v75, v9
	v_fma_f32 v59, -v115, v75, v59
	v_fma_f32 v61, -v188, v75, v61
	v_fma_f32 v63, -v189, v75, v63
	v_fma_f32 v65, -v190, v75, v65
	v_fma_f32 v67, -v191, v75, v67
	ds_read_b128 v[230:233], v3 offset:3040
	s_waitcnt lgkmcnt(5)
	v_fma_f32 v7, -v195, v6, v7
	v_fma_f32 v9, -v196, v6, v9
	v_fma_f32 v59, -v197, v6, v59
	v_fma_f32 v61, -v198, v6, v61
	v_fma_f32 v63, -v199, v6, v63
	v_fma_f32 v65, -v200, v6, v65
	v_fma_f32 v67, -v201, v6, v67
	ds_read_b128 v[234:237], v3 offset:3312
	s_waitcnt lgkmcnt(4)
	v_fma_f32 v9, -v204, v7, v9
	v_fma_f32 v59, -v205, v7, v59
	v_fma_f32 v61, -v206, v7, v61
	v_fma_f32 v63, -v207, v7, v63
	v_fma_f32 v65, -v208, v7, v65
	v_fma_f32 v67, -v209, v7, v67
	ds_read_b128 v[238:241], v3 offset:3584
	s_waitcnt lgkmcnt(3)
	v_fma_f32 v59, -v223, v9, v59
	v_fma_f32 v61, -v226, v9, v61
	v_fma_f32 v63, -v227, v9, v63
	v_fma_f32 v65, -v228, v9, v65
	v_fma_f32 v67, -v229, v9, v67
	ds_read_b128 v[242:245], v3 offset:3856
	s_waitcnt lgkmcnt(3)
	v_fma_f32 v61, -v230, v59, v61
	v_fma_f32 v63, -v231, v59, v63
	v_fma_f32 v65, -v232, v59, v65
	v_fma_f32 v67, -v233, v59, v67
	s_waitcnt lgkmcnt(2)
	v_fma_f32 v63, -v235, v61, v63
	v_fma_f32 v65, -v236, v61, v65
	v_fma_f32 v67, -v237, v61, v67
	s_waitcnt lgkmcnt(1)
	v_fma_f32 v65, -v240, v63, v65
	v_fma_f32 v67, -v241, v63, v67
	s_waitcnt lgkmcnt(0)
	v_fma_f32 v67, -v245, v65, v67
	s_nop 0
	ds_write_b32 v0, v6 offset:12416
	ds_write_b32 v0, v7 offset:13968
	ds_write_b32 v0, v9 offset:15520
	ds_write_b32 v0, v59 offset:17072
	ds_write_b32 v0, v61 offset:18624
	ds_write_b32 v0, v63 offset:20176
	ds_write_b32 v0, v65 offset:21728
	ds_write_b32 v0, v67 offset:23280
	ds_read_b32 v6, v0 offset:24832
	ds_read_b32 v7, v0 offset:26384
	ds_read_b32 v9, v0 offset:27936
	ds_read_b32 v59, v0 offset:29488
	ds_read_b32 v61, v0 offset:31040
	ds_read_b32 v63, v0 offset:32592
	ds_read_b32 v65, v0 offset:34144
	ds_read_b32 v67, v0 offset:35696
	ds_read_b32 v69, v0 offset:0
	ds_read_b128 v[10:13], v3 offset:64
	ds_read_b128 v[14:17], v3 offset:80
	s_waitcnt lgkmcnt(0)
	v_fma_f32 v6, -v10, v69, v6
	v_fma_f32 v7, -v11, v69, v7
	v_fma_f32 v9, -v12, v69, v9
	v_fma_f32 v59, -v13, v69, v59
	v_fma_f32 v61, -v14, v69, v61
	v_fma_f32 v63, -v15, v69, v63
	v_fma_f32 v65, -v16, v69, v65
	v_fma_f32 v67, -v17, v69, v67
	ds_read_b32 v71, v0 offset:1552
	ds_read_b128 v[96:99], v3 offset:336
	ds_read_b128 v[100:103], v3 offset:352
	ds_read_b32 v73, v0 offset:3104
	ds_read_b128 v[104:107], v3 offset:608
	ds_read_b128 v[108:111], v3 offset:624
	ds_read_b32 v75, v0 offset:4656
	ds_read_b128 v[112:115], v3 offset:880
	ds_read_b128 v[188:191], v3 offset:896
	ds_read_b32 v69, v0 offset:6208
	ds_read_b128 v[10:13], v3 offset:1152
	ds_read_b128 v[14:17], v3 offset:1168
	s_waitcnt lgkmcnt(9)
	v_fma_f32 v6, -v96, v71, v6
	v_fma_f32 v7, -v97, v71, v7
	v_fma_f32 v9, -v98, v71, v9
	v_fma_f32 v59, -v99, v71, v59
	v_fma_f32 v61, -v100, v71, v61
	v_fma_f32 v63, -v101, v71, v63
	v_fma_f32 v65, -v102, v71, v65
	v_fma_f32 v67, -v103, v71, v67
	ds_read_b32 v71, v0 offset:7760
	ds_read_b128 v[96:99], v3 offset:1424
	ds_read_b128 v[100:103], v3 offset:1440
	s_waitcnt lgkmcnt(9)
	v_fma_f32 v6, -v104, v73, v6
	v_fma_f32 v7, -v105, v73, v7
	v_fma_f32 v9, -v106, v73, v9
	v_fma_f32 v59, -v107, v73, v59
	v_fma_f32 v61, -v108, v73, v61
	v_fma_f32 v63, -v109, v73, v63
	v_fma_f32 v65, -v110, v73, v65
	v_fma_f32 v67, -v111, v73, v67
	ds_read_b32 v73, v0 offset:9312
	ds_read_b128 v[104:107], v3 offset:1696
	ds_read_b128 v[108:111], v3 offset:1712
	s_waitcnt lgkmcnt(9)
	v_fma_f32 v6, -v112, v75, v6
	v_fma_f32 v7, -v113, v75, v7
	v_fma_f32 v9, -v114, v75, v9
	v_fma_f32 v59, -v115, v75, v59
	v_fma_f32 v61, -v188, v75, v61
	v_fma_f32 v63, -v189, v75, v63
	v_fma_f32 v65, -v190, v75, v65
	v_fma_f32 v67, -v191, v75, v67
	ds_read_b32 v75, v0 offset:10864
	ds_read_b128 v[112:115], v3 offset:1968
	ds_read_b128 v[188:191], v3 offset:1984
	s_waitcnt lgkmcnt(9)
	v_fma_f32 v6, -v10, v69, v6
	v_fma_f32 v7, -v11, v69, v7
	v_fma_f32 v9, -v12, v69, v9
	v_fma_f32 v59, -v13, v69, v59
	v_fma_f32 v61, -v14, v69, v61
	v_fma_f32 v63, -v15, v69, v63
	v_fma_f32 v65, -v16, v69, v65
	v_fma_f32 v67, -v17, v69, v67
	ds_read_b32 v69, v0 offset:12416
	ds_read_b128 v[10:13], v3 offset:2240
	ds_read_b128 v[14:17], v3 offset:2256
	s_waitcnt lgkmcnt(9)
	v_fma_f32 v6, -v96, v71, v6
	v_fma_f32 v7, -v97, v71, v7
	v_fma_f32 v9, -v98, v71, v9
	v_fma_f32 v59, -v99, v71, v59
	v_fma_f32 v61, -v100, v71, v61
	v_fma_f32 v63, -v101, v71, v63
	v_fma_f32 v65, -v102, v71, v65
	v_fma_f32 v67, -v103, v71, v67
	ds_read_b32 v71, v0 offset:13968
	ds_read_b128 v[96:99], v3 offset:2512
	ds_read_b128 v[100:103], v3 offset:2528
	s_waitcnt lgkmcnt(9)
	v_fma_f32 v6, -v104, v73, v6
	v_fma_f32 v7, -v105, v73, v7
	v_fma_f32 v9, -v106, v73, v9
	v_fma_f32 v59, -v107, v73, v59
	v_fma_f32 v61, -v108, v73, v61
	v_fma_f32 v63, -v109, v73, v63
	v_fma_f32 v65, -v110, v73, v65
	v_fma_f32 v67, -v111, v73, v67
	ds_read_b32 v73, v0 offset:15520
	ds_read_b128 v[104:107], v3 offset:2784
	ds_read_b128 v[108:111], v3 offset:2800
	s_waitcnt lgkmcnt(9)
	v_fma_f32 v6, -v112, v75, v6
	v_fma_f32 v7, -v113, v75, v7
	v_fma_f32 v9, -v114, v75, v9
	v_fma_f32 v59, -v115, v75, v59
	v_fma_f32 v61, -v188, v75, v61
	v_fma_f32 v63, -v189, v75, v63
	v_fma_f32 v65, -v190, v75, v65
	v_fma_f32 v67, -v191, v75, v67
	ds_read_b32 v75, v0 offset:17072
	ds_read_b128 v[112:115], v3 offset:3056
	ds_read_b128 v[188:191], v3 offset:3072
	s_waitcnt lgkmcnt(9)
	v_fma_f32 v6, -v10, v69, v6
	v_fma_f32 v7, -v11, v69, v7
	v_fma_f32 v9, -v12, v69, v9
	v_fma_f32 v59, -v13, v69, v59
	v_fma_f32 v61, -v14, v69, v61
	v_fma_f32 v63, -v15, v69, v63
	v_fma_f32 v65, -v16, v69, v65
	v_fma_f32 v67, -v17, v69, v67
	ds_read_b32 v69, v0 offset:18624
	ds_read_b128 v[10:13], v3 offset:3328
	ds_read_b128 v[14:17], v3 offset:3344
	s_waitcnt lgkmcnt(9)
	v_fma_f32 v6, -v96, v71, v6
	v_fma_f32 v7, -v97, v71, v7
	v_fma_f32 v9, -v98, v71, v9
	v_fma_f32 v59, -v99, v71, v59
	v_fma_f32 v61, -v100, v71, v61
	v_fma_f32 v63, -v101, v71, v63
	v_fma_f32 v65, -v102, v71, v65
	v_fma_f32 v67, -v103, v71, v67
	ds_read_b32 v71, v0 offset:20176
	ds_read_b128 v[96:99], v3 offset:3600
	ds_read_b128 v[100:103], v3 offset:3616
	s_waitcnt lgkmcnt(9)
	v_fma_f32 v6, -v104, v73, v6
	v_fma_f32 v7, -v105, v73, v7
	v_fma_f32 v9, -v106, v73, v9
	v_fma_f32 v59, -v107, v73, v59
	v_fma_f32 v61, -v108, v73, v61
	v_fma_f32 v63, -v109, v73, v63
	v_fma_f32 v65, -v110, v73, v65
	v_fma_f32 v67, -v111, v73, v67
	ds_read_b32 v73, v0 offset:21728
	ds_read_b128 v[104:107], v3 offset:3872
	ds_read_b128 v[108:111], v3 offset:3888
	s_waitcnt lgkmcnt(9)
	v_fma_f32 v6, -v112, v75, v6
	v_fma_f32 v7, -v113, v75, v7
	v_fma_f32 v9, -v114, v75, v9
	v_fma_f32 v59, -v115, v75, v59
	v_fma_f32 v61, -v188, v75, v61
	v_fma_f32 v63, -v189, v75, v63
	v_fma_f32 v65, -v190, v75, v65
	v_fma_f32 v67, -v191, v75, v67
	ds_read_b32 v75, v0 offset:23280
	ds_read_b128 v[112:115], v3 offset:4144
	ds_read_b128 v[188:191], v3 offset:4160
	s_waitcnt lgkmcnt(9)
	v_fma_f32 v6, -v10, v69, v6
	v_fma_f32 v7, -v11, v69, v7
	v_fma_f32 v9, -v12, v69, v9
	v_fma_f32 v59, -v13, v69, v59
	v_fma_f32 v61, -v14, v69, v61
	v_fma_f32 v63, -v15, v69, v63
	v_fma_f32 v65, -v16, v69, v65
	v_fma_f32 v67, -v17, v69, v67
	ds_read_b128 v[194:197], v3 offset:4416
	ds_read_b128 v[198:201], v3 offset:4432
	s_waitcnt lgkmcnt(8)
	v_fma_f32 v6, -v96, v71, v6
	v_fma_f32 v7, -v97, v71, v7
	v_fma_f32 v9, -v98, v71, v9
	v_fma_f32 v59, -v99, v71, v59
	v_fma_f32 v61, -v100, v71, v61
	v_fma_f32 v63, -v101, v71, v63
	v_fma_f32 v65, -v102, v71, v65
	v_fma_f32 v67, -v103, v71, v67
	ds_read_b128 v[202:205], v3 offset:4688
	ds_read_b128 v[206:209], v3 offset:4704
	s_waitcnt lgkmcnt(7)
	v_fma_f32 v6, -v104, v73, v6
	v_fma_f32 v7, -v105, v73, v7
	v_fma_f32 v9, -v106, v73, v9
	v_fma_f32 v59, -v107, v73, v59
	v_fma_f32 v61, -v108, v73, v61
	v_fma_f32 v63, -v109, v73, v63
	v_fma_f32 v65, -v110, v73, v65
	v_fma_f32 v67, -v111, v73, v67
	ds_read_b128 v[220:223], v3 offset:4960
	ds_read_b128 v[226:229], v3 offset:4976
	s_waitcnt lgkmcnt(6)
	v_fma_f32 v6, -v112, v75, v6
	v_fma_f32 v7, -v113, v75, v7
	v_fma_f32 v9, -v114, v75, v9
	v_fma_f32 v59, -v115, v75, v59
	v_fma_f32 v61, -v188, v75, v61
	v_fma_f32 v63, -v189, v75, v63
	v_fma_f32 v65, -v190, v75, v65
	v_fma_f32 v67, -v191, v75, v67
	ds_read_b128 v[230:233], v3 offset:5248
	s_waitcnt lgkmcnt(5)
	v_fma_f32 v7, -v195, v6, v7
	v_fma_f32 v9, -v196, v6, v9
	v_fma_f32 v59, -v197, v6, v59
	v_fma_f32 v61, -v198, v6, v61
	v_fma_f32 v63, -v199, v6, v63
	v_fma_f32 v65, -v200, v6, v65
	v_fma_f32 v67, -v201, v6, v67
	ds_read_b128 v[234:237], v3 offset:5520
	s_waitcnt lgkmcnt(4)
	v_fma_f32 v9, -v204, v7, v9
	v_fma_f32 v59, -v205, v7, v59
	v_fma_f32 v61, -v206, v7, v61
	v_fma_f32 v63, -v207, v7, v63
	v_fma_f32 v65, -v208, v7, v65
	v_fma_f32 v67, -v209, v7, v67
	ds_read_b128 v[238:241], v3 offset:5792
	s_waitcnt lgkmcnt(3)
	v_fma_f32 v59, -v223, v9, v59
	v_fma_f32 v61, -v226, v9, v61
	v_fma_f32 v63, -v227, v9, v63
	v_fma_f32 v65, -v228, v9, v65
	v_fma_f32 v67, -v229, v9, v67
	ds_read_b128 v[242:245], v3 offset:6064
	s_waitcnt lgkmcnt(3)
	v_fma_f32 v61, -v230, v59, v61
	v_fma_f32 v63, -v231, v59, v63
	v_fma_f32 v65, -v232, v59, v65
	v_fma_f32 v67, -v233, v59, v67
	s_waitcnt lgkmcnt(2)
	v_fma_f32 v63, -v235, v61, v63
	v_fma_f32 v65, -v236, v61, v65
	v_fma_f32 v67, -v237, v61, v67
	s_waitcnt lgkmcnt(1)
	v_fma_f32 v65, -v240, v63, v65
	v_fma_f32 v67, -v241, v63, v67
	s_waitcnt lgkmcnt(0)
	v_fma_f32 v67, -v245, v65, v67
	s_nop 0
	ds_write_b32 v0, v6 offset:24832
	ds_write_b32 v0, v7 offset:26384
	ds_write_b32 v0, v9 offset:27936
	ds_write_b32 v0, v59 offset:29488
	ds_write_b32 v0, v61 offset:31040
	ds_write_b32 v0, v63 offset:32592
	ds_write_b32 v0, v65 offset:34144
	ds_write_b32 v0, v67 offset:35696
	ds_read_b32 v6, v0 offset:37248
	ds_read_b32 v7, v0 offset:38800
	ds_read_b32 v9, v0 offset:40352
	ds_read_b32 v59, v0 offset:41904
	ds_read_b32 v61, v0 offset:43456
	ds_read_b32 v63, v0 offset:45008
	ds_read_b32 v65, v0 offset:46560
	ds_read_b32 v67, v0 offset:48112
	ds_read_b32 v69, v0 offset:0
	ds_read_b128 v[10:13], v3 offset:96
	ds_read_b128 v[14:17], v3 offset:112
	s_waitcnt lgkmcnt(0)
	v_fma_f32 v6, -v10, v69, v6
	v_fma_f32 v7, -v11, v69, v7
	v_fma_f32 v9, -v12, v69, v9
	v_fma_f32 v59, -v13, v69, v59
	v_fma_f32 v61, -v14, v69, v61
	v_fma_f32 v63, -v15, v69, v63
	v_fma_f32 v65, -v16, v69, v65
	v_fma_f32 v67, -v17, v69, v67
	ds_read_b32 v71, v0 offset:1552
	ds_read_b128 v[96:99], v3 offset:368
	ds_read_b128 v[100:103], v3 offset:384
	ds_read_b32 v73, v0 offset:3104
	ds_read_b128 v[104:107], v3 offset:640
	ds_read_b128 v[108:111], v3 offset:656
	ds_read_b32 v75, v0 offset:4656
	ds_read_b128 v[112:115], v3 offset:912
	ds_read_b128 v[188:191], v3 offset:928
	ds_read_b32 v69, v0 offset:6208
	ds_read_b128 v[10:13], v3 offset:1184
	ds_read_b128 v[14:17], v3 offset:1200
	s_waitcnt lgkmcnt(9)
	v_fma_f32 v6, -v96, v71, v6
	v_fma_f32 v7, -v97, v71, v7
	v_fma_f32 v9, -v98, v71, v9
	v_fma_f32 v59, -v99, v71, v59
	v_fma_f32 v61, -v100, v71, v61
	v_fma_f32 v63, -v101, v71, v63
	v_fma_f32 v65, -v102, v71, v65
	v_fma_f32 v67, -v103, v71, v67
	ds_read_b32 v71, v0 offset:7760
	ds_read_b128 v[96:99], v3 offset:1456
	ds_read_b128 v[100:103], v3 offset:1472
	s_waitcnt lgkmcnt(9)
	v_fma_f32 v6, -v104, v73, v6
	v_fma_f32 v7, -v105, v73, v7
	v_fma_f32 v9, -v106, v73, v9
	v_fma_f32 v59, -v107, v73, v59
	v_fma_f32 v61, -v108, v73, v61
	v_fma_f32 v63, -v109, v73, v63
	v_fma_f32 v65, -v110, v73, v65
	v_fma_f32 v67, -v111, v73, v67
	ds_read_b32 v73, v0 offset:9312
	ds_read_b128 v[104:107], v3 offset:1728
	ds_read_b128 v[108:111], v3 offset:1744
	s_waitcnt lgkmcnt(9)
	v_fma_f32 v6, -v112, v75, v6
	v_fma_f32 v7, -v113, v75, v7
	v_fma_f32 v9, -v114, v75, v9
	v_fma_f32 v59, -v115, v75, v59
	v_fma_f32 v61, -v188, v75, v61
	v_fma_f32 v63, -v189, v75, v63
	v_fma_f32 v65, -v190, v75, v65
	v_fma_f32 v67, -v191, v75, v67
	ds_read_b32 v75, v0 offset:10864
	ds_read_b128 v[112:115], v3 offset:2000
	ds_read_b128 v[188:191], v3 offset:2016
	s_waitcnt lgkmcnt(9)
	v_fma_f32 v6, -v10, v69, v6
	v_fma_f32 v7, -v11, v69, v7
	v_fma_f32 v9, -v12, v69, v9
	v_fma_f32 v59, -v13, v69, v59
	v_fma_f32 v61, -v14, v69, v61
	v_fma_f32 v63, -v15, v69, v63
	v_fma_f32 v65, -v16, v69, v65
	v_fma_f32 v67, -v17, v69, v67
	ds_read_b32 v69, v0 offset:12416
	ds_read_b128 v[10:13], v3 offset:2272
	ds_read_b128 v[14:17], v3 offset:2288
	s_waitcnt lgkmcnt(9)
	v_fma_f32 v6, -v96, v71, v6
	v_fma_f32 v7, -v97, v71, v7
	v_fma_f32 v9, -v98, v71, v9
	v_fma_f32 v59, -v99, v71, v59
	v_fma_f32 v61, -v100, v71, v61
	v_fma_f32 v63, -v101, v71, v63
	v_fma_f32 v65, -v102, v71, v65
	v_fma_f32 v67, -v103, v71, v67
	ds_read_b32 v71, v0 offset:13968
	ds_read_b128 v[96:99], v3 offset:2544
	ds_read_b128 v[100:103], v3 offset:2560
	s_waitcnt lgkmcnt(9)
	v_fma_f32 v6, -v104, v73, v6
	v_fma_f32 v7, -v105, v73, v7
	v_fma_f32 v9, -v106, v73, v9
	v_fma_f32 v59, -v107, v73, v59
	v_fma_f32 v61, -v108, v73, v61
	v_fma_f32 v63, -v109, v73, v63
	v_fma_f32 v65, -v110, v73, v65
	v_fma_f32 v67, -v111, v73, v67
	ds_read_b32 v73, v0 offset:15520
	ds_read_b128 v[104:107], v3 offset:2816
	ds_read_b128 v[108:111], v3 offset:2832
	s_waitcnt lgkmcnt(9)
	v_fma_f32 v6, -v112, v75, v6
	v_fma_f32 v7, -v113, v75, v7
	v_fma_f32 v9, -v114, v75, v9
	v_fma_f32 v59, -v115, v75, v59
	v_fma_f32 v61, -v188, v75, v61
	v_fma_f32 v63, -v189, v75, v63
	v_fma_f32 v65, -v190, v75, v65
	v_fma_f32 v67, -v191, v75, v67
	ds_read_b32 v75, v0 offset:17072
	ds_read_b128 v[112:115], v3 offset:3088
	ds_read_b128 v[188:191], v3 offset:3104
	s_waitcnt lgkmcnt(9)
	v_fma_f32 v6, -v10, v69, v6
	v_fma_f32 v7, -v11, v69, v7
	v_fma_f32 v9, -v12, v69, v9
	v_fma_f32 v59, -v13, v69, v59
	v_fma_f32 v61, -v14, v69, v61
	v_fma_f32 v63, -v15, v69, v63
	v_fma_f32 v65, -v16, v69, v65
	v_fma_f32 v67, -v17, v69, v67
	ds_read_b32 v69, v0 offset:18624
	ds_read_b128 v[10:13], v3 offset:3360
	ds_read_b128 v[14:17], v3 offset:3376
	s_waitcnt lgkmcnt(9)
	v_fma_f32 v6, -v96, v71, v6
	v_fma_f32 v7, -v97, v71, v7
	v_fma_f32 v9, -v98, v71, v9
	v_fma_f32 v59, -v99, v71, v59
	v_fma_f32 v61, -v100, v71, v61
	v_fma_f32 v63, -v101, v71, v63
	v_fma_f32 v65, -v102, v71, v65
	v_fma_f32 v67, -v103, v71, v67
	ds_read_b32 v71, v0 offset:20176
	ds_read_b128 v[96:99], v3 offset:3632
	ds_read_b128 v[100:103], v3 offset:3648
	s_waitcnt lgkmcnt(9)
	v_fma_f32 v6, -v104, v73, v6
	v_fma_f32 v7, -v105, v73, v7
	v_fma_f32 v9, -v106, v73, v9
	v_fma_f32 v59, -v107, v73, v59
	v_fma_f32 v61, -v108, v73, v61
	v_fma_f32 v63, -v109, v73, v63
	v_fma_f32 v65, -v110, v73, v65
	v_fma_f32 v67, -v111, v73, v67
	ds_read_b32 v73, v0 offset:21728
	ds_read_b128 v[104:107], v3 offset:3904
	ds_read_b128 v[108:111], v3 offset:3920
	s_waitcnt lgkmcnt(9)
	v_fma_f32 v6, -v112, v75, v6
	v_fma_f32 v7, -v113, v75, v7
	v_fma_f32 v9, -v114, v75, v9
	v_fma_f32 v59, -v115, v75, v59
	v_fma_f32 v61, -v188, v75, v61
	v_fma_f32 v63, -v189, v75, v63
	v_fma_f32 v65, -v190, v75, v65
	v_fma_f32 v67, -v191, v75, v67
	ds_read_b32 v75, v0 offset:23280
	ds_read_b128 v[112:115], v3 offset:4176
	ds_read_b128 v[188:191], v3 offset:4192
	s_waitcnt lgkmcnt(9)
	v_fma_f32 v6, -v10, v69, v6
	v_fma_f32 v7, -v11, v69, v7
	v_fma_f32 v9, -v12, v69, v9
	v_fma_f32 v59, -v13, v69, v59
	v_fma_f32 v61, -v14, v69, v61
	v_fma_f32 v63, -v15, v69, v63
	v_fma_f32 v65, -v16, v69, v65
	v_fma_f32 v67, -v17, v69, v67
	ds_read_b32 v69, v0 offset:24832
	ds_read_b128 v[10:13], v3 offset:4448
	ds_read_b128 v[14:17], v3 offset:4464
	s_waitcnt lgkmcnt(9)
	v_fma_f32 v6, -v96, v71, v6
	v_fma_f32 v7, -v97, v71, v7
	v_fma_f32 v9, -v98, v71, v9
	v_fma_f32 v59, -v99, v71, v59
	v_fma_f32 v61, -v100, v71, v61
	v_fma_f32 v63, -v101, v71, v63
	v_fma_f32 v65, -v102, v71, v65
	v_fma_f32 v67, -v103, v71, v67
	ds_read_b32 v71, v0 offset:26384
	ds_read_b128 v[96:99], v3 offset:4720
	ds_read_b128 v[100:103], v3 offset:4736
	s_waitcnt lgkmcnt(9)
	v_fma_f32 v6, -v104, v73, v6
	v_fma_f32 v7, -v105, v73, v7
	v_fma_f32 v9, -v106, v73, v9
	v_fma_f32 v59, -v107, v73, v59
	v_fma_f32 v61, -v108, v73, v61
	v_fma_f32 v63, -v109, v73, v63
	v_fma_f32 v65, -v110, v73, v65
	v_fma_f32 v67, -v111, v73, v67
	ds_read_b32 v73, v0 offset:27936
	ds_read_b128 v[104:107], v3 offset:4992
	ds_read_b128 v[108:111], v3 offset:5008
	s_waitcnt lgkmcnt(9)
	v_fma_f32 v6, -v112, v75, v6
	v_fma_f32 v7, -v113, v75, v7
	v_fma_f32 v9, -v114, v75, v9
	v_fma_f32 v59, -v115, v75, v59
	v_fma_f32 v61, -v188, v75, v61
	v_fma_f32 v63, -v189, v75, v63
	v_fma_f32 v65, -v190, v75, v65
	v_fma_f32 v67, -v191, v75, v67
	ds_read_b32 v75, v0 offset:29488
	ds_read_b128 v[112:115], v3 offset:5264
	ds_read_b128 v[188:191], v3 offset:5280
	s_waitcnt lgkmcnt(9)
	v_fma_f32 v6, -v10, v69, v6
	v_fma_f32 v7, -v11, v69, v7
	v_fma_f32 v9, -v12, v69, v9
	v_fma_f32 v59, -v13, v69, v59
	v_fma_f32 v61, -v14, v69, v61
	v_fma_f32 v63, -v15, v69, v63
	v_fma_f32 v65, -v16, v69, v65
	v_fma_f32 v67, -v17, v69, v67
	ds_read_b32 v69, v0 offset:31040
	ds_read_b128 v[10:13], v3 offset:5536
	ds_read_b128 v[14:17], v3 offset:5552
	s_waitcnt lgkmcnt(9)
	v_fma_f32 v6, -v96, v71, v6
	v_fma_f32 v7, -v97, v71, v7
	v_fma_f32 v9, -v98, v71, v9
	v_fma_f32 v59, -v99, v71, v59
	v_fma_f32 v61, -v100, v71, v61
	v_fma_f32 v63, -v101, v71, v63
	v_fma_f32 v65, -v102, v71, v65
	v_fma_f32 v67, -v103, v71, v67
	ds_read_b32 v71, v0 offset:32592
	ds_read_b128 v[96:99], v3 offset:5808
	ds_read_b128 v[100:103], v3 offset:5824
	s_waitcnt lgkmcnt(9)
	v_fma_f32 v6, -v104, v73, v6
	v_fma_f32 v7, -v105, v73, v7
	v_fma_f32 v9, -v106, v73, v9
	v_fma_f32 v59, -v107, v73, v59
	v_fma_f32 v61, -v108, v73, v61
	v_fma_f32 v63, -v109, v73, v63
	v_fma_f32 v65, -v110, v73, v65
	v_fma_f32 v67, -v111, v73, v67
	ds_read_b32 v73, v0 offset:34144
	ds_read_b128 v[104:107], v3 offset:6080
	ds_read_b128 v[108:111], v3 offset:6096
	s_waitcnt lgkmcnt(9)
	v_fma_f32 v6, -v112, v75, v6
	v_fma_f32 v7, -v113, v75, v7
	v_fma_f32 v9, -v114, v75, v9
	v_fma_f32 v59, -v115, v75, v59
	v_fma_f32 v61, -v188, v75, v61
	v_fma_f32 v63, -v189, v75, v63
	v_fma_f32 v65, -v190, v75, v65
	v_fma_f32 v67, -v191, v75, v67
	ds_read_b32 v75, v0 offset:35696
	ds_read_b128 v[112:115], v3 offset:6352
	ds_read_b128 v[188:191], v3 offset:6368
	s_waitcnt lgkmcnt(9)
	v_fma_f32 v6, -v10, v69, v6
	v_fma_f32 v7, -v11, v69, v7
	v_fma_f32 v9, -v12, v69, v9
	v_fma_f32 v59, -v13, v69, v59
	v_fma_f32 v61, -v14, v69, v61
	v_fma_f32 v63, -v15, v69, v63
	v_fma_f32 v65, -v16, v69, v65
	v_fma_f32 v67, -v17, v69, v67
	ds_read_b128 v[194:197], v3 offset:6624
	ds_read_b128 v[198:201], v3 offset:6640
	s_waitcnt lgkmcnt(8)
	v_fma_f32 v6, -v96, v71, v6
	v_fma_f32 v7, -v97, v71, v7
	v_fma_f32 v9, -v98, v71, v9
	v_fma_f32 v59, -v99, v71, v59
	v_fma_f32 v61, -v100, v71, v61
	v_fma_f32 v63, -v101, v71, v63
	v_fma_f32 v65, -v102, v71, v65
	v_fma_f32 v67, -v103, v71, v67
	ds_read_b128 v[202:205], v3 offset:6896
	ds_read_b128 v[206:209], v3 offset:6912
	s_waitcnt lgkmcnt(7)
	v_fma_f32 v6, -v104, v73, v6
	v_fma_f32 v7, -v105, v73, v7
	v_fma_f32 v9, -v106, v73, v9
	v_fma_f32 v59, -v107, v73, v59
	v_fma_f32 v61, -v108, v73, v61
	v_fma_f32 v63, -v109, v73, v63
	v_fma_f32 v65, -v110, v73, v65
	v_fma_f32 v67, -v111, v73, v67
	ds_read_b128 v[220:223], v3 offset:7168
	ds_read_b128 v[226:229], v3 offset:7184
	s_waitcnt lgkmcnt(6)
	v_fma_f32 v6, -v112, v75, v6
	v_fma_f32 v7, -v113, v75, v7
	v_fma_f32 v9, -v114, v75, v9
	v_fma_f32 v59, -v115, v75, v59
	v_fma_f32 v61, -v188, v75, v61
	v_fma_f32 v63, -v189, v75, v63
	v_fma_f32 v65, -v190, v75, v65
	v_fma_f32 v67, -v191, v75, v67
	ds_read_b128 v[230:233], v3 offset:7456
	s_waitcnt lgkmcnt(5)
	v_fma_f32 v7, -v195, v6, v7
	v_fma_f32 v9, -v196, v6, v9
	v_fma_f32 v59, -v197, v6, v59
	v_fma_f32 v61, -v198, v6, v61
	v_fma_f32 v63, -v199, v6, v63
	v_fma_f32 v65, -v200, v6, v65
	v_fma_f32 v67, -v201, v6, v67
	ds_read_b128 v[234:237], v3 offset:7728
	s_waitcnt lgkmcnt(4)
	v_fma_f32 v9, -v204, v7, v9
	v_fma_f32 v59, -v205, v7, v59
	v_fma_f32 v61, -v206, v7, v61
	v_fma_f32 v63, -v207, v7, v63
	v_fma_f32 v65, -v208, v7, v65
	v_fma_f32 v67, -v209, v7, v67
	ds_read_b128 v[238:241], v3 offset:8000
	s_waitcnt lgkmcnt(3)
	v_fma_f32 v59, -v223, v9, v59
	v_fma_f32 v61, -v226, v9, v61
	v_fma_f32 v63, -v227, v9, v63
	v_fma_f32 v65, -v228, v9, v65
	v_fma_f32 v67, -v229, v9, v67
	ds_read_b128 v[242:245], v3 offset:8272
	s_waitcnt lgkmcnt(3)
	v_fma_f32 v61, -v230, v59, v61
	v_fma_f32 v63, -v231, v59, v63
	v_fma_f32 v65, -v232, v59, v65
	v_fma_f32 v67, -v233, v59, v67
	s_waitcnt lgkmcnt(2)
	v_fma_f32 v63, -v235, v61, v63
	v_fma_f32 v65, -v236, v61, v65
	v_fma_f32 v67, -v237, v61, v67
	s_waitcnt lgkmcnt(1)
	v_fma_f32 v65, -v240, v63, v65
	v_fma_f32 v67, -v241, v63, v67
	s_waitcnt lgkmcnt(0)
	v_fma_f32 v67, -v245, v65, v67
	s_nop 0
	ds_write_b32 v0, v6 offset:37248
	ds_write_b32 v0, v7 offset:38800
	ds_write_b32 v0, v9 offset:40352
	ds_write_b32 v0, v59 offset:41904
	ds_write_b32 v0, v61 offset:43456
	ds_write_b32 v0, v63 offset:45008
	ds_write_b32 v0, v65 offset:46560
	ds_write_b32 v0, v67 offset:48112
	ds_read_b32 v6, v2 offset:0
	ds_read_b32 v7, v2 offset:1552
	ds_read_b32 v9, v2 offset:3104
	ds_read_b32 v59, v2 offset:4656
	ds_read_b32 v61, v2 offset:6208
	ds_read_b32 v63, v2 offset:7760
	ds_read_b32 v65, v2 offset:9312
	ds_read_b32 v67, v2 offset:10864
	ds_read_b32 v69, v0 offset:0
	ds_read_b128 v[10:13], v3 offset:128
	ds_read_b128 v[14:17], v3 offset:144
	s_waitcnt lgkmcnt(0)
	v_fma_f32 v6, -v10, v69, v6
	v_fma_f32 v7, -v11, v69, v7
	v_fma_f32 v9, -v12, v69, v9
	v_fma_f32 v59, -v13, v69, v59
	v_fma_f32 v61, -v14, v69, v61
	v_fma_f32 v63, -v15, v69, v63
	v_fma_f32 v65, -v16, v69, v65
	v_fma_f32 v67, -v17, v69, v67
	ds_read_b32 v71, v0 offset:1552
	ds_read_b128 v[96:99], v3 offset:400
	ds_read_b128 v[100:103], v3 offset:416
	ds_read_b32 v73, v0 offset:3104
	ds_read_b128 v[104:107], v3 offset:672
	ds_read_b128 v[108:111], v3 offset:688
	ds_read_b32 v75, v0 offset:4656
	ds_read_b128 v[112:115], v3 offset:944
	ds_read_b128 v[188:191], v3 offset:960
	ds_read_b32 v69, v0 offset:6208
	ds_read_b128 v[10:13], v3 offset:1216
	ds_read_b128 v[14:17], v3 offset:1232
	s_waitcnt lgkmcnt(9)
	v_fma_f32 v6, -v96, v71, v6
	v_fma_f32 v7, -v97, v71, v7
	v_fma_f32 v9, -v98, v71, v9
	v_fma_f32 v59, -v99, v71, v59
	v_fma_f32 v61, -v100, v71, v61
	v_fma_f32 v63, -v101, v71, v63
	v_fma_f32 v65, -v102, v71, v65
	v_fma_f32 v67, -v103, v71, v67
	ds_read_b32 v71, v0 offset:7760
	ds_read_b128 v[96:99], v3 offset:1488
	ds_read_b128 v[100:103], v3 offset:1504
	s_waitcnt lgkmcnt(9)
	v_fma_f32 v6, -v104, v73, v6
	v_fma_f32 v7, -v105, v73, v7
	v_fma_f32 v9, -v106, v73, v9
	v_fma_f32 v59, -v107, v73, v59
	v_fma_f32 v61, -v108, v73, v61
	v_fma_f32 v63, -v109, v73, v63
	v_fma_f32 v65, -v110, v73, v65
	v_fma_f32 v67, -v111, v73, v67
	ds_read_b32 v73, v0 offset:9312
	ds_read_b128 v[104:107], v3 offset:1760
	ds_read_b128 v[108:111], v3 offset:1776
	s_waitcnt lgkmcnt(9)
	v_fma_f32 v6, -v112, v75, v6
	v_fma_f32 v7, -v113, v75, v7
	v_fma_f32 v9, -v114, v75, v9
	v_fma_f32 v59, -v115, v75, v59
	v_fma_f32 v61, -v188, v75, v61
	v_fma_f32 v63, -v189, v75, v63
	v_fma_f32 v65, -v190, v75, v65
	v_fma_f32 v67, -v191, v75, v67
	ds_read_b32 v75, v0 offset:10864
	ds_read_b128 v[112:115], v3 offset:2032
	ds_read_b128 v[188:191], v3 offset:2048
	s_waitcnt lgkmcnt(9)
	v_fma_f32 v6, -v10, v69, v6
	v_fma_f32 v7, -v11, v69, v7
	v_fma_f32 v9, -v12, v69, v9
	v_fma_f32 v59, -v13, v69, v59
	v_fma_f32 v61, -v14, v69, v61
	v_fma_f32 v63, -v15, v69, v63
	v_fma_f32 v65, -v16, v69, v65
	v_fma_f32 v67, -v17, v69, v67
	ds_read_b32 v69, v0 offset:12416
	ds_read_b128 v[10:13], v3 offset:2304
	ds_read_b128 v[14:17], v3 offset:2320
	s_waitcnt lgkmcnt(9)
	v_fma_f32 v6, -v96, v71, v6
	v_fma_f32 v7, -v97, v71, v7
	v_fma_f32 v9, -v98, v71, v9
	v_fma_f32 v59, -v99, v71, v59
	v_fma_f32 v61, -v100, v71, v61
	v_fma_f32 v63, -v101, v71, v63
	v_fma_f32 v65, -v102, v71, v65
	v_fma_f32 v67, -v103, v71, v67
	ds_read_b32 v71, v0 offset:13968
	ds_read_b128 v[96:99], v3 offset:2576
	ds_read_b128 v[100:103], v3 offset:2592
	s_waitcnt lgkmcnt(9)
	v_fma_f32 v6, -v104, v73, v6
	v_fma_f32 v7, -v105, v73, v7
	v_fma_f32 v9, -v106, v73, v9
	v_fma_f32 v59, -v107, v73, v59
	v_fma_f32 v61, -v108, v73, v61
	v_fma_f32 v63, -v109, v73, v63
	v_fma_f32 v65, -v110, v73, v65
	v_fma_f32 v67, -v111, v73, v67
	ds_read_b32 v73, v0 offset:15520
	ds_read_b128 v[104:107], v3 offset:2848
	ds_read_b128 v[108:111], v3 offset:2864
	s_waitcnt lgkmcnt(9)
	v_fma_f32 v6, -v112, v75, v6
	v_fma_f32 v7, -v113, v75, v7
	v_fma_f32 v9, -v114, v75, v9
	v_fma_f32 v59, -v115, v75, v59
	v_fma_f32 v61, -v188, v75, v61
	v_fma_f32 v63, -v189, v75, v63
	v_fma_f32 v65, -v190, v75, v65
	v_fma_f32 v67, -v191, v75, v67
	ds_read_b32 v75, v0 offset:17072
	ds_read_b128 v[112:115], v3 offset:3120
	ds_read_b128 v[188:191], v3 offset:3136
	s_waitcnt lgkmcnt(9)
	v_fma_f32 v6, -v10, v69, v6
	v_fma_f32 v7, -v11, v69, v7
	v_fma_f32 v9, -v12, v69, v9
	v_fma_f32 v59, -v13, v69, v59
	v_fma_f32 v61, -v14, v69, v61
	v_fma_f32 v63, -v15, v69, v63
	v_fma_f32 v65, -v16, v69, v65
	v_fma_f32 v67, -v17, v69, v67
	ds_read_b32 v69, v0 offset:18624
	ds_read_b128 v[10:13], v3 offset:3392
	ds_read_b128 v[14:17], v3 offset:3408
	s_waitcnt lgkmcnt(9)
	v_fma_f32 v6, -v96, v71, v6
	v_fma_f32 v7, -v97, v71, v7
	v_fma_f32 v9, -v98, v71, v9
	v_fma_f32 v59, -v99, v71, v59
	v_fma_f32 v61, -v100, v71, v61
	v_fma_f32 v63, -v101, v71, v63
	v_fma_f32 v65, -v102, v71, v65
	v_fma_f32 v67, -v103, v71, v67
	ds_read_b32 v71, v0 offset:20176
	ds_read_b128 v[96:99], v3 offset:3664
	ds_read_b128 v[100:103], v3 offset:3680
	s_waitcnt lgkmcnt(9)
	v_fma_f32 v6, -v104, v73, v6
	v_fma_f32 v7, -v105, v73, v7
	v_fma_f32 v9, -v106, v73, v9
	v_fma_f32 v59, -v107, v73, v59
	v_fma_f32 v61, -v108, v73, v61
	v_fma_f32 v63, -v109, v73, v63
	v_fma_f32 v65, -v110, v73, v65
	v_fma_f32 v67, -v111, v73, v67
	ds_read_b32 v73, v0 offset:21728
	ds_read_b128 v[104:107], v3 offset:3936
	ds_read_b128 v[108:111], v3 offset:3952
	s_waitcnt lgkmcnt(9)
	v_fma_f32 v6, -v112, v75, v6
	v_fma_f32 v7, -v113, v75, v7
	v_fma_f32 v9, -v114, v75, v9
	v_fma_f32 v59, -v115, v75, v59
	v_fma_f32 v61, -v188, v75, v61
	v_fma_f32 v63, -v189, v75, v63
	v_fma_f32 v65, -v190, v75, v65
	v_fma_f32 v67, -v191, v75, v67
	ds_read_b32 v75, v0 offset:23280
	ds_read_b128 v[112:115], v3 offset:4208
	ds_read_b128 v[188:191], v3 offset:4224
	s_waitcnt lgkmcnt(9)
	v_fma_f32 v6, -v10, v69, v6
	v_fma_f32 v7, -v11, v69, v7
	v_fma_f32 v9, -v12, v69, v9
	v_fma_f32 v59, -v13, v69, v59
	v_fma_f32 v61, -v14, v69, v61
	v_fma_f32 v63, -v15, v69, v63
	v_fma_f32 v65, -v16, v69, v65
	v_fma_f32 v67, -v17, v69, v67
	ds_read_b32 v69, v0 offset:24832
	ds_read_b128 v[10:13], v3 offset:4480
	ds_read_b128 v[14:17], v3 offset:4496
	s_waitcnt lgkmcnt(9)
	v_fma_f32 v6, -v96, v71, v6
	v_fma_f32 v7, -v97, v71, v7
	v_fma_f32 v9, -v98, v71, v9
	v_fma_f32 v59, -v99, v71, v59
	v_fma_f32 v61, -v100, v71, v61
	v_fma_f32 v63, -v101, v71, v63
	v_fma_f32 v65, -v102, v71, v65
	v_fma_f32 v67, -v103, v71, v67
	ds_read_b32 v71, v0 offset:26384
	ds_read_b128 v[96:99], v3 offset:4752
	ds_read_b128 v[100:103], v3 offset:4768
	s_waitcnt lgkmcnt(9)
	v_fma_f32 v6, -v104, v73, v6
	v_fma_f32 v7, -v105, v73, v7
	v_fma_f32 v9, -v106, v73, v9
	v_fma_f32 v59, -v107, v73, v59
	v_fma_f32 v61, -v108, v73, v61
	v_fma_f32 v63, -v109, v73, v63
	v_fma_f32 v65, -v110, v73, v65
	v_fma_f32 v67, -v111, v73, v67
	ds_read_b32 v73, v0 offset:27936
	ds_read_b128 v[104:107], v3 offset:5024
	ds_read_b128 v[108:111], v3 offset:5040
	s_waitcnt lgkmcnt(9)
	v_fma_f32 v6, -v112, v75, v6
	v_fma_f32 v7, -v113, v75, v7
	v_fma_f32 v9, -v114, v75, v9
	v_fma_f32 v59, -v115, v75, v59
	v_fma_f32 v61, -v188, v75, v61
	v_fma_f32 v63, -v189, v75, v63
	v_fma_f32 v65, -v190, v75, v65
	v_fma_f32 v67, -v191, v75, v67
	ds_read_b32 v75, v0 offset:29488
	ds_read_b128 v[112:115], v3 offset:5296
	ds_read_b128 v[188:191], v3 offset:5312
	s_waitcnt lgkmcnt(9)
	v_fma_f32 v6, -v10, v69, v6
	v_fma_f32 v7, -v11, v69, v7
	v_fma_f32 v9, -v12, v69, v9
	v_fma_f32 v59, -v13, v69, v59
	v_fma_f32 v61, -v14, v69, v61
	v_fma_f32 v63, -v15, v69, v63
	v_fma_f32 v65, -v16, v69, v65
	v_fma_f32 v67, -v17, v69, v67
	ds_read_b32 v69, v0 offset:31040
	ds_read_b128 v[10:13], v3 offset:5568
	ds_read_b128 v[14:17], v3 offset:5584
	s_waitcnt lgkmcnt(9)
	v_fma_f32 v6, -v96, v71, v6
	v_fma_f32 v7, -v97, v71, v7
	v_fma_f32 v9, -v98, v71, v9
	v_fma_f32 v59, -v99, v71, v59
	v_fma_f32 v61, -v100, v71, v61
	v_fma_f32 v63, -v101, v71, v63
	v_fma_f32 v65, -v102, v71, v65
	v_fma_f32 v67, -v103, v71, v67
	ds_read_b32 v71, v0 offset:32592
	ds_read_b128 v[96:99], v3 offset:5840
	ds_read_b128 v[100:103], v3 offset:5856
	s_waitcnt lgkmcnt(9)
	v_fma_f32 v6, -v104, v73, v6
	v_fma_f32 v7, -v105, v73, v7
	v_fma_f32 v9, -v106, v73, v9
	v_fma_f32 v59, -v107, v73, v59
	v_fma_f32 v61, -v108, v73, v61
	v_fma_f32 v63, -v109, v73, v63
	v_fma_f32 v65, -v110, v73, v65
	v_fma_f32 v67, -v111, v73, v67
	ds_read_b32 v73, v0 offset:34144
	ds_read_b128 v[104:107], v3 offset:6112
	ds_read_b128 v[108:111], v3 offset:6128
	s_waitcnt lgkmcnt(9)
	v_fma_f32 v6, -v112, v75, v6
	v_fma_f32 v7, -v113, v75, v7
	v_fma_f32 v9, -v114, v75, v9
	v_fma_f32 v59, -v115, v75, v59
	v_fma_f32 v61, -v188, v75, v61
	v_fma_f32 v63, -v189, v75, v63
	v_fma_f32 v65, -v190, v75, v65
	v_fma_f32 v67, -v191, v75, v67
	ds_read_b32 v75, v0 offset:35696
	ds_read_b128 v[112:115], v3 offset:6384
	ds_read_b128 v[188:191], v3 offset:6400
	s_waitcnt lgkmcnt(9)
	v_fma_f32 v6, -v10, v69, v6
	v_fma_f32 v7, -v11, v69, v7
	v_fma_f32 v9, -v12, v69, v9
	v_fma_f32 v59, -v13, v69, v59
	v_fma_f32 v61, -v14, v69, v61
	v_fma_f32 v63, -v15, v69, v63
	v_fma_f32 v65, -v16, v69, v65
	v_fma_f32 v67, -v17, v69, v67
	ds_read_b32 v69, v0 offset:37248
	ds_read_b128 v[10:13], v3 offset:6656
	ds_read_b128 v[14:17], v3 offset:6672
	s_waitcnt lgkmcnt(9)
	v_fma_f32 v6, -v96, v71, v6
	v_fma_f32 v7, -v97, v71, v7
	v_fma_f32 v9, -v98, v71, v9
	v_fma_f32 v59, -v99, v71, v59
	v_fma_f32 v61, -v100, v71, v61
	v_fma_f32 v63, -v101, v71, v63
	v_fma_f32 v65, -v102, v71, v65
	v_fma_f32 v67, -v103, v71, v67
	ds_read_b32 v71, v0 offset:38800
	ds_read_b128 v[96:99], v3 offset:6928
	ds_read_b128 v[100:103], v3 offset:6944
	s_waitcnt lgkmcnt(9)
	v_fma_f32 v6, -v104, v73, v6
	v_fma_f32 v7, -v105, v73, v7
	v_fma_f32 v9, -v106, v73, v9
	v_fma_f32 v59, -v107, v73, v59
	v_fma_f32 v61, -v108, v73, v61
	v_fma_f32 v63, -v109, v73, v63
	v_fma_f32 v65, -v110, v73, v65
	v_fma_f32 v67, -v111, v73, v67
	ds_read_b32 v73, v0 offset:40352
	ds_read_b128 v[104:107], v3 offset:7200
	ds_read_b128 v[108:111], v3 offset:7216
	s_waitcnt lgkmcnt(9)
	v_fma_f32 v6, -v112, v75, v6
	v_fma_f32 v7, -v113, v75, v7
	v_fma_f32 v9, -v114, v75, v9
	v_fma_f32 v59, -v115, v75, v59
	v_fma_f32 v61, -v188, v75, v61
	v_fma_f32 v63, -v189, v75, v63
	v_fma_f32 v65, -v190, v75, v65
	v_fma_f32 v67, -v191, v75, v67
	ds_read_b32 v75, v0 offset:41904
	ds_read_b128 v[112:115], v3 offset:7472
	ds_read_b128 v[188:191], v3 offset:7488
	s_waitcnt lgkmcnt(9)
	v_fma_f32 v6, -v10, v69, v6
	v_fma_f32 v7, -v11, v69, v7
	v_fma_f32 v9, -v12, v69, v9
	v_fma_f32 v59, -v13, v69, v59
	v_fma_f32 v61, -v14, v69, v61
	v_fma_f32 v63, -v15, v69, v63
	v_fma_f32 v65, -v16, v69, v65
	v_fma_f32 v67, -v17, v69, v67
	ds_read_b32 v69, v0 offset:43456
	ds_read_b128 v[10:13], v3 offset:7744
	ds_read_b128 v[14:17], v3 offset:7760
	s_waitcnt lgkmcnt(9)
	v_fma_f32 v6, -v96, v71, v6
	v_fma_f32 v7, -v97, v71, v7
	v_fma_f32 v9, -v98, v71, v9
	v_fma_f32 v59, -v99, v71, v59
	v_fma_f32 v61, -v100, v71, v61
	v_fma_f32 v63, -v101, v71, v63
	v_fma_f32 v65, -v102, v71, v65
	v_fma_f32 v67, -v103, v71, v67
	ds_read_b32 v71, v0 offset:45008
	ds_read_b128 v[96:99], v3 offset:8016
	ds_read_b128 v[100:103], v3 offset:8032
	s_waitcnt lgkmcnt(9)
	v_fma_f32 v6, -v104, v73, v6
	v_fma_f32 v7, -v105, v73, v7
	v_fma_f32 v9, -v106, v73, v9
	v_fma_f32 v59, -v107, v73, v59
	v_fma_f32 v61, -v108, v73, v61
	v_fma_f32 v63, -v109, v73, v63
	v_fma_f32 v65, -v110, v73, v65
	v_fma_f32 v67, -v111, v73, v67
	ds_read_b32 v73, v0 offset:46560
	ds_read_b128 v[104:107], v3 offset:8288
	ds_read_b128 v[108:111], v3 offset:8304
	s_waitcnt lgkmcnt(9)
	v_fma_f32 v6, -v112, v75, v6
	v_fma_f32 v7, -v113, v75, v7
	v_fma_f32 v9, -v114, v75, v9
	v_fma_f32 v59, -v115, v75, v59
	v_fma_f32 v61, -v188, v75, v61
	v_fma_f32 v63, -v189, v75, v63
	v_fma_f32 v65, -v190, v75, v65
	v_fma_f32 v67, -v191, v75, v67
	ds_read_b32 v75, v0 offset:48112
	ds_read_b128 v[112:115], v3 offset:8560
	ds_read_b128 v[188:191], v3 offset:8576
	s_waitcnt lgkmcnt(9)
	v_fma_f32 v6, -v10, v69, v6
	v_fma_f32 v7, -v11, v69, v7
	v_fma_f32 v9, -v12, v69, v9
	v_fma_f32 v59, -v13, v69, v59
	v_fma_f32 v61, -v14, v69, v61
	v_fma_f32 v63, -v15, v69, v63
	v_fma_f32 v65, -v16, v69, v65
	v_fma_f32 v67, -v17, v69, v67
	ds_read_b128 v[194:197], v3 offset:8832
	ds_read_b128 v[198:201], v3 offset:8848
	s_waitcnt lgkmcnt(8)
	v_fma_f32 v6, -v96, v71, v6
	v_fma_f32 v7, -v97, v71, v7
	v_fma_f32 v9, -v98, v71, v9
	v_fma_f32 v59, -v99, v71, v59
	v_fma_f32 v61, -v100, v71, v61
	v_fma_f32 v63, -v101, v71, v63
	v_fma_f32 v65, -v102, v71, v65
	v_fma_f32 v67, -v103, v71, v67
	ds_read_b128 v[202:205], v3 offset:9104
	ds_read_b128 v[206:209], v3 offset:9120
	s_waitcnt lgkmcnt(7)
	v_fma_f32 v6, -v104, v73, v6
	v_fma_f32 v7, -v105, v73, v7
	v_fma_f32 v9, -v106, v73, v9
	v_fma_f32 v59, -v107, v73, v59
	v_fma_f32 v61, -v108, v73, v61
	v_fma_f32 v63, -v109, v73, v63
	v_fma_f32 v65, -v110, v73, v65
	v_fma_f32 v67, -v111, v73, v67
	ds_read_b128 v[220:223], v3 offset:9376
	ds_read_b128 v[226:229], v3 offset:9392
	s_waitcnt lgkmcnt(6)
	v_fma_f32 v6, -v112, v75, v6
	v_fma_f32 v7, -v113, v75, v7
	v_fma_f32 v9, -v114, v75, v9
	v_fma_f32 v59, -v115, v75, v59
	v_fma_f32 v61, -v188, v75, v61
	v_fma_f32 v63, -v189, v75, v63
	v_fma_f32 v65, -v190, v75, v65
	v_fma_f32 v67, -v191, v75, v67
	ds_read_b128 v[230:233], v3 offset:9664
	s_waitcnt lgkmcnt(5)
	v_fma_f32 v7, -v195, v6, v7
	v_fma_f32 v9, -v196, v6, v9
	v_fma_f32 v59, -v197, v6, v59
	v_fma_f32 v61, -v198, v6, v61
	v_fma_f32 v63, -v199, v6, v63
	v_fma_f32 v65, -v200, v6, v65
	v_fma_f32 v67, -v201, v6, v67
	ds_read_b128 v[234:237], v3 offset:9936
	s_waitcnt lgkmcnt(4)
	v_fma_f32 v9, -v204, v7, v9
	v_fma_f32 v59, -v205, v7, v59
	v_fma_f32 v61, -v206, v7, v61
	v_fma_f32 v63, -v207, v7, v63
	v_fma_f32 v65, -v208, v7, v65
	v_fma_f32 v67, -v209, v7, v67
	ds_read_b128 v[238:241], v3 offset:10208
	s_waitcnt lgkmcnt(3)
	v_fma_f32 v59, -v223, v9, v59
	v_fma_f32 v61, -v226, v9, v61
	v_fma_f32 v63, -v227, v9, v63
	v_fma_f32 v65, -v228, v9, v65
	v_fma_f32 v67, -v229, v9, v67
	ds_read_b128 v[242:245], v3 offset:10480
	s_waitcnt lgkmcnt(3)
	v_fma_f32 v61, -v230, v59, v61
	v_fma_f32 v63, -v231, v59, v63
	v_fma_f32 v65, -v232, v59, v65
	v_fma_f32 v67, -v233, v59, v67
	s_waitcnt lgkmcnt(2)
	v_fma_f32 v63, -v235, v61, v63
	v_fma_f32 v65, -v236, v61, v65
	v_fma_f32 v67, -v237, v61, v67
	s_waitcnt lgkmcnt(1)
	v_fma_f32 v65, -v240, v63, v65
	v_fma_f32 v67, -v241, v63, v67
	s_waitcnt lgkmcnt(0)
	v_fma_f32 v67, -v245, v65, v67
	s_nop 0
	ds_write_b32 v2, v6 offset:0
	ds_write_b32 v2, v7 offset:1552
	ds_write_b32 v2, v9 offset:3104
	ds_write_b32 v2, v59 offset:4656
	ds_write_b32 v2, v61 offset:6208
	ds_write_b32 v2, v63 offset:7760
	ds_write_b32 v2, v65 offset:9312
	ds_write_b32 v2, v67 offset:10864
	ds_read_b32 v6, v2 offset:12416
	ds_read_b32 v7, v2 offset:13968
	ds_read_b32 v9, v2 offset:15520
	ds_read_b32 v59, v2 offset:17072
	ds_read_b32 v61, v2 offset:18624
	ds_read_b32 v63, v2 offset:20176
	ds_read_b32 v65, v2 offset:21728
	ds_read_b32 v67, v2 offset:23280
	ds_read_b32 v69, v0 offset:0
	ds_read_b128 v[10:13], v3 offset:160
	ds_read_b128 v[14:17], v3 offset:176
	s_waitcnt lgkmcnt(0)
	v_fma_f32 v6, -v10, v69, v6
	v_fma_f32 v7, -v11, v69, v7
	v_fma_f32 v9, -v12, v69, v9
	v_fma_f32 v59, -v13, v69, v59
	v_fma_f32 v61, -v14, v69, v61
	v_fma_f32 v63, -v15, v69, v63
	v_fma_f32 v65, -v16, v69, v65
	v_fma_f32 v67, -v17, v69, v67
	ds_read_b32 v71, v0 offset:1552
	ds_read_b128 v[96:99], v3 offset:432
	ds_read_b128 v[100:103], v3 offset:448
	ds_read_b32 v73, v0 offset:3104
	ds_read_b128 v[104:107], v3 offset:704
	ds_read_b128 v[108:111], v3 offset:720
	ds_read_b32 v75, v0 offset:4656
	ds_read_b128 v[112:115], v3 offset:976
	ds_read_b128 v[188:191], v3 offset:992
	ds_read_b32 v69, v0 offset:6208
	ds_read_b128 v[10:13], v3 offset:1248
	ds_read_b128 v[14:17], v3 offset:1264
	s_waitcnt lgkmcnt(9)
	v_fma_f32 v6, -v96, v71, v6
	v_fma_f32 v7, -v97, v71, v7
	v_fma_f32 v9, -v98, v71, v9
	v_fma_f32 v59, -v99, v71, v59
	v_fma_f32 v61, -v100, v71, v61
	v_fma_f32 v63, -v101, v71, v63
	v_fma_f32 v65, -v102, v71, v65
	v_fma_f32 v67, -v103, v71, v67
	ds_read_b32 v71, v0 offset:7760
	ds_read_b128 v[96:99], v3 offset:1520
	ds_read_b128 v[100:103], v3 offset:1536
	s_waitcnt lgkmcnt(9)
	v_fma_f32 v6, -v104, v73, v6
	v_fma_f32 v7, -v105, v73, v7
	v_fma_f32 v9, -v106, v73, v9
	v_fma_f32 v59, -v107, v73, v59
	v_fma_f32 v61, -v108, v73, v61
	v_fma_f32 v63, -v109, v73, v63
	v_fma_f32 v65, -v110, v73, v65
	v_fma_f32 v67, -v111, v73, v67
	ds_read_b32 v73, v0 offset:9312
	ds_read_b128 v[104:107], v3 offset:1792
	ds_read_b128 v[108:111], v3 offset:1808
	s_waitcnt lgkmcnt(9)
	v_fma_f32 v6, -v112, v75, v6
	v_fma_f32 v7, -v113, v75, v7
	v_fma_f32 v9, -v114, v75, v9
	v_fma_f32 v59, -v115, v75, v59
	v_fma_f32 v61, -v188, v75, v61
	v_fma_f32 v63, -v189, v75, v63
	v_fma_f32 v65, -v190, v75, v65
	v_fma_f32 v67, -v191, v75, v67
	ds_read_b32 v75, v0 offset:10864
	ds_read_b128 v[112:115], v3 offset:2064
	ds_read_b128 v[188:191], v3 offset:2080
	s_waitcnt lgkmcnt(9)
	v_fma_f32 v6, -v10, v69, v6
	v_fma_f32 v7, -v11, v69, v7
	v_fma_f32 v9, -v12, v69, v9
	v_fma_f32 v59, -v13, v69, v59
	v_fma_f32 v61, -v14, v69, v61
	v_fma_f32 v63, -v15, v69, v63
	v_fma_f32 v65, -v16, v69, v65
	v_fma_f32 v67, -v17, v69, v67
	ds_read_b32 v69, v0 offset:12416
	ds_read_b128 v[10:13], v3 offset:2336
	ds_read_b128 v[14:17], v3 offset:2352
	s_waitcnt lgkmcnt(9)
	v_fma_f32 v6, -v96, v71, v6
	v_fma_f32 v7, -v97, v71, v7
	v_fma_f32 v9, -v98, v71, v9
	v_fma_f32 v59, -v99, v71, v59
	v_fma_f32 v61, -v100, v71, v61
	v_fma_f32 v63, -v101, v71, v63
	v_fma_f32 v65, -v102, v71, v65
	v_fma_f32 v67, -v103, v71, v67
	ds_read_b32 v71, v0 offset:13968
	ds_read_b128 v[96:99], v3 offset:2608
	ds_read_b128 v[100:103], v3 offset:2624
	s_waitcnt lgkmcnt(9)
	v_fma_f32 v6, -v104, v73, v6
	v_fma_f32 v7, -v105, v73, v7
	v_fma_f32 v9, -v106, v73, v9
	v_fma_f32 v59, -v107, v73, v59
	v_fma_f32 v61, -v108, v73, v61
	v_fma_f32 v63, -v109, v73, v63
	v_fma_f32 v65, -v110, v73, v65
	v_fma_f32 v67, -v111, v73, v67
	ds_read_b32 v73, v0 offset:15520
	ds_read_b128 v[104:107], v3 offset:2880
	ds_read_b128 v[108:111], v3 offset:2896
	s_waitcnt lgkmcnt(9)
	v_fma_f32 v6, -v112, v75, v6
	v_fma_f32 v7, -v113, v75, v7
	v_fma_f32 v9, -v114, v75, v9
	v_fma_f32 v59, -v115, v75, v59
	v_fma_f32 v61, -v188, v75, v61
	v_fma_f32 v63, -v189, v75, v63
	v_fma_f32 v65, -v190, v75, v65
	v_fma_f32 v67, -v191, v75, v67
	ds_read_b32 v75, v0 offset:17072
	ds_read_b128 v[112:115], v3 offset:3152
	ds_read_b128 v[188:191], v3 offset:3168
	s_waitcnt lgkmcnt(9)
	v_fma_f32 v6, -v10, v69, v6
	v_fma_f32 v7, -v11, v69, v7
	v_fma_f32 v9, -v12, v69, v9
	v_fma_f32 v59, -v13, v69, v59
	v_fma_f32 v61, -v14, v69, v61
	v_fma_f32 v63, -v15, v69, v63
	v_fma_f32 v65, -v16, v69, v65
	v_fma_f32 v67, -v17, v69, v67
	ds_read_b32 v69, v0 offset:18624
	ds_read_b128 v[10:13], v3 offset:3424
	ds_read_b128 v[14:17], v3 offset:3440
	s_waitcnt lgkmcnt(9)
	v_fma_f32 v6, -v96, v71, v6
	v_fma_f32 v7, -v97, v71, v7
	v_fma_f32 v9, -v98, v71, v9
	v_fma_f32 v59, -v99, v71, v59
	v_fma_f32 v61, -v100, v71, v61
	v_fma_f32 v63, -v101, v71, v63
	v_fma_f32 v65, -v102, v71, v65
	v_fma_f32 v67, -v103, v71, v67
	ds_read_b32 v71, v0 offset:20176
	ds_read_b128 v[96:99], v3 offset:3696
	ds_read_b128 v[100:103], v3 offset:3712
	s_waitcnt lgkmcnt(9)
	v_fma_f32 v6, -v104, v73, v6
	v_fma_f32 v7, -v105, v73, v7
	v_fma_f32 v9, -v106, v73, v9
	v_fma_f32 v59, -v107, v73, v59
	v_fma_f32 v61, -v108, v73, v61
	v_fma_f32 v63, -v109, v73, v63
	v_fma_f32 v65, -v110, v73, v65
	v_fma_f32 v67, -v111, v73, v67
	ds_read_b32 v73, v0 offset:21728
	ds_read_b128 v[104:107], v3 offset:3968
	ds_read_b128 v[108:111], v3 offset:3984
	s_waitcnt lgkmcnt(9)
	v_fma_f32 v6, -v112, v75, v6
	v_fma_f32 v7, -v113, v75, v7
	v_fma_f32 v9, -v114, v75, v9
	v_fma_f32 v59, -v115, v75, v59
	v_fma_f32 v61, -v188, v75, v61
	v_fma_f32 v63, -v189, v75, v63
	v_fma_f32 v65, -v190, v75, v65
	v_fma_f32 v67, -v191, v75, v67
	ds_read_b32 v75, v0 offset:23280
	ds_read_b128 v[112:115], v3 offset:4240
	ds_read_b128 v[188:191], v3 offset:4256
	s_waitcnt lgkmcnt(9)
	v_fma_f32 v6, -v10, v69, v6
	v_fma_f32 v7, -v11, v69, v7
	v_fma_f32 v9, -v12, v69, v9
	v_fma_f32 v59, -v13, v69, v59
	v_fma_f32 v61, -v14, v69, v61
	v_fma_f32 v63, -v15, v69, v63
	v_fma_f32 v65, -v16, v69, v65
	v_fma_f32 v67, -v17, v69, v67
	ds_read_b32 v69, v0 offset:24832
	ds_read_b128 v[10:13], v3 offset:4512
	ds_read_b128 v[14:17], v3 offset:4528
	s_waitcnt lgkmcnt(9)
	v_fma_f32 v6, -v96, v71, v6
	v_fma_f32 v7, -v97, v71, v7
	v_fma_f32 v9, -v98, v71, v9
	v_fma_f32 v59, -v99, v71, v59
	v_fma_f32 v61, -v100, v71, v61
	v_fma_f32 v63, -v101, v71, v63
	v_fma_f32 v65, -v102, v71, v65
	v_fma_f32 v67, -v103, v71, v67
	ds_read_b32 v71, v0 offset:26384
	ds_read_b128 v[96:99], v3 offset:4784
	ds_read_b128 v[100:103], v3 offset:4800
	s_waitcnt lgkmcnt(9)
	v_fma_f32 v6, -v104, v73, v6
	v_fma_f32 v7, -v105, v73, v7
	v_fma_f32 v9, -v106, v73, v9
	v_fma_f32 v59, -v107, v73, v59
	v_fma_f32 v61, -v108, v73, v61
	v_fma_f32 v63, -v109, v73, v63
	v_fma_f32 v65, -v110, v73, v65
	v_fma_f32 v67, -v111, v73, v67
	ds_read_b32 v73, v0 offset:27936
	ds_read_b128 v[104:107], v3 offset:5056
	ds_read_b128 v[108:111], v3 offset:5072
	s_waitcnt lgkmcnt(9)
	v_fma_f32 v6, -v112, v75, v6
	v_fma_f32 v7, -v113, v75, v7
	v_fma_f32 v9, -v114, v75, v9
	v_fma_f32 v59, -v115, v75, v59
	v_fma_f32 v61, -v188, v75, v61
	v_fma_f32 v63, -v189, v75, v63
	v_fma_f32 v65, -v190, v75, v65
	v_fma_f32 v67, -v191, v75, v67
	ds_read_b32 v75, v0 offset:29488
	ds_read_b128 v[112:115], v3 offset:5328
	ds_read_b128 v[188:191], v3 offset:5344
	s_waitcnt lgkmcnt(9)
	v_fma_f32 v6, -v10, v69, v6
	v_fma_f32 v7, -v11, v69, v7
	v_fma_f32 v9, -v12, v69, v9
	v_fma_f32 v59, -v13, v69, v59
	v_fma_f32 v61, -v14, v69, v61
	v_fma_f32 v63, -v15, v69, v63
	v_fma_f32 v65, -v16, v69, v65
	v_fma_f32 v67, -v17, v69, v67
	ds_read_b32 v69, v0 offset:31040
	ds_read_b128 v[10:13], v3 offset:5600
	ds_read_b128 v[14:17], v3 offset:5616
	s_waitcnt lgkmcnt(9)
	v_fma_f32 v6, -v96, v71, v6
	v_fma_f32 v7, -v97, v71, v7
	v_fma_f32 v9, -v98, v71, v9
	v_fma_f32 v59, -v99, v71, v59
	v_fma_f32 v61, -v100, v71, v61
	v_fma_f32 v63, -v101, v71, v63
	v_fma_f32 v65, -v102, v71, v65
	v_fma_f32 v67, -v103, v71, v67
	ds_read_b32 v71, v0 offset:32592
	ds_read_b128 v[96:99], v3 offset:5872
	ds_read_b128 v[100:103], v3 offset:5888
	s_waitcnt lgkmcnt(9)
	v_fma_f32 v6, -v104, v73, v6
	v_fma_f32 v7, -v105, v73, v7
	v_fma_f32 v9, -v106, v73, v9
	v_fma_f32 v59, -v107, v73, v59
	v_fma_f32 v61, -v108, v73, v61
	v_fma_f32 v63, -v109, v73, v63
	v_fma_f32 v65, -v110, v73, v65
	v_fma_f32 v67, -v111, v73, v67
	ds_read_b32 v73, v0 offset:34144
	ds_read_b128 v[104:107], v3 offset:6144
	ds_read_b128 v[108:111], v3 offset:6160
	s_waitcnt lgkmcnt(9)
	v_fma_f32 v6, -v112, v75, v6
	v_fma_f32 v7, -v113, v75, v7
	v_fma_f32 v9, -v114, v75, v9
	v_fma_f32 v59, -v115, v75, v59
	v_fma_f32 v61, -v188, v75, v61
	v_fma_f32 v63, -v189, v75, v63
	v_fma_f32 v65, -v190, v75, v65
	v_fma_f32 v67, -v191, v75, v67
	ds_read_b32 v75, v0 offset:35696
	ds_read_b128 v[112:115], v3 offset:6416
	ds_read_b128 v[188:191], v3 offset:6432
	s_waitcnt lgkmcnt(9)
	v_fma_f32 v6, -v10, v69, v6
	v_fma_f32 v7, -v11, v69, v7
	v_fma_f32 v9, -v12, v69, v9
	v_fma_f32 v59, -v13, v69, v59
	v_fma_f32 v61, -v14, v69, v61
	v_fma_f32 v63, -v15, v69, v63
	v_fma_f32 v65, -v16, v69, v65
	v_fma_f32 v67, -v17, v69, v67
	ds_read_b32 v69, v0 offset:37248
	ds_read_b128 v[10:13], v3 offset:6688
	ds_read_b128 v[14:17], v3 offset:6704
	s_waitcnt lgkmcnt(9)
	v_fma_f32 v6, -v96, v71, v6
	v_fma_f32 v7, -v97, v71, v7
	v_fma_f32 v9, -v98, v71, v9
	v_fma_f32 v59, -v99, v71, v59
	v_fma_f32 v61, -v100, v71, v61
	v_fma_f32 v63, -v101, v71, v63
	v_fma_f32 v65, -v102, v71, v65
	v_fma_f32 v67, -v103, v71, v67
	ds_read_b32 v71, v0 offset:38800
	ds_read_b128 v[96:99], v3 offset:6960
	ds_read_b128 v[100:103], v3 offset:6976
	s_waitcnt lgkmcnt(9)
	v_fma_f32 v6, -v104, v73, v6
	v_fma_f32 v7, -v105, v73, v7
	v_fma_f32 v9, -v106, v73, v9
	v_fma_f32 v59, -v107, v73, v59
	v_fma_f32 v61, -v108, v73, v61
	v_fma_f32 v63, -v109, v73, v63
	v_fma_f32 v65, -v110, v73, v65
	v_fma_f32 v67, -v111, v73, v67
	ds_read_b32 v73, v0 offset:40352
	ds_read_b128 v[104:107], v3 offset:7232
	ds_read_b128 v[108:111], v3 offset:7248
	s_waitcnt lgkmcnt(9)
	v_fma_f32 v6, -v112, v75, v6
	v_fma_f32 v7, -v113, v75, v7
	v_fma_f32 v9, -v114, v75, v9
	v_fma_f32 v59, -v115, v75, v59
	v_fma_f32 v61, -v188, v75, v61
	v_fma_f32 v63, -v189, v75, v63
	v_fma_f32 v65, -v190, v75, v65
	v_fma_f32 v67, -v191, v75, v67
	ds_read_b32 v75, v0 offset:41904
	ds_read_b128 v[112:115], v3 offset:7504
	ds_read_b128 v[188:191], v3 offset:7520
	s_waitcnt lgkmcnt(9)
	v_fma_f32 v6, -v10, v69, v6
	v_fma_f32 v7, -v11, v69, v7
	v_fma_f32 v9, -v12, v69, v9
	v_fma_f32 v59, -v13, v69, v59
	v_fma_f32 v61, -v14, v69, v61
	v_fma_f32 v63, -v15, v69, v63
	v_fma_f32 v65, -v16, v69, v65
	v_fma_f32 v67, -v17, v69, v67
	ds_read_b32 v69, v0 offset:43456
	ds_read_b128 v[10:13], v3 offset:7776
	ds_read_b128 v[14:17], v3 offset:7792
	s_waitcnt lgkmcnt(9)
	v_fma_f32 v6, -v96, v71, v6
	v_fma_f32 v7, -v97, v71, v7
	v_fma_f32 v9, -v98, v71, v9
	v_fma_f32 v59, -v99, v71, v59
	v_fma_f32 v61, -v100, v71, v61
	v_fma_f32 v63, -v101, v71, v63
	v_fma_f32 v65, -v102, v71, v65
	v_fma_f32 v67, -v103, v71, v67
	ds_read_b32 v71, v0 offset:45008
	ds_read_b128 v[96:99], v3 offset:8048
	ds_read_b128 v[100:103], v3 offset:8064
	s_waitcnt lgkmcnt(9)
	v_fma_f32 v6, -v104, v73, v6
	v_fma_f32 v7, -v105, v73, v7
	v_fma_f32 v9, -v106, v73, v9
	v_fma_f32 v59, -v107, v73, v59
	v_fma_f32 v61, -v108, v73, v61
	v_fma_f32 v63, -v109, v73, v63
	v_fma_f32 v65, -v110, v73, v65
	v_fma_f32 v67, -v111, v73, v67
	ds_read_b32 v73, v0 offset:46560
	ds_read_b128 v[104:107], v3 offset:8320
	ds_read_b128 v[108:111], v3 offset:8336
	s_waitcnt lgkmcnt(9)
	v_fma_f32 v6, -v112, v75, v6
	v_fma_f32 v7, -v113, v75, v7
	v_fma_f32 v9, -v114, v75, v9
	v_fma_f32 v59, -v115, v75, v59
	v_fma_f32 v61, -v188, v75, v61
	v_fma_f32 v63, -v189, v75, v63
	v_fma_f32 v65, -v190, v75, v65
	v_fma_f32 v67, -v191, v75, v67
	ds_read_b32 v75, v0 offset:48112
	ds_read_b128 v[112:115], v3 offset:8592
	ds_read_b128 v[188:191], v3 offset:8608
	s_waitcnt lgkmcnt(9)
	v_fma_f32 v6, -v10, v69, v6
	v_fma_f32 v7, -v11, v69, v7
	v_fma_f32 v9, -v12, v69, v9
	v_fma_f32 v59, -v13, v69, v59
	v_fma_f32 v61, -v14, v69, v61
	v_fma_f32 v63, -v15, v69, v63
	v_fma_f32 v65, -v16, v69, v65
	v_fma_f32 v67, -v17, v69, v67
	ds_read_b32 v69, v2 offset:0
	ds_read_b128 v[10:13], v3 offset:8864
	ds_read_b128 v[14:17], v3 offset:8880
	s_waitcnt lgkmcnt(9)
	v_fma_f32 v6, -v96, v71, v6
	v_fma_f32 v7, -v97, v71, v7
	v_fma_f32 v9, -v98, v71, v9
	v_fma_f32 v59, -v99, v71, v59
	v_fma_f32 v61, -v100, v71, v61
	v_fma_f32 v63, -v101, v71, v63
	v_fma_f32 v65, -v102, v71, v65
	v_fma_f32 v67, -v103, v71, v67
	ds_read_b32 v71, v2 offset:1552
	ds_read_b128 v[96:99], v3 offset:9136
	ds_read_b128 v[100:103], v3 offset:9152
	s_waitcnt lgkmcnt(9)
	v_fma_f32 v6, -v104, v73, v6
	v_fma_f32 v7, -v105, v73, v7
	v_fma_f32 v9, -v106, v73, v9
	v_fma_f32 v59, -v107, v73, v59
	v_fma_f32 v61, -v108, v73, v61
	v_fma_f32 v63, -v109, v73, v63
	v_fma_f32 v65, -v110, v73, v65
	v_fma_f32 v67, -v111, v73, v67
	ds_read_b32 v73, v2 offset:3104
	ds_read_b128 v[104:107], v3 offset:9408
	ds_read_b128 v[108:111], v3 offset:9424
	s_waitcnt lgkmcnt(9)
	v_fma_f32 v6, -v112, v75, v6
	v_fma_f32 v7, -v113, v75, v7
	v_fma_f32 v9, -v114, v75, v9
	v_fma_f32 v59, -v115, v75, v59
	v_fma_f32 v61, -v188, v75, v61
	v_fma_f32 v63, -v189, v75, v63
	v_fma_f32 v65, -v190, v75, v65
	v_fma_f32 v67, -v191, v75, v67
	ds_read_b32 v75, v2 offset:4656
	ds_read_b128 v[112:115], v3 offset:9680
	ds_read_b128 v[188:191], v3 offset:9696
	s_waitcnt lgkmcnt(9)
	v_fma_f32 v6, -v10, v69, v6
	v_fma_f32 v7, -v11, v69, v7
	v_fma_f32 v9, -v12, v69, v9
	v_fma_f32 v59, -v13, v69, v59
	v_fma_f32 v61, -v14, v69, v61
	v_fma_f32 v63, -v15, v69, v63
	v_fma_f32 v65, -v16, v69, v65
	v_fma_f32 v67, -v17, v69, v67
	ds_read_b32 v69, v2 offset:6208
	ds_read_b128 v[10:13], v3 offset:9952
	ds_read_b128 v[14:17], v3 offset:9968
	s_waitcnt lgkmcnt(9)
	v_fma_f32 v6, -v96, v71, v6
	v_fma_f32 v7, -v97, v71, v7
	v_fma_f32 v9, -v98, v71, v9
	v_fma_f32 v59, -v99, v71, v59
	v_fma_f32 v61, -v100, v71, v61
	v_fma_f32 v63, -v101, v71, v63
	v_fma_f32 v65, -v102, v71, v65
	v_fma_f32 v67, -v103, v71, v67
	ds_read_b32 v71, v2 offset:7760
	ds_read_b128 v[96:99], v3 offset:10224
	ds_read_b128 v[100:103], v3 offset:10240
	s_waitcnt lgkmcnt(9)
	v_fma_f32 v6, -v104, v73, v6
	v_fma_f32 v7, -v105, v73, v7
	v_fma_f32 v9, -v106, v73, v9
	v_fma_f32 v59, -v107, v73, v59
	v_fma_f32 v61, -v108, v73, v61
	v_fma_f32 v63, -v109, v73, v63
	v_fma_f32 v65, -v110, v73, v65
	v_fma_f32 v67, -v111, v73, v67
	ds_read_b32 v73, v2 offset:9312
	ds_read_b128 v[104:107], v3 offset:10496
	ds_read_b128 v[108:111], v3 offset:10512
	s_waitcnt lgkmcnt(9)
	v_fma_f32 v6, -v112, v75, v6
	v_fma_f32 v7, -v113, v75, v7
	v_fma_f32 v9, -v114, v75, v9
	v_fma_f32 v59, -v115, v75, v59
	v_fma_f32 v61, -v188, v75, v61
	v_fma_f32 v63, -v189, v75, v63
	v_fma_f32 v65, -v190, v75, v65
	v_fma_f32 v67, -v191, v75, v67
	ds_read_b32 v75, v2 offset:10864
	ds_read_b128 v[112:115], v3 offset:10768
	ds_read_b128 v[188:191], v3 offset:10784
	s_waitcnt lgkmcnt(9)
	v_fma_f32 v6, -v10, v69, v6
	v_fma_f32 v7, -v11, v69, v7
	v_fma_f32 v9, -v12, v69, v9
	v_fma_f32 v59, -v13, v69, v59
	v_fma_f32 v61, -v14, v69, v61
	v_fma_f32 v63, -v15, v69, v63
	v_fma_f32 v65, -v16, v69, v65
	v_fma_f32 v67, -v17, v69, v67
	ds_read_b128 v[194:197], v3 offset:11040
	ds_read_b128 v[198:201], v3 offset:11056
	s_waitcnt lgkmcnt(8)
	v_fma_f32 v6, -v96, v71, v6
	v_fma_f32 v7, -v97, v71, v7
	v_fma_f32 v9, -v98, v71, v9
	v_fma_f32 v59, -v99, v71, v59
	v_fma_f32 v61, -v100, v71, v61
	v_fma_f32 v63, -v101, v71, v63
	v_fma_f32 v65, -v102, v71, v65
	v_fma_f32 v67, -v103, v71, v67
	ds_read_b128 v[202:205], v3 offset:11312
	ds_read_b128 v[206:209], v3 offset:11328
	s_waitcnt lgkmcnt(7)
	v_fma_f32 v6, -v104, v73, v6
	v_fma_f32 v7, -v105, v73, v7
	v_fma_f32 v9, -v106, v73, v9
	v_fma_f32 v59, -v107, v73, v59
	v_fma_f32 v61, -v108, v73, v61
	v_fma_f32 v63, -v109, v73, v63
	v_fma_f32 v65, -v110, v73, v65
	v_fma_f32 v67, -v111, v73, v67
	ds_read_b128 v[220:223], v3 offset:11584
	ds_read_b128 v[226:229], v3 offset:11600
	s_waitcnt lgkmcnt(6)
	v_fma_f32 v6, -v112, v75, v6
	v_fma_f32 v7, -v113, v75, v7
	v_fma_f32 v9, -v114, v75, v9
	v_fma_f32 v59, -v115, v75, v59
	v_fma_f32 v61, -v188, v75, v61
	v_fma_f32 v63, -v189, v75, v63
	v_fma_f32 v65, -v190, v75, v65
	v_fma_f32 v67, -v191, v75, v67
	ds_read_b128 v[230:233], v3 offset:11872
	s_waitcnt lgkmcnt(5)
	v_fma_f32 v7, -v195, v6, v7
	v_fma_f32 v9, -v196, v6, v9
	v_fma_f32 v59, -v197, v6, v59
	v_fma_f32 v61, -v198, v6, v61
	v_fma_f32 v63, -v199, v6, v63
	v_fma_f32 v65, -v200, v6, v65
	v_fma_f32 v67, -v201, v6, v67
	ds_read_b128 v[234:237], v3 offset:12144
	s_waitcnt lgkmcnt(4)
	v_fma_f32 v9, -v204, v7, v9
	v_fma_f32 v59, -v205, v7, v59
	v_fma_f32 v61, -v206, v7, v61
	v_fma_f32 v63, -v207, v7, v63
	v_fma_f32 v65, -v208, v7, v65
	v_fma_f32 v67, -v209, v7, v67
	ds_read_b128 v[238:241], v3 offset:12416
	s_waitcnt lgkmcnt(3)
	v_fma_f32 v59, -v223, v9, v59
	v_fma_f32 v61, -v226, v9, v61
	v_fma_f32 v63, -v227, v9, v63
	v_fma_f32 v65, -v228, v9, v65
	v_fma_f32 v67, -v229, v9, v67
	ds_read_b128 v[242:245], v3 offset:12688
	s_waitcnt lgkmcnt(3)
	v_fma_f32 v61, -v230, v59, v61
	v_fma_f32 v63, -v231, v59, v63
	v_fma_f32 v65, -v232, v59, v65
	v_fma_f32 v67, -v233, v59, v67
	s_waitcnt lgkmcnt(2)
	v_fma_f32 v63, -v235, v61, v63
	v_fma_f32 v65, -v236, v61, v65
	v_fma_f32 v67, -v237, v61, v67
	s_waitcnt lgkmcnt(1)
	v_fma_f32 v65, -v240, v63, v65
	v_fma_f32 v67, -v241, v63, v67
	s_waitcnt lgkmcnt(0)
	v_fma_f32 v67, -v245, v65, v67
	s_nop 0
	ds_write_b32 v2, v6 offset:12416
	ds_write_b32 v2, v7 offset:13968
	ds_write_b32 v2, v9 offset:15520
	ds_write_b32 v2, v59 offset:17072
	ds_write_b32 v2, v61 offset:18624
	ds_write_b32 v2, v63 offset:20176
	ds_write_b32 v2, v65 offset:21728
	ds_write_b32 v2, v67 offset:23280
	ds_read_b32 v6, v2 offset:24832
	ds_read_b32 v7, v2 offset:26384
	ds_read_b32 v9, v2 offset:27936
	ds_read_b32 v59, v2 offset:29488
	ds_read_b32 v61, v2 offset:31040
	ds_read_b32 v63, v2 offset:32592
	ds_read_b32 v65, v2 offset:34144
	ds_read_b32 v67, v2 offset:35696
	ds_read_b32 v69, v0 offset:0
	ds_read_b128 v[10:13], v3 offset:192
	ds_read_b128 v[14:17], v3 offset:208
	s_waitcnt lgkmcnt(0)
	v_fma_f32 v6, -v10, v69, v6
	v_fma_f32 v7, -v11, v69, v7
	v_fma_f32 v9, -v12, v69, v9
	v_fma_f32 v59, -v13, v69, v59
	v_fma_f32 v61, -v14, v69, v61
	v_fma_f32 v63, -v15, v69, v63
	v_fma_f32 v65, -v16, v69, v65
	v_fma_f32 v67, -v17, v69, v67
	ds_read_b32 v71, v0 offset:1552
	ds_read_b128 v[96:99], v3 offset:464
	ds_read_b128 v[100:103], v3 offset:480
	ds_read_b32 v73, v0 offset:3104
	ds_read_b128 v[104:107], v3 offset:736
	ds_read_b128 v[108:111], v3 offset:752
	ds_read_b32 v75, v0 offset:4656
	ds_read_b128 v[112:115], v3 offset:1008
	ds_read_b128 v[188:191], v3 offset:1024
	ds_read_b32 v69, v0 offset:6208
	ds_read_b128 v[10:13], v3 offset:1280
	ds_read_b128 v[14:17], v3 offset:1296
	s_waitcnt lgkmcnt(9)
	v_fma_f32 v6, -v96, v71, v6
	v_fma_f32 v7, -v97, v71, v7
	v_fma_f32 v9, -v98, v71, v9
	v_fma_f32 v59, -v99, v71, v59
	v_fma_f32 v61, -v100, v71, v61
	v_fma_f32 v63, -v101, v71, v63
	v_fma_f32 v65, -v102, v71, v65
	v_fma_f32 v67, -v103, v71, v67
	ds_read_b32 v71, v0 offset:7760
	ds_read_b128 v[96:99], v3 offset:1552
	ds_read_b128 v[100:103], v3 offset:1568
	s_waitcnt lgkmcnt(9)
	v_fma_f32 v6, -v104, v73, v6
	v_fma_f32 v7, -v105, v73, v7
	v_fma_f32 v9, -v106, v73, v9
	v_fma_f32 v59, -v107, v73, v59
	v_fma_f32 v61, -v108, v73, v61
	v_fma_f32 v63, -v109, v73, v63
	v_fma_f32 v65, -v110, v73, v65
	v_fma_f32 v67, -v111, v73, v67
	ds_read_b32 v73, v0 offset:9312
	ds_read_b128 v[104:107], v3 offset:1824
	ds_read_b128 v[108:111], v3 offset:1840
	s_waitcnt lgkmcnt(9)
	v_fma_f32 v6, -v112, v75, v6
	v_fma_f32 v7, -v113, v75, v7
	v_fma_f32 v9, -v114, v75, v9
	v_fma_f32 v59, -v115, v75, v59
	v_fma_f32 v61, -v188, v75, v61
	v_fma_f32 v63, -v189, v75, v63
	v_fma_f32 v65, -v190, v75, v65
	v_fma_f32 v67, -v191, v75, v67
	ds_read_b32 v75, v0 offset:10864
	ds_read_b128 v[112:115], v3 offset:2096
	ds_read_b128 v[188:191], v3 offset:2112
	s_waitcnt lgkmcnt(9)
	v_fma_f32 v6, -v10, v69, v6
	v_fma_f32 v7, -v11, v69, v7
	v_fma_f32 v9, -v12, v69, v9
	v_fma_f32 v59, -v13, v69, v59
	v_fma_f32 v61, -v14, v69, v61
	v_fma_f32 v63, -v15, v69, v63
	v_fma_f32 v65, -v16, v69, v65
	v_fma_f32 v67, -v17, v69, v67
	ds_read_b32 v69, v0 offset:12416
	ds_read_b128 v[10:13], v3 offset:2368
	ds_read_b128 v[14:17], v3 offset:2384
	s_waitcnt lgkmcnt(9)
	v_fma_f32 v6, -v96, v71, v6
	v_fma_f32 v7, -v97, v71, v7
	v_fma_f32 v9, -v98, v71, v9
	v_fma_f32 v59, -v99, v71, v59
	v_fma_f32 v61, -v100, v71, v61
	v_fma_f32 v63, -v101, v71, v63
	v_fma_f32 v65, -v102, v71, v65
	v_fma_f32 v67, -v103, v71, v67
	ds_read_b32 v71, v0 offset:13968
	ds_read_b128 v[96:99], v3 offset:2640
	ds_read_b128 v[100:103], v3 offset:2656
	s_waitcnt lgkmcnt(9)
	v_fma_f32 v6, -v104, v73, v6
	v_fma_f32 v7, -v105, v73, v7
	v_fma_f32 v9, -v106, v73, v9
	v_fma_f32 v59, -v107, v73, v59
	v_fma_f32 v61, -v108, v73, v61
	v_fma_f32 v63, -v109, v73, v63
	v_fma_f32 v65, -v110, v73, v65
	v_fma_f32 v67, -v111, v73, v67
	ds_read_b32 v73, v0 offset:15520
	ds_read_b128 v[104:107], v3 offset:2912
	ds_read_b128 v[108:111], v3 offset:2928
	s_waitcnt lgkmcnt(9)
	v_fma_f32 v6, -v112, v75, v6
	v_fma_f32 v7, -v113, v75, v7
	v_fma_f32 v9, -v114, v75, v9
	v_fma_f32 v59, -v115, v75, v59
	v_fma_f32 v61, -v188, v75, v61
	v_fma_f32 v63, -v189, v75, v63
	v_fma_f32 v65, -v190, v75, v65
	v_fma_f32 v67, -v191, v75, v67
	ds_read_b32 v75, v0 offset:17072
	ds_read_b128 v[112:115], v3 offset:3184
	ds_read_b128 v[188:191], v3 offset:3200
	s_waitcnt lgkmcnt(9)
	v_fma_f32 v6, -v10, v69, v6
	v_fma_f32 v7, -v11, v69, v7
	v_fma_f32 v9, -v12, v69, v9
	v_fma_f32 v59, -v13, v69, v59
	v_fma_f32 v61, -v14, v69, v61
	v_fma_f32 v63, -v15, v69, v63
	v_fma_f32 v65, -v16, v69, v65
	v_fma_f32 v67, -v17, v69, v67
	ds_read_b32 v69, v0 offset:18624
	ds_read_b128 v[10:13], v3 offset:3456
	ds_read_b128 v[14:17], v3 offset:3472
	s_waitcnt lgkmcnt(9)
	v_fma_f32 v6, -v96, v71, v6
	v_fma_f32 v7, -v97, v71, v7
	v_fma_f32 v9, -v98, v71, v9
	v_fma_f32 v59, -v99, v71, v59
	v_fma_f32 v61, -v100, v71, v61
	v_fma_f32 v63, -v101, v71, v63
	v_fma_f32 v65, -v102, v71, v65
	v_fma_f32 v67, -v103, v71, v67
	ds_read_b32 v71, v0 offset:20176
	ds_read_b128 v[96:99], v3 offset:3728
	ds_read_b128 v[100:103], v3 offset:3744
	s_waitcnt lgkmcnt(9)
	v_fma_f32 v6, -v104, v73, v6
	v_fma_f32 v7, -v105, v73, v7
	v_fma_f32 v9, -v106, v73, v9
	v_fma_f32 v59, -v107, v73, v59
	v_fma_f32 v61, -v108, v73, v61
	v_fma_f32 v63, -v109, v73, v63
	v_fma_f32 v65, -v110, v73, v65
	v_fma_f32 v67, -v111, v73, v67
	ds_read_b32 v73, v0 offset:21728
	ds_read_b128 v[104:107], v3 offset:4000
	ds_read_b128 v[108:111], v3 offset:4016
	s_waitcnt lgkmcnt(9)
	v_fma_f32 v6, -v112, v75, v6
	v_fma_f32 v7, -v113, v75, v7
	v_fma_f32 v9, -v114, v75, v9
	v_fma_f32 v59, -v115, v75, v59
	v_fma_f32 v61, -v188, v75, v61
	v_fma_f32 v63, -v189, v75, v63
	v_fma_f32 v65, -v190, v75, v65
	v_fma_f32 v67, -v191, v75, v67
	ds_read_b32 v75, v0 offset:23280
	ds_read_b128 v[112:115], v3 offset:4272
	ds_read_b128 v[188:191], v3 offset:4288
	s_waitcnt lgkmcnt(9)
	v_fma_f32 v6, -v10, v69, v6
	v_fma_f32 v7, -v11, v69, v7
	v_fma_f32 v9, -v12, v69, v9
	v_fma_f32 v59, -v13, v69, v59
	v_fma_f32 v61, -v14, v69, v61
	v_fma_f32 v63, -v15, v69, v63
	v_fma_f32 v65, -v16, v69, v65
	v_fma_f32 v67, -v17, v69, v67
	ds_read_b32 v69, v0 offset:24832
	ds_read_b128 v[10:13], v3 offset:4544
	ds_read_b128 v[14:17], v3 offset:4560
	s_waitcnt lgkmcnt(9)
	v_fma_f32 v6, -v96, v71, v6
	v_fma_f32 v7, -v97, v71, v7
	v_fma_f32 v9, -v98, v71, v9
	v_fma_f32 v59, -v99, v71, v59
	v_fma_f32 v61, -v100, v71, v61
	v_fma_f32 v63, -v101, v71, v63
	v_fma_f32 v65, -v102, v71, v65
	v_fma_f32 v67, -v103, v71, v67
	ds_read_b32 v71, v0 offset:26384
	ds_read_b128 v[96:99], v3 offset:4816
	ds_read_b128 v[100:103], v3 offset:4832
	s_waitcnt lgkmcnt(9)
	v_fma_f32 v6, -v104, v73, v6
	v_fma_f32 v7, -v105, v73, v7
	v_fma_f32 v9, -v106, v73, v9
	v_fma_f32 v59, -v107, v73, v59
	v_fma_f32 v61, -v108, v73, v61
	v_fma_f32 v63, -v109, v73, v63
	v_fma_f32 v65, -v110, v73, v65
	v_fma_f32 v67, -v111, v73, v67
	ds_read_b32 v73, v0 offset:27936
	ds_read_b128 v[104:107], v3 offset:5088
	ds_read_b128 v[108:111], v3 offset:5104
	s_waitcnt lgkmcnt(9)
	v_fma_f32 v6, -v112, v75, v6
	v_fma_f32 v7, -v113, v75, v7
	v_fma_f32 v9, -v114, v75, v9
	v_fma_f32 v59, -v115, v75, v59
	v_fma_f32 v61, -v188, v75, v61
	v_fma_f32 v63, -v189, v75, v63
	v_fma_f32 v65, -v190, v75, v65
	v_fma_f32 v67, -v191, v75, v67
	ds_read_b32 v75, v0 offset:29488
	ds_read_b128 v[112:115], v3 offset:5360
	ds_read_b128 v[188:191], v3 offset:5376
	s_waitcnt lgkmcnt(9)
	v_fma_f32 v6, -v10, v69, v6
	v_fma_f32 v7, -v11, v69, v7
	v_fma_f32 v9, -v12, v69, v9
	v_fma_f32 v59, -v13, v69, v59
	v_fma_f32 v61, -v14, v69, v61
	v_fma_f32 v63, -v15, v69, v63
	v_fma_f32 v65, -v16, v69, v65
	v_fma_f32 v67, -v17, v69, v67
	ds_read_b32 v69, v0 offset:31040
	ds_read_b128 v[10:13], v3 offset:5632
	ds_read_b128 v[14:17], v3 offset:5648
	s_waitcnt lgkmcnt(9)
	v_fma_f32 v6, -v96, v71, v6
	v_fma_f32 v7, -v97, v71, v7
	v_fma_f32 v9, -v98, v71, v9
	v_fma_f32 v59, -v99, v71, v59
	v_fma_f32 v61, -v100, v71, v61
	v_fma_f32 v63, -v101, v71, v63
	v_fma_f32 v65, -v102, v71, v65
	v_fma_f32 v67, -v103, v71, v67
	ds_read_b32 v71, v0 offset:32592
	ds_read_b128 v[96:99], v3 offset:5904
	ds_read_b128 v[100:103], v3 offset:5920
	s_waitcnt lgkmcnt(9)
	v_fma_f32 v6, -v104, v73, v6
	v_fma_f32 v7, -v105, v73, v7
	v_fma_f32 v9, -v106, v73, v9
	v_fma_f32 v59, -v107, v73, v59
	v_fma_f32 v61, -v108, v73, v61
	v_fma_f32 v63, -v109, v73, v63
	v_fma_f32 v65, -v110, v73, v65
	v_fma_f32 v67, -v111, v73, v67
	ds_read_b32 v73, v0 offset:34144
	ds_read_b128 v[104:107], v3 offset:6176
	ds_read_b128 v[108:111], v3 offset:6192
	s_waitcnt lgkmcnt(9)
	v_fma_f32 v6, -v112, v75, v6
	v_fma_f32 v7, -v113, v75, v7
	v_fma_f32 v9, -v114, v75, v9
	v_fma_f32 v59, -v115, v75, v59
	v_fma_f32 v61, -v188, v75, v61
	v_fma_f32 v63, -v189, v75, v63
	v_fma_f32 v65, -v190, v75, v65
	v_fma_f32 v67, -v191, v75, v67
	ds_read_b32 v75, v0 offset:35696
	ds_read_b128 v[112:115], v3 offset:6448
	ds_read_b128 v[188:191], v3 offset:6464
	s_waitcnt lgkmcnt(9)
	v_fma_f32 v6, -v10, v69, v6
	v_fma_f32 v7, -v11, v69, v7
	v_fma_f32 v9, -v12, v69, v9
	v_fma_f32 v59, -v13, v69, v59
	v_fma_f32 v61, -v14, v69, v61
	v_fma_f32 v63, -v15, v69, v63
	v_fma_f32 v65, -v16, v69, v65
	v_fma_f32 v67, -v17, v69, v67
	ds_read_b32 v69, v0 offset:37248
	ds_read_b128 v[10:13], v3 offset:6720
	ds_read_b128 v[14:17], v3 offset:6736
	s_waitcnt lgkmcnt(9)
	v_fma_f32 v6, -v96, v71, v6
	v_fma_f32 v7, -v97, v71, v7
	v_fma_f32 v9, -v98, v71, v9
	v_fma_f32 v59, -v99, v71, v59
	v_fma_f32 v61, -v100, v71, v61
	v_fma_f32 v63, -v101, v71, v63
	v_fma_f32 v65, -v102, v71, v65
	v_fma_f32 v67, -v103, v71, v67
	ds_read_b32 v71, v0 offset:38800
	ds_read_b128 v[96:99], v3 offset:6992
	ds_read_b128 v[100:103], v3 offset:7008
	s_waitcnt lgkmcnt(9)
	v_fma_f32 v6, -v104, v73, v6
	v_fma_f32 v7, -v105, v73, v7
	v_fma_f32 v9, -v106, v73, v9
	v_fma_f32 v59, -v107, v73, v59
	v_fma_f32 v61, -v108, v73, v61
	v_fma_f32 v63, -v109, v73, v63
	v_fma_f32 v65, -v110, v73, v65
	v_fma_f32 v67, -v111, v73, v67
	ds_read_b32 v73, v0 offset:40352
	ds_read_b128 v[104:107], v3 offset:7264
	ds_read_b128 v[108:111], v3 offset:7280
	s_waitcnt lgkmcnt(9)
	v_fma_f32 v6, -v112, v75, v6
	v_fma_f32 v7, -v113, v75, v7
	v_fma_f32 v9, -v114, v75, v9
	v_fma_f32 v59, -v115, v75, v59
	v_fma_f32 v61, -v188, v75, v61
	v_fma_f32 v63, -v189, v75, v63
	v_fma_f32 v65, -v190, v75, v65
	v_fma_f32 v67, -v191, v75, v67
	ds_read_b32 v75, v0 offset:41904
	ds_read_b128 v[112:115], v3 offset:7536
	ds_read_b128 v[188:191], v3 offset:7552
	s_waitcnt lgkmcnt(9)
	v_fma_f32 v6, -v10, v69, v6
	v_fma_f32 v7, -v11, v69, v7
	v_fma_f32 v9, -v12, v69, v9
	v_fma_f32 v59, -v13, v69, v59
	v_fma_f32 v61, -v14, v69, v61
	v_fma_f32 v63, -v15, v69, v63
	v_fma_f32 v65, -v16, v69, v65
	v_fma_f32 v67, -v17, v69, v67
	ds_read_b32 v69, v0 offset:43456
	ds_read_b128 v[10:13], v3 offset:7808
	ds_read_b128 v[14:17], v3 offset:7824
	s_waitcnt lgkmcnt(9)
	v_fma_f32 v6, -v96, v71, v6
	v_fma_f32 v7, -v97, v71, v7
	v_fma_f32 v9, -v98, v71, v9
	v_fma_f32 v59, -v99, v71, v59
	v_fma_f32 v61, -v100, v71, v61
	v_fma_f32 v63, -v101, v71, v63
	v_fma_f32 v65, -v102, v71, v65
	v_fma_f32 v67, -v103, v71, v67
	ds_read_b32 v71, v0 offset:45008
	ds_read_b128 v[96:99], v3 offset:8080
	ds_read_b128 v[100:103], v3 offset:8096
	s_waitcnt lgkmcnt(9)
	v_fma_f32 v6, -v104, v73, v6
	v_fma_f32 v7, -v105, v73, v7
	v_fma_f32 v9, -v106, v73, v9
	v_fma_f32 v59, -v107, v73, v59
	v_fma_f32 v61, -v108, v73, v61
	v_fma_f32 v63, -v109, v73, v63
	v_fma_f32 v65, -v110, v73, v65
	v_fma_f32 v67, -v111, v73, v67
	ds_read_b32 v73, v0 offset:46560
	ds_read_b128 v[104:107], v3 offset:8352
	ds_read_b128 v[108:111], v3 offset:8368
	s_waitcnt lgkmcnt(9)
	v_fma_f32 v6, -v112, v75, v6
	v_fma_f32 v7, -v113, v75, v7
	v_fma_f32 v9, -v114, v75, v9
	v_fma_f32 v59, -v115, v75, v59
	v_fma_f32 v61, -v188, v75, v61
	v_fma_f32 v63, -v189, v75, v63
	v_fma_f32 v65, -v190, v75, v65
	v_fma_f32 v67, -v191, v75, v67
	ds_read_b32 v75, v0 offset:48112
	ds_read_b128 v[112:115], v3 offset:8624
	ds_read_b128 v[188:191], v3 offset:8640
	s_waitcnt lgkmcnt(9)
	v_fma_f32 v6, -v10, v69, v6
	v_fma_f32 v7, -v11, v69, v7
	v_fma_f32 v9, -v12, v69, v9
	v_fma_f32 v59, -v13, v69, v59
	v_fma_f32 v61, -v14, v69, v61
	v_fma_f32 v63, -v15, v69, v63
	v_fma_f32 v65, -v16, v69, v65
	v_fma_f32 v67, -v17, v69, v67
	ds_read_b32 v69, v2 offset:0
	ds_read_b128 v[10:13], v3 offset:8896
	ds_read_b128 v[14:17], v3 offset:8912
	s_waitcnt lgkmcnt(9)
	v_fma_f32 v6, -v96, v71, v6
	v_fma_f32 v7, -v97, v71, v7
	v_fma_f32 v9, -v98, v71, v9
	v_fma_f32 v59, -v99, v71, v59
	v_fma_f32 v61, -v100, v71, v61
	v_fma_f32 v63, -v101, v71, v63
	v_fma_f32 v65, -v102, v71, v65
	v_fma_f32 v67, -v103, v71, v67
	ds_read_b32 v71, v2 offset:1552
	ds_read_b128 v[96:99], v3 offset:9168
	ds_read_b128 v[100:103], v3 offset:9184
	s_waitcnt lgkmcnt(9)
	v_fma_f32 v6, -v104, v73, v6
	v_fma_f32 v7, -v105, v73, v7
	v_fma_f32 v9, -v106, v73, v9
	v_fma_f32 v59, -v107, v73, v59
	v_fma_f32 v61, -v108, v73, v61
	v_fma_f32 v63, -v109, v73, v63
	v_fma_f32 v65, -v110, v73, v65
	v_fma_f32 v67, -v111, v73, v67
	ds_read_b32 v73, v2 offset:3104
	ds_read_b128 v[104:107], v3 offset:9440
	ds_read_b128 v[108:111], v3 offset:9456
	s_waitcnt lgkmcnt(9)
	v_fma_f32 v6, -v112, v75, v6
	v_fma_f32 v7, -v113, v75, v7
	v_fma_f32 v9, -v114, v75, v9
	v_fma_f32 v59, -v115, v75, v59
	v_fma_f32 v61, -v188, v75, v61
	v_fma_f32 v63, -v189, v75, v63
	v_fma_f32 v65, -v190, v75, v65
	v_fma_f32 v67, -v191, v75, v67
	ds_read_b32 v75, v2 offset:4656
	ds_read_b128 v[112:115], v3 offset:9712
	ds_read_b128 v[188:191], v3 offset:9728
	s_waitcnt lgkmcnt(9)
	v_fma_f32 v6, -v10, v69, v6
	v_fma_f32 v7, -v11, v69, v7
	v_fma_f32 v9, -v12, v69, v9
	v_fma_f32 v59, -v13, v69, v59
	v_fma_f32 v61, -v14, v69, v61
	v_fma_f32 v63, -v15, v69, v63
	v_fma_f32 v65, -v16, v69, v65
	v_fma_f32 v67, -v17, v69, v67
	ds_read_b32 v69, v2 offset:6208
	ds_read_b128 v[10:13], v3 offset:9984
	ds_read_b128 v[14:17], v3 offset:10000
	s_waitcnt lgkmcnt(9)
	v_fma_f32 v6, -v96, v71, v6
	v_fma_f32 v7, -v97, v71, v7
	v_fma_f32 v9, -v98, v71, v9
	v_fma_f32 v59, -v99, v71, v59
	v_fma_f32 v61, -v100, v71, v61
	v_fma_f32 v63, -v101, v71, v63
	v_fma_f32 v65, -v102, v71, v65
	v_fma_f32 v67, -v103, v71, v67
	ds_read_b32 v71, v2 offset:7760
	ds_read_b128 v[96:99], v3 offset:10256
	ds_read_b128 v[100:103], v3 offset:10272
	s_waitcnt lgkmcnt(9)
	v_fma_f32 v6, -v104, v73, v6
	v_fma_f32 v7, -v105, v73, v7
	v_fma_f32 v9, -v106, v73, v9
	v_fma_f32 v59, -v107, v73, v59
	v_fma_f32 v61, -v108, v73, v61
	v_fma_f32 v63, -v109, v73, v63
	v_fma_f32 v65, -v110, v73, v65
	v_fma_f32 v67, -v111, v73, v67
	ds_read_b32 v73, v2 offset:9312
	ds_read_b128 v[104:107], v3 offset:10528
	ds_read_b128 v[108:111], v3 offset:10544
	s_waitcnt lgkmcnt(9)
	v_fma_f32 v6, -v112, v75, v6
	v_fma_f32 v7, -v113, v75, v7
	v_fma_f32 v9, -v114, v75, v9
	v_fma_f32 v59, -v115, v75, v59
	v_fma_f32 v61, -v188, v75, v61
	v_fma_f32 v63, -v189, v75, v63
	v_fma_f32 v65, -v190, v75, v65
	v_fma_f32 v67, -v191, v75, v67
	ds_read_b32 v75, v2 offset:10864
	ds_read_b128 v[112:115], v3 offset:10800
	ds_read_b128 v[188:191], v3 offset:10816
	s_waitcnt lgkmcnt(9)
	v_fma_f32 v6, -v10, v69, v6
	v_fma_f32 v7, -v11, v69, v7
	v_fma_f32 v9, -v12, v69, v9
	v_fma_f32 v59, -v13, v69, v59
	v_fma_f32 v61, -v14, v69, v61
	v_fma_f32 v63, -v15, v69, v63
	v_fma_f32 v65, -v16, v69, v65
	v_fma_f32 v67, -v17, v69, v67
	ds_read_b32 v69, v2 offset:12416
	ds_read_b128 v[10:13], v3 offset:11072
	ds_read_b128 v[14:17], v3 offset:11088
	s_waitcnt lgkmcnt(9)
	v_fma_f32 v6, -v96, v71, v6
	v_fma_f32 v7, -v97, v71, v7
	v_fma_f32 v9, -v98, v71, v9
	v_fma_f32 v59, -v99, v71, v59
	v_fma_f32 v61, -v100, v71, v61
	v_fma_f32 v63, -v101, v71, v63
	v_fma_f32 v65, -v102, v71, v65
	v_fma_f32 v67, -v103, v71, v67
	ds_read_b32 v71, v2 offset:13968
	ds_read_b128 v[96:99], v3 offset:11344
	ds_read_b128 v[100:103], v3 offset:11360
	s_waitcnt lgkmcnt(9)
	v_fma_f32 v6, -v104, v73, v6
	v_fma_f32 v7, -v105, v73, v7
	v_fma_f32 v9, -v106, v73, v9
	v_fma_f32 v59, -v107, v73, v59
	v_fma_f32 v61, -v108, v73, v61
	v_fma_f32 v63, -v109, v73, v63
	v_fma_f32 v65, -v110, v73, v65
	v_fma_f32 v67, -v111, v73, v67
	ds_read_b32 v73, v2 offset:15520
	ds_read_b128 v[104:107], v3 offset:11616
	ds_read_b128 v[108:111], v3 offset:11632
	s_waitcnt lgkmcnt(9)
	v_fma_f32 v6, -v112, v75, v6
	v_fma_f32 v7, -v113, v75, v7
	v_fma_f32 v9, -v114, v75, v9
	v_fma_f32 v59, -v115, v75, v59
	v_fma_f32 v61, -v188, v75, v61
	v_fma_f32 v63, -v189, v75, v63
	v_fma_f32 v65, -v190, v75, v65
	v_fma_f32 v67, -v191, v75, v67
	ds_read_b32 v75, v2 offset:17072
	ds_read_b128 v[112:115], v3 offset:11888
	ds_read_b128 v[188:191], v3 offset:11904
	s_waitcnt lgkmcnt(9)
	v_fma_f32 v6, -v10, v69, v6
	v_fma_f32 v7, -v11, v69, v7
	v_fma_f32 v9, -v12, v69, v9
	v_fma_f32 v59, -v13, v69, v59
	v_fma_f32 v61, -v14, v69, v61
	v_fma_f32 v63, -v15, v69, v63
	v_fma_f32 v65, -v16, v69, v65
	v_fma_f32 v67, -v17, v69, v67
	ds_read_b32 v69, v2 offset:18624
	ds_read_b128 v[10:13], v3 offset:12160
	ds_read_b128 v[14:17], v3 offset:12176
	s_waitcnt lgkmcnt(9)
	v_fma_f32 v6, -v96, v71, v6
	v_fma_f32 v7, -v97, v71, v7
	v_fma_f32 v9, -v98, v71, v9
	v_fma_f32 v59, -v99, v71, v59
	v_fma_f32 v61, -v100, v71, v61
	v_fma_f32 v63, -v101, v71, v63
	v_fma_f32 v65, -v102, v71, v65
	v_fma_f32 v67, -v103, v71, v67
	ds_read_b32 v71, v2 offset:20176
	ds_read_b128 v[96:99], v3 offset:12432
	ds_read_b128 v[100:103], v3 offset:12448
	s_waitcnt lgkmcnt(9)
	v_fma_f32 v6, -v104, v73, v6
	v_fma_f32 v7, -v105, v73, v7
	v_fma_f32 v9, -v106, v73, v9
	v_fma_f32 v59, -v107, v73, v59
	v_fma_f32 v61, -v108, v73, v61
	v_fma_f32 v63, -v109, v73, v63
	v_fma_f32 v65, -v110, v73, v65
	v_fma_f32 v67, -v111, v73, v67
	ds_read_b32 v73, v2 offset:21728
	ds_read_b128 v[104:107], v3 offset:12704
	ds_read_b128 v[108:111], v3 offset:12720
	s_waitcnt lgkmcnt(9)
	v_fma_f32 v6, -v112, v75, v6
	v_fma_f32 v7, -v113, v75, v7
	v_fma_f32 v9, -v114, v75, v9
	v_fma_f32 v59, -v115, v75, v59
	v_fma_f32 v61, -v188, v75, v61
	v_fma_f32 v63, -v189, v75, v63
	v_fma_f32 v65, -v190, v75, v65
	v_fma_f32 v67, -v191, v75, v67
	ds_read_b32 v75, v2 offset:23280
	ds_read_b128 v[112:115], v3 offset:12976
	ds_read_b128 v[188:191], v3 offset:12992
	s_waitcnt lgkmcnt(9)
	v_fma_f32 v6, -v10, v69, v6
	v_fma_f32 v7, -v11, v69, v7
	v_fma_f32 v9, -v12, v69, v9
	v_fma_f32 v59, -v13, v69, v59
	v_fma_f32 v61, -v14, v69, v61
	v_fma_f32 v63, -v15, v69, v63
	v_fma_f32 v65, -v16, v69, v65
	v_fma_f32 v67, -v17, v69, v67
	ds_read_b128 v[194:197], v3 offset:13248
	ds_read_b128 v[198:201], v3 offset:13264
	s_waitcnt lgkmcnt(8)
	v_fma_f32 v6, -v96, v71, v6
	v_fma_f32 v7, -v97, v71, v7
	v_fma_f32 v9, -v98, v71, v9
	v_fma_f32 v59, -v99, v71, v59
	v_fma_f32 v61, -v100, v71, v61
	v_fma_f32 v63, -v101, v71, v63
	v_fma_f32 v65, -v102, v71, v65
	v_fma_f32 v67, -v103, v71, v67
	ds_read_b128 v[202:205], v3 offset:13520
	ds_read_b128 v[206:209], v3 offset:13536
	s_waitcnt lgkmcnt(7)
	v_fma_f32 v6, -v104, v73, v6
	v_fma_f32 v7, -v105, v73, v7
	v_fma_f32 v9, -v106, v73, v9
	v_fma_f32 v59, -v107, v73, v59
	v_fma_f32 v61, -v108, v73, v61
	v_fma_f32 v63, -v109, v73, v63
	v_fma_f32 v65, -v110, v73, v65
	v_fma_f32 v67, -v111, v73, v67
	ds_read_b128 v[220:223], v3 offset:13792
	ds_read_b128 v[226:229], v3 offset:13808
	s_waitcnt lgkmcnt(6)
	v_fma_f32 v6, -v112, v75, v6
	v_fma_f32 v7, -v113, v75, v7
	v_fma_f32 v9, -v114, v75, v9
	v_fma_f32 v59, -v115, v75, v59
	v_fma_f32 v61, -v188, v75, v61
	v_fma_f32 v63, -v189, v75, v63
	v_fma_f32 v65, -v190, v75, v65
	v_fma_f32 v67, -v191, v75, v67
	ds_read_b128 v[230:233], v3 offset:14080
	s_waitcnt lgkmcnt(5)
	v_fma_f32 v7, -v195, v6, v7
	v_fma_f32 v9, -v196, v6, v9
	v_fma_f32 v59, -v197, v6, v59
	v_fma_f32 v61, -v198, v6, v61
	v_fma_f32 v63, -v199, v6, v63
	v_fma_f32 v65, -v200, v6, v65
	v_fma_f32 v67, -v201, v6, v67
	ds_read_b128 v[234:237], v3 offset:14352
	s_waitcnt lgkmcnt(4)
	v_fma_f32 v9, -v204, v7, v9
	v_fma_f32 v59, -v205, v7, v59
	v_fma_f32 v61, -v206, v7, v61
	v_fma_f32 v63, -v207, v7, v63
	v_fma_f32 v65, -v208, v7, v65
	v_fma_f32 v67, -v209, v7, v67
	ds_read_b128 v[238:241], v3 offset:14624
	s_waitcnt lgkmcnt(3)
	v_fma_f32 v59, -v223, v9, v59
	v_fma_f32 v61, -v226, v9, v61
	v_fma_f32 v63, -v227, v9, v63
	v_fma_f32 v65, -v228, v9, v65
	v_fma_f32 v67, -v229, v9, v67
	ds_read_b128 v[242:245], v3 offset:14896
	s_waitcnt lgkmcnt(3)
	v_fma_f32 v61, -v230, v59, v61
	v_fma_f32 v63, -v231, v59, v63
	v_fma_f32 v65, -v232, v59, v65
	v_fma_f32 v67, -v233, v59, v67
	s_waitcnt lgkmcnt(2)
	v_fma_f32 v63, -v235, v61, v63
	v_fma_f32 v65, -v236, v61, v65
	v_fma_f32 v67, -v237, v61, v67
	s_waitcnt lgkmcnt(1)
	v_fma_f32 v65, -v240, v63, v65
	v_fma_f32 v67, -v241, v63, v67
	s_waitcnt lgkmcnt(0)
	v_fma_f32 v67, -v245, v65, v67
	s_nop 0
	ds_write_b32 v2, v6 offset:24832
	ds_write_b32 v2, v7 offset:26384
	ds_write_b32 v2, v9 offset:27936
	ds_write_b32 v2, v59 offset:29488
	ds_write_b32 v2, v61 offset:31040
	ds_write_b32 v2, v63 offset:32592
	ds_write_b32 v2, v65 offset:34144
	ds_write_b32 v2, v67 offset:35696
	ds_read_b32 v6, v2 offset:37248
	ds_read_b32 v7, v2 offset:38800
	ds_read_b32 v9, v2 offset:40352
	ds_read_b32 v59, v2 offset:41904
	ds_read_b32 v61, v2 offset:43456
	ds_read_b32 v63, v2 offset:45008
	ds_read_b32 v65, v2 offset:46560
	ds_read_b32 v67, v2 offset:48112
	ds_read_b32 v69, v0 offset:0
	ds_read_b128 v[10:13], v3 offset:224
	ds_read_b128 v[14:17], v3 offset:240
	s_waitcnt lgkmcnt(0)
	v_fma_f32 v6, -v10, v69, v6
	v_fma_f32 v7, -v11, v69, v7
	v_fma_f32 v9, -v12, v69, v9
	v_fma_f32 v59, -v13, v69, v59
	v_fma_f32 v61, -v14, v69, v61
	v_fma_f32 v63, -v15, v69, v63
	v_fma_f32 v65, -v16, v69, v65
	v_fma_f32 v67, -v17, v69, v67
	ds_read_b32 v71, v0 offset:1552
	ds_read_b128 v[96:99], v3 offset:496
	ds_read_b128 v[100:103], v3 offset:512
	ds_read_b32 v73, v0 offset:3104
	ds_read_b128 v[104:107], v3 offset:768
	ds_read_b128 v[108:111], v3 offset:784
	ds_read_b32 v75, v0 offset:4656
	ds_read_b128 v[112:115], v3 offset:1040
	ds_read_b128 v[188:191], v3 offset:1056
	ds_read_b32 v69, v0 offset:6208
	ds_read_b128 v[10:13], v3 offset:1312
	ds_read_b128 v[14:17], v3 offset:1328
	s_waitcnt lgkmcnt(9)
	v_fma_f32 v6, -v96, v71, v6
	v_fma_f32 v7, -v97, v71, v7
	v_fma_f32 v9, -v98, v71, v9
	v_fma_f32 v59, -v99, v71, v59
	v_fma_f32 v61, -v100, v71, v61
	v_fma_f32 v63, -v101, v71, v63
	v_fma_f32 v65, -v102, v71, v65
	v_fma_f32 v67, -v103, v71, v67
	ds_read_b32 v71, v0 offset:7760
	ds_read_b128 v[96:99], v3 offset:1584
	ds_read_b128 v[100:103], v3 offset:1600
	s_waitcnt lgkmcnt(9)
	v_fma_f32 v6, -v104, v73, v6
	v_fma_f32 v7, -v105, v73, v7
	v_fma_f32 v9, -v106, v73, v9
	v_fma_f32 v59, -v107, v73, v59
	v_fma_f32 v61, -v108, v73, v61
	v_fma_f32 v63, -v109, v73, v63
	v_fma_f32 v65, -v110, v73, v65
	v_fma_f32 v67, -v111, v73, v67
	ds_read_b32 v73, v0 offset:9312
	ds_read_b128 v[104:107], v3 offset:1856
	ds_read_b128 v[108:111], v3 offset:1872
	s_waitcnt lgkmcnt(9)
	v_fma_f32 v6, -v112, v75, v6
	v_fma_f32 v7, -v113, v75, v7
	v_fma_f32 v9, -v114, v75, v9
	v_fma_f32 v59, -v115, v75, v59
	v_fma_f32 v61, -v188, v75, v61
	v_fma_f32 v63, -v189, v75, v63
	v_fma_f32 v65, -v190, v75, v65
	v_fma_f32 v67, -v191, v75, v67
	ds_read_b32 v75, v0 offset:10864
	ds_read_b128 v[112:115], v3 offset:2128
	ds_read_b128 v[188:191], v3 offset:2144
	s_waitcnt lgkmcnt(9)
	v_fma_f32 v6, -v10, v69, v6
	v_fma_f32 v7, -v11, v69, v7
	v_fma_f32 v9, -v12, v69, v9
	v_fma_f32 v59, -v13, v69, v59
	v_fma_f32 v61, -v14, v69, v61
	v_fma_f32 v63, -v15, v69, v63
	v_fma_f32 v65, -v16, v69, v65
	v_fma_f32 v67, -v17, v69, v67
	ds_read_b32 v69, v0 offset:12416
	ds_read_b128 v[10:13], v3 offset:2400
	ds_read_b128 v[14:17], v3 offset:2416
	s_waitcnt lgkmcnt(9)
	v_fma_f32 v6, -v96, v71, v6
	v_fma_f32 v7, -v97, v71, v7
	v_fma_f32 v9, -v98, v71, v9
	v_fma_f32 v59, -v99, v71, v59
	v_fma_f32 v61, -v100, v71, v61
	v_fma_f32 v63, -v101, v71, v63
	v_fma_f32 v65, -v102, v71, v65
	v_fma_f32 v67, -v103, v71, v67
	ds_read_b32 v71, v0 offset:13968
	ds_read_b128 v[96:99], v3 offset:2672
	ds_read_b128 v[100:103], v3 offset:2688
	s_waitcnt lgkmcnt(9)
	v_fma_f32 v6, -v104, v73, v6
	v_fma_f32 v7, -v105, v73, v7
	v_fma_f32 v9, -v106, v73, v9
	v_fma_f32 v59, -v107, v73, v59
	v_fma_f32 v61, -v108, v73, v61
	v_fma_f32 v63, -v109, v73, v63
	v_fma_f32 v65, -v110, v73, v65
	v_fma_f32 v67, -v111, v73, v67
	ds_read_b32 v73, v0 offset:15520
	ds_read_b128 v[104:107], v3 offset:2944
	ds_read_b128 v[108:111], v3 offset:2960
	s_waitcnt lgkmcnt(9)
	v_fma_f32 v6, -v112, v75, v6
	v_fma_f32 v7, -v113, v75, v7
	v_fma_f32 v9, -v114, v75, v9
	v_fma_f32 v59, -v115, v75, v59
	v_fma_f32 v61, -v188, v75, v61
	v_fma_f32 v63, -v189, v75, v63
	v_fma_f32 v65, -v190, v75, v65
	v_fma_f32 v67, -v191, v75, v67
	ds_read_b32 v75, v0 offset:17072
	ds_read_b128 v[112:115], v3 offset:3216
	ds_read_b128 v[188:191], v3 offset:3232
	s_waitcnt lgkmcnt(9)
	v_fma_f32 v6, -v10, v69, v6
	v_fma_f32 v7, -v11, v69, v7
	v_fma_f32 v9, -v12, v69, v9
	v_fma_f32 v59, -v13, v69, v59
	v_fma_f32 v61, -v14, v69, v61
	v_fma_f32 v63, -v15, v69, v63
	v_fma_f32 v65, -v16, v69, v65
	v_fma_f32 v67, -v17, v69, v67
	ds_read_b32 v69, v0 offset:18624
	ds_read_b128 v[10:13], v3 offset:3488
	ds_read_b128 v[14:17], v3 offset:3504
	s_waitcnt lgkmcnt(9)
	v_fma_f32 v6, -v96, v71, v6
	v_fma_f32 v7, -v97, v71, v7
	v_fma_f32 v9, -v98, v71, v9
	v_fma_f32 v59, -v99, v71, v59
	v_fma_f32 v61, -v100, v71, v61
	v_fma_f32 v63, -v101, v71, v63
	v_fma_f32 v65, -v102, v71, v65
	v_fma_f32 v67, -v103, v71, v67
	ds_read_b32 v71, v0 offset:20176
	ds_read_b128 v[96:99], v3 offset:3760
	ds_read_b128 v[100:103], v3 offset:3776
	s_waitcnt lgkmcnt(9)
	v_fma_f32 v6, -v104, v73, v6
	v_fma_f32 v7, -v105, v73, v7
	v_fma_f32 v9, -v106, v73, v9
	v_fma_f32 v59, -v107, v73, v59
	v_fma_f32 v61, -v108, v73, v61
	v_fma_f32 v63, -v109, v73, v63
	v_fma_f32 v65, -v110, v73, v65
	v_fma_f32 v67, -v111, v73, v67
	ds_read_b32 v73, v0 offset:21728
	ds_read_b128 v[104:107], v3 offset:4032
	ds_read_b128 v[108:111], v3 offset:4048
	s_waitcnt lgkmcnt(9)
	v_fma_f32 v6, -v112, v75, v6
	v_fma_f32 v7, -v113, v75, v7
	v_fma_f32 v9, -v114, v75, v9
	v_fma_f32 v59, -v115, v75, v59
	v_fma_f32 v61, -v188, v75, v61
	v_fma_f32 v63, -v189, v75, v63
	v_fma_f32 v65, -v190, v75, v65
	v_fma_f32 v67, -v191, v75, v67
	ds_read_b32 v75, v0 offset:23280
	ds_read_b128 v[112:115], v3 offset:4304
	ds_read_b128 v[188:191], v3 offset:4320
	s_waitcnt lgkmcnt(9)
	v_fma_f32 v6, -v10, v69, v6
	v_fma_f32 v7, -v11, v69, v7
	v_fma_f32 v9, -v12, v69, v9
	v_fma_f32 v59, -v13, v69, v59
	v_fma_f32 v61, -v14, v69, v61
	v_fma_f32 v63, -v15, v69, v63
	v_fma_f32 v65, -v16, v69, v65
	v_fma_f32 v67, -v17, v69, v67
	ds_read_b32 v69, v0 offset:24832
	ds_read_b128 v[10:13], v3 offset:4576
	ds_read_b128 v[14:17], v3 offset:4592
	s_waitcnt lgkmcnt(9)
	v_fma_f32 v6, -v96, v71, v6
	v_fma_f32 v7, -v97, v71, v7
	v_fma_f32 v9, -v98, v71, v9
	v_fma_f32 v59, -v99, v71, v59
	v_fma_f32 v61, -v100, v71, v61
	v_fma_f32 v63, -v101, v71, v63
	v_fma_f32 v65, -v102, v71, v65
	v_fma_f32 v67, -v103, v71, v67
	ds_read_b32 v71, v0 offset:26384
	ds_read_b128 v[96:99], v3 offset:4848
	ds_read_b128 v[100:103], v3 offset:4864
	s_waitcnt lgkmcnt(9)
	v_fma_f32 v6, -v104, v73, v6
	v_fma_f32 v7, -v105, v73, v7
	v_fma_f32 v9, -v106, v73, v9
	v_fma_f32 v59, -v107, v73, v59
	v_fma_f32 v61, -v108, v73, v61
	v_fma_f32 v63, -v109, v73, v63
	v_fma_f32 v65, -v110, v73, v65
	v_fma_f32 v67, -v111, v73, v67
	ds_read_b32 v73, v0 offset:27936
	ds_read_b128 v[104:107], v3 offset:5120
	ds_read_b128 v[108:111], v3 offset:5136
	s_waitcnt lgkmcnt(9)
	v_fma_f32 v6, -v112, v75, v6
	v_fma_f32 v7, -v113, v75, v7
	v_fma_f32 v9, -v114, v75, v9
	v_fma_f32 v59, -v115, v75, v59
	v_fma_f32 v61, -v188, v75, v61
	v_fma_f32 v63, -v189, v75, v63
	v_fma_f32 v65, -v190, v75, v65
	v_fma_f32 v67, -v191, v75, v67
	ds_read_b32 v75, v0 offset:29488
	ds_read_b128 v[112:115], v3 offset:5392
	ds_read_b128 v[188:191], v3 offset:5408
	s_waitcnt lgkmcnt(9)
	v_fma_f32 v6, -v10, v69, v6
	v_fma_f32 v7, -v11, v69, v7
	v_fma_f32 v9, -v12, v69, v9
	v_fma_f32 v59, -v13, v69, v59
	v_fma_f32 v61, -v14, v69, v61
	v_fma_f32 v63, -v15, v69, v63
	v_fma_f32 v65, -v16, v69, v65
	v_fma_f32 v67, -v17, v69, v67
	ds_read_b32 v69, v0 offset:31040
	ds_read_b128 v[10:13], v3 offset:5664
	ds_read_b128 v[14:17], v3 offset:5680
	s_waitcnt lgkmcnt(9)
	v_fma_f32 v6, -v96, v71, v6
	v_fma_f32 v7, -v97, v71, v7
	v_fma_f32 v9, -v98, v71, v9
	v_fma_f32 v59, -v99, v71, v59
	v_fma_f32 v61, -v100, v71, v61
	v_fma_f32 v63, -v101, v71, v63
	v_fma_f32 v65, -v102, v71, v65
	v_fma_f32 v67, -v103, v71, v67
	ds_read_b32 v71, v0 offset:32592
	ds_read_b128 v[96:99], v3 offset:5936
	ds_read_b128 v[100:103], v3 offset:5952
	s_waitcnt lgkmcnt(9)
	v_fma_f32 v6, -v104, v73, v6
	v_fma_f32 v7, -v105, v73, v7
	v_fma_f32 v9, -v106, v73, v9
	v_fma_f32 v59, -v107, v73, v59
	v_fma_f32 v61, -v108, v73, v61
	v_fma_f32 v63, -v109, v73, v63
	v_fma_f32 v65, -v110, v73, v65
	v_fma_f32 v67, -v111, v73, v67
	ds_read_b32 v73, v0 offset:34144
	ds_read_b128 v[104:107], v3 offset:6208
	ds_read_b128 v[108:111], v3 offset:6224
	s_waitcnt lgkmcnt(9)
	v_fma_f32 v6, -v112, v75, v6
	v_fma_f32 v7, -v113, v75, v7
	v_fma_f32 v9, -v114, v75, v9
	v_fma_f32 v59, -v115, v75, v59
	v_fma_f32 v61, -v188, v75, v61
	v_fma_f32 v63, -v189, v75, v63
	v_fma_f32 v65, -v190, v75, v65
	v_fma_f32 v67, -v191, v75, v67
	ds_read_b32 v75, v0 offset:35696
	ds_read_b128 v[112:115], v3 offset:6480
	ds_read_b128 v[188:191], v3 offset:6496
	s_waitcnt lgkmcnt(9)
	v_fma_f32 v6, -v10, v69, v6
	v_fma_f32 v7, -v11, v69, v7
	v_fma_f32 v9, -v12, v69, v9
	v_fma_f32 v59, -v13, v69, v59
	v_fma_f32 v61, -v14, v69, v61
	v_fma_f32 v63, -v15, v69, v63
	v_fma_f32 v65, -v16, v69, v65
	v_fma_f32 v67, -v17, v69, v67
	ds_read_b32 v69, v0 offset:37248
	ds_read_b128 v[10:13], v3 offset:6752
	ds_read_b128 v[14:17], v3 offset:6768
	s_waitcnt lgkmcnt(9)
	v_fma_f32 v6, -v96, v71, v6
	v_fma_f32 v7, -v97, v71, v7
	v_fma_f32 v9, -v98, v71, v9
	v_fma_f32 v59, -v99, v71, v59
	v_fma_f32 v61, -v100, v71, v61
	v_fma_f32 v63, -v101, v71, v63
	v_fma_f32 v65, -v102, v71, v65
	v_fma_f32 v67, -v103, v71, v67
	ds_read_b32 v71, v0 offset:38800
	ds_read_b128 v[96:99], v3 offset:7024
	ds_read_b128 v[100:103], v3 offset:7040
	s_waitcnt lgkmcnt(9)
	v_fma_f32 v6, -v104, v73, v6
	v_fma_f32 v7, -v105, v73, v7
	v_fma_f32 v9, -v106, v73, v9
	v_fma_f32 v59, -v107, v73, v59
	v_fma_f32 v61, -v108, v73, v61
	v_fma_f32 v63, -v109, v73, v63
	v_fma_f32 v65, -v110, v73, v65
	v_fma_f32 v67, -v111, v73, v67
	ds_read_b32 v73, v0 offset:40352
	ds_read_b128 v[104:107], v3 offset:7296
	ds_read_b128 v[108:111], v3 offset:7312
	s_waitcnt lgkmcnt(9)
	v_fma_f32 v6, -v112, v75, v6
	v_fma_f32 v7, -v113, v75, v7
	v_fma_f32 v9, -v114, v75, v9
	v_fma_f32 v59, -v115, v75, v59
	v_fma_f32 v61, -v188, v75, v61
	v_fma_f32 v63, -v189, v75, v63
	v_fma_f32 v65, -v190, v75, v65
	v_fma_f32 v67, -v191, v75, v67
	ds_read_b32 v75, v0 offset:41904
	ds_read_b128 v[112:115], v3 offset:7568
	ds_read_b128 v[188:191], v3 offset:7584
	s_waitcnt lgkmcnt(9)
	v_fma_f32 v6, -v10, v69, v6
	v_fma_f32 v7, -v11, v69, v7
	v_fma_f32 v9, -v12, v69, v9
	v_fma_f32 v59, -v13, v69, v59
	v_fma_f32 v61, -v14, v69, v61
	v_fma_f32 v63, -v15, v69, v63
	v_fma_f32 v65, -v16, v69, v65
	v_fma_f32 v67, -v17, v69, v67
	ds_read_b32 v69, v0 offset:43456
	ds_read_b128 v[10:13], v3 offset:7840
	ds_read_b128 v[14:17], v3 offset:7856
	s_waitcnt lgkmcnt(9)
	v_fma_f32 v6, -v96, v71, v6
	v_fma_f32 v7, -v97, v71, v7
	v_fma_f32 v9, -v98, v71, v9
	v_fma_f32 v59, -v99, v71, v59
	v_fma_f32 v61, -v100, v71, v61
	v_fma_f32 v63, -v101, v71, v63
	v_fma_f32 v65, -v102, v71, v65
	v_fma_f32 v67, -v103, v71, v67
	ds_read_b32 v71, v0 offset:45008
	ds_read_b128 v[96:99], v3 offset:8112
	ds_read_b128 v[100:103], v3 offset:8128
	s_waitcnt lgkmcnt(9)
	v_fma_f32 v6, -v104, v73, v6
	v_fma_f32 v7, -v105, v73, v7
	v_fma_f32 v9, -v106, v73, v9
	v_fma_f32 v59, -v107, v73, v59
	v_fma_f32 v61, -v108, v73, v61
	v_fma_f32 v63, -v109, v73, v63
	v_fma_f32 v65, -v110, v73, v65
	v_fma_f32 v67, -v111, v73, v67
	ds_read_b32 v73, v0 offset:46560
	ds_read_b128 v[104:107], v3 offset:8384
	ds_read_b128 v[108:111], v3 offset:8400
	s_waitcnt lgkmcnt(9)
	v_fma_f32 v6, -v112, v75, v6
	v_fma_f32 v7, -v113, v75, v7
	v_fma_f32 v9, -v114, v75, v9
	v_fma_f32 v59, -v115, v75, v59
	v_fma_f32 v61, -v188, v75, v61
	v_fma_f32 v63, -v189, v75, v63
	v_fma_f32 v65, -v190, v75, v65
	v_fma_f32 v67, -v191, v75, v67
	ds_read_b32 v75, v0 offset:48112
	ds_read_b128 v[112:115], v3 offset:8656
	ds_read_b128 v[188:191], v3 offset:8672
	s_waitcnt lgkmcnt(9)
	v_fma_f32 v6, -v10, v69, v6
	v_fma_f32 v7, -v11, v69, v7
	v_fma_f32 v9, -v12, v69, v9
	v_fma_f32 v59, -v13, v69, v59
	v_fma_f32 v61, -v14, v69, v61
	v_fma_f32 v63, -v15, v69, v63
	v_fma_f32 v65, -v16, v69, v65
	v_fma_f32 v67, -v17, v69, v67
	ds_read_b32 v69, v2 offset:0
	ds_read_b128 v[10:13], v3 offset:8928
	ds_read_b128 v[14:17], v3 offset:8944
	s_waitcnt lgkmcnt(9)
	v_fma_f32 v6, -v96, v71, v6
	v_fma_f32 v7, -v97, v71, v7
	v_fma_f32 v9, -v98, v71, v9
	v_fma_f32 v59, -v99, v71, v59
	v_fma_f32 v61, -v100, v71, v61
	v_fma_f32 v63, -v101, v71, v63
	v_fma_f32 v65, -v102, v71, v65
	v_fma_f32 v67, -v103, v71, v67
	ds_read_b32 v71, v2 offset:1552
	ds_read_b128 v[96:99], v3 offset:9200
	ds_read_b128 v[100:103], v3 offset:9216
	s_waitcnt lgkmcnt(9)
	v_fma_f32 v6, -v104, v73, v6
	v_fma_f32 v7, -v105, v73, v7
	v_fma_f32 v9, -v106, v73, v9
	v_fma_f32 v59, -v107, v73, v59
	v_fma_f32 v61, -v108, v73, v61
	v_fma_f32 v63, -v109, v73, v63
	v_fma_f32 v65, -v110, v73, v65
	v_fma_f32 v67, -v111, v73, v67
	ds_read_b32 v73, v2 offset:3104
	ds_read_b128 v[104:107], v3 offset:9472
	ds_read_b128 v[108:111], v3 offset:9488
	s_waitcnt lgkmcnt(9)
	v_fma_f32 v6, -v112, v75, v6
	v_fma_f32 v7, -v113, v75, v7
	v_fma_f32 v9, -v114, v75, v9
	v_fma_f32 v59, -v115, v75, v59
	v_fma_f32 v61, -v188, v75, v61
	v_fma_f32 v63, -v189, v75, v63
	v_fma_f32 v65, -v190, v75, v65
	v_fma_f32 v67, -v191, v75, v67
	ds_read_b32 v75, v2 offset:4656
	ds_read_b128 v[112:115], v3 offset:9744
	ds_read_b128 v[188:191], v3 offset:9760
	s_waitcnt lgkmcnt(9)
	v_fma_f32 v6, -v10, v69, v6
	v_fma_f32 v7, -v11, v69, v7
	v_fma_f32 v9, -v12, v69, v9
	v_fma_f32 v59, -v13, v69, v59
	v_fma_f32 v61, -v14, v69, v61
	v_fma_f32 v63, -v15, v69, v63
	v_fma_f32 v65, -v16, v69, v65
	v_fma_f32 v67, -v17, v69, v67
	ds_read_b32 v69, v2 offset:6208
	ds_read_b128 v[10:13], v3 offset:10016
	ds_read_b128 v[14:17], v3 offset:10032
	s_waitcnt lgkmcnt(9)
	v_fma_f32 v6, -v96, v71, v6
	v_fma_f32 v7, -v97, v71, v7
	v_fma_f32 v9, -v98, v71, v9
	v_fma_f32 v59, -v99, v71, v59
	v_fma_f32 v61, -v100, v71, v61
	v_fma_f32 v63, -v101, v71, v63
	v_fma_f32 v65, -v102, v71, v65
	v_fma_f32 v67, -v103, v71, v67
	ds_read_b32 v71, v2 offset:7760
	ds_read_b128 v[96:99], v3 offset:10288
	ds_read_b128 v[100:103], v3 offset:10304
	s_waitcnt lgkmcnt(9)
	v_fma_f32 v6, -v104, v73, v6
	v_fma_f32 v7, -v105, v73, v7
	v_fma_f32 v9, -v106, v73, v9
	v_fma_f32 v59, -v107, v73, v59
	v_fma_f32 v61, -v108, v73, v61
	v_fma_f32 v63, -v109, v73, v63
	v_fma_f32 v65, -v110, v73, v65
	v_fma_f32 v67, -v111, v73, v67
	ds_read_b32 v73, v2 offset:9312
	ds_read_b128 v[104:107], v3 offset:10560
	ds_read_b128 v[108:111], v3 offset:10576
	s_waitcnt lgkmcnt(9)
	v_fma_f32 v6, -v112, v75, v6
	v_fma_f32 v7, -v113, v75, v7
	v_fma_f32 v9, -v114, v75, v9
	v_fma_f32 v59, -v115, v75, v59
	v_fma_f32 v61, -v188, v75, v61
	v_fma_f32 v63, -v189, v75, v63
	v_fma_f32 v65, -v190, v75, v65
	v_fma_f32 v67, -v191, v75, v67
	ds_read_b32 v75, v2 offset:10864
	ds_read_b128 v[112:115], v3 offset:10832
	ds_read_b128 v[188:191], v3 offset:10848
	s_waitcnt lgkmcnt(9)
	v_fma_f32 v6, -v10, v69, v6
	v_fma_f32 v7, -v11, v69, v7
	v_fma_f32 v9, -v12, v69, v9
	v_fma_f32 v59, -v13, v69, v59
	v_fma_f32 v61, -v14, v69, v61
	v_fma_f32 v63, -v15, v69, v63
	v_fma_f32 v65, -v16, v69, v65
	v_fma_f32 v67, -v17, v69, v67
	ds_read_b32 v69, v2 offset:12416
	ds_read_b128 v[10:13], v3 offset:11104
	ds_read_b128 v[14:17], v3 offset:11120
	s_waitcnt lgkmcnt(9)
	v_fma_f32 v6, -v96, v71, v6
	v_fma_f32 v7, -v97, v71, v7
	v_fma_f32 v9, -v98, v71, v9
	v_fma_f32 v59, -v99, v71, v59
	v_fma_f32 v61, -v100, v71, v61
	v_fma_f32 v63, -v101, v71, v63
	v_fma_f32 v65, -v102, v71, v65
	v_fma_f32 v67, -v103, v71, v67
	ds_read_b32 v71, v2 offset:13968
	ds_read_b128 v[96:99], v3 offset:11376
	ds_read_b128 v[100:103], v3 offset:11392
	s_waitcnt lgkmcnt(9)
	v_fma_f32 v6, -v104, v73, v6
	v_fma_f32 v7, -v105, v73, v7
	v_fma_f32 v9, -v106, v73, v9
	v_fma_f32 v59, -v107, v73, v59
	v_fma_f32 v61, -v108, v73, v61
	v_fma_f32 v63, -v109, v73, v63
	v_fma_f32 v65, -v110, v73, v65
	v_fma_f32 v67, -v111, v73, v67
	ds_read_b32 v73, v2 offset:15520
	ds_read_b128 v[104:107], v3 offset:11648
	ds_read_b128 v[108:111], v3 offset:11664
	s_waitcnt lgkmcnt(9)
	v_fma_f32 v6, -v112, v75, v6
	v_fma_f32 v7, -v113, v75, v7
	v_fma_f32 v9, -v114, v75, v9
	v_fma_f32 v59, -v115, v75, v59
	v_fma_f32 v61, -v188, v75, v61
	v_fma_f32 v63, -v189, v75, v63
	v_fma_f32 v65, -v190, v75, v65
	v_fma_f32 v67, -v191, v75, v67
	ds_read_b32 v75, v2 offset:17072
	ds_read_b128 v[112:115], v3 offset:11920
	ds_read_b128 v[188:191], v3 offset:11936
	s_waitcnt lgkmcnt(9)
	v_fma_f32 v6, -v10, v69, v6
	v_fma_f32 v7, -v11, v69, v7
	v_fma_f32 v9, -v12, v69, v9
	v_fma_f32 v59, -v13, v69, v59
	v_fma_f32 v61, -v14, v69, v61
	v_fma_f32 v63, -v15, v69, v63
	v_fma_f32 v65, -v16, v69, v65
	v_fma_f32 v67, -v17, v69, v67
	ds_read_b32 v69, v2 offset:18624
	ds_read_b128 v[10:13], v3 offset:12192
	ds_read_b128 v[14:17], v3 offset:12208
	s_waitcnt lgkmcnt(9)
	v_fma_f32 v6, -v96, v71, v6
	v_fma_f32 v7, -v97, v71, v7
	v_fma_f32 v9, -v98, v71, v9
	v_fma_f32 v59, -v99, v71, v59
	v_fma_f32 v61, -v100, v71, v61
	v_fma_f32 v63, -v101, v71, v63
	v_fma_f32 v65, -v102, v71, v65
	v_fma_f32 v67, -v103, v71, v67
	ds_read_b32 v71, v2 offset:20176
	ds_read_b128 v[96:99], v3 offset:12464
	ds_read_b128 v[100:103], v3 offset:12480
	s_waitcnt lgkmcnt(9)
	v_fma_f32 v6, -v104, v73, v6
	v_fma_f32 v7, -v105, v73, v7
	v_fma_f32 v9, -v106, v73, v9
	v_fma_f32 v59, -v107, v73, v59
	v_fma_f32 v61, -v108, v73, v61
	v_fma_f32 v63, -v109, v73, v63
	v_fma_f32 v65, -v110, v73, v65
	v_fma_f32 v67, -v111, v73, v67
	ds_read_b32 v73, v2 offset:21728
	ds_read_b128 v[104:107], v3 offset:12736
	ds_read_b128 v[108:111], v3 offset:12752
	s_waitcnt lgkmcnt(9)
	v_fma_f32 v6, -v112, v75, v6
	v_fma_f32 v7, -v113, v75, v7
	v_fma_f32 v9, -v114, v75, v9
	v_fma_f32 v59, -v115, v75, v59
	v_fma_f32 v61, -v188, v75, v61
	v_fma_f32 v63, -v189, v75, v63
	v_fma_f32 v65, -v190, v75, v65
	v_fma_f32 v67, -v191, v75, v67
	ds_read_b32 v75, v2 offset:23280
	ds_read_b128 v[112:115], v3 offset:13008
	ds_read_b128 v[188:191], v3 offset:13024
	s_waitcnt lgkmcnt(9)
	v_fma_f32 v6, -v10, v69, v6
	v_fma_f32 v7, -v11, v69, v7
	v_fma_f32 v9, -v12, v69, v9
	v_fma_f32 v59, -v13, v69, v59
	v_fma_f32 v61, -v14, v69, v61
	v_fma_f32 v63, -v15, v69, v63
	v_fma_f32 v65, -v16, v69, v65
	v_fma_f32 v67, -v17, v69, v67
	ds_read_b32 v69, v2 offset:24832
	ds_read_b128 v[10:13], v3 offset:13280
	ds_read_b128 v[14:17], v3 offset:13296
	s_waitcnt lgkmcnt(9)
	v_fma_f32 v6, -v96, v71, v6
	v_fma_f32 v7, -v97, v71, v7
	v_fma_f32 v9, -v98, v71, v9
	v_fma_f32 v59, -v99, v71, v59
	v_fma_f32 v61, -v100, v71, v61
	v_fma_f32 v63, -v101, v71, v63
	v_fma_f32 v65, -v102, v71, v65
	v_fma_f32 v67, -v103, v71, v67
	ds_read_b32 v71, v2 offset:26384
	ds_read_b128 v[96:99], v3 offset:13552
	ds_read_b128 v[100:103], v3 offset:13568
	s_waitcnt lgkmcnt(9)
	v_fma_f32 v6, -v104, v73, v6
	v_fma_f32 v7, -v105, v73, v7
	v_fma_f32 v9, -v106, v73, v9
	v_fma_f32 v59, -v107, v73, v59
	v_fma_f32 v61, -v108, v73, v61
	v_fma_f32 v63, -v109, v73, v63
	v_fma_f32 v65, -v110, v73, v65
	v_fma_f32 v67, -v111, v73, v67
	ds_read_b32 v73, v2 offset:27936
	ds_read_b128 v[104:107], v3 offset:13824
	ds_read_b128 v[108:111], v3 offset:13840
	s_waitcnt lgkmcnt(9)
	v_fma_f32 v6, -v112, v75, v6
	v_fma_f32 v7, -v113, v75, v7
	v_fma_f32 v9, -v114, v75, v9
	v_fma_f32 v59, -v115, v75, v59
	v_fma_f32 v61, -v188, v75, v61
	v_fma_f32 v63, -v189, v75, v63
	v_fma_f32 v65, -v190, v75, v65
	v_fma_f32 v67, -v191, v75, v67
	ds_read_b32 v75, v2 offset:29488
	ds_read_b128 v[112:115], v3 offset:14096
	ds_read_b128 v[188:191], v3 offset:14112
	s_waitcnt lgkmcnt(9)
	v_fma_f32 v6, -v10, v69, v6
	v_fma_f32 v7, -v11, v69, v7
	v_fma_f32 v9, -v12, v69, v9
	v_fma_f32 v59, -v13, v69, v59
	v_fma_f32 v61, -v14, v69, v61
	v_fma_f32 v63, -v15, v69, v63
	v_fma_f32 v65, -v16, v69, v65
	v_fma_f32 v67, -v17, v69, v67
	ds_read_b32 v69, v2 offset:31040
	ds_read_b128 v[10:13], v3 offset:14368
	ds_read_b128 v[14:17], v3 offset:14384
	s_waitcnt lgkmcnt(9)
	v_fma_f32 v6, -v96, v71, v6
	v_fma_f32 v7, -v97, v71, v7
	v_fma_f32 v9, -v98, v71, v9
	v_fma_f32 v59, -v99, v71, v59
	v_fma_f32 v61, -v100, v71, v61
	v_fma_f32 v63, -v101, v71, v63
	v_fma_f32 v65, -v102, v71, v65
	v_fma_f32 v67, -v103, v71, v67
	ds_read_b32 v71, v2 offset:32592
	ds_read_b128 v[96:99], v3 offset:14640
	ds_read_b128 v[100:103], v3 offset:14656
	s_waitcnt lgkmcnt(9)
	v_fma_f32 v6, -v104, v73, v6
	v_fma_f32 v7, -v105, v73, v7
	v_fma_f32 v9, -v106, v73, v9
	v_fma_f32 v59, -v107, v73, v59
	v_fma_f32 v61, -v108, v73, v61
	v_fma_f32 v63, -v109, v73, v63
	v_fma_f32 v65, -v110, v73, v65
	v_fma_f32 v67, -v111, v73, v67
	ds_read_b32 v73, v2 offset:34144
	ds_read_b128 v[104:107], v3 offset:14912
	ds_read_b128 v[108:111], v3 offset:14928
	s_waitcnt lgkmcnt(9)
	v_fma_f32 v6, -v112, v75, v6
	v_fma_f32 v7, -v113, v75, v7
	v_fma_f32 v9, -v114, v75, v9
	v_fma_f32 v59, -v115, v75, v59
	v_fma_f32 v61, -v188, v75, v61
	v_fma_f32 v63, -v189, v75, v63
	v_fma_f32 v65, -v190, v75, v65
	v_fma_f32 v67, -v191, v75, v67
	ds_read_b32 v75, v2 offset:35696
	ds_read_b128 v[112:115], v3 offset:15184
	ds_read_b128 v[188:191], v3 offset:15200
	s_waitcnt lgkmcnt(9)
	v_fma_f32 v6, -v10, v69, v6
	v_fma_f32 v7, -v11, v69, v7
	v_fma_f32 v9, -v12, v69, v9
	v_fma_f32 v59, -v13, v69, v59
	v_fma_f32 v61, -v14, v69, v61
	v_fma_f32 v63, -v15, v69, v63
	v_fma_f32 v65, -v16, v69, v65
	v_fma_f32 v67, -v17, v69, v67
	ds_read_b128 v[194:197], v3 offset:15456
	ds_read_b128 v[198:201], v3 offset:15472
	s_waitcnt lgkmcnt(8)
	v_fma_f32 v6, -v96, v71, v6
	v_fma_f32 v7, -v97, v71, v7
	v_fma_f32 v9, -v98, v71, v9
	v_fma_f32 v59, -v99, v71, v59
	v_fma_f32 v61, -v100, v71, v61
	v_fma_f32 v63, -v101, v71, v63
	v_fma_f32 v65, -v102, v71, v65
	v_fma_f32 v67, -v103, v71, v67
	ds_read_b128 v[202:205], v3 offset:15728
	ds_read_b128 v[206:209], v3 offset:15744
	s_waitcnt lgkmcnt(7)
	v_fma_f32 v6, -v104, v73, v6
	v_fma_f32 v7, -v105, v73, v7
	v_fma_f32 v9, -v106, v73, v9
	v_fma_f32 v59, -v107, v73, v59
	v_fma_f32 v61, -v108, v73, v61
	v_fma_f32 v63, -v109, v73, v63
	v_fma_f32 v65, -v110, v73, v65
	v_fma_f32 v67, -v111, v73, v67
	ds_read_b128 v[220:223], v3 offset:16000
	ds_read_b128 v[226:229], v3 offset:16016
	s_waitcnt lgkmcnt(6)
	v_fma_f32 v6, -v112, v75, v6
	v_fma_f32 v7, -v113, v75, v7
	v_fma_f32 v9, -v114, v75, v9
	v_fma_f32 v59, -v115, v75, v59
	v_fma_f32 v61, -v188, v75, v61
	v_fma_f32 v63, -v189, v75, v63
	v_fma_f32 v65, -v190, v75, v65
	v_fma_f32 v67, -v191, v75, v67
	ds_read_b128 v[230:233], v3 offset:16288
	s_waitcnt lgkmcnt(5)
	v_fma_f32 v7, -v195, v6, v7
	v_fma_f32 v9, -v196, v6, v9
	v_fma_f32 v59, -v197, v6, v59
	v_fma_f32 v61, -v198, v6, v61
	v_fma_f32 v63, -v199, v6, v63
	v_fma_f32 v65, -v200, v6, v65
	v_fma_f32 v67, -v201, v6, v67
	ds_read_b128 v[234:237], v3 offset:16560
	s_waitcnt lgkmcnt(4)
	v_fma_f32 v9, -v204, v7, v9
	v_fma_f32 v59, -v205, v7, v59
	v_fma_f32 v61, -v206, v7, v61
	v_fma_f32 v63, -v207, v7, v63
	v_fma_f32 v65, -v208, v7, v65
	v_fma_f32 v67, -v209, v7, v67
	ds_read_b128 v[238:241], v3 offset:16832
	s_waitcnt lgkmcnt(3)
	v_fma_f32 v59, -v223, v9, v59
	v_fma_f32 v61, -v226, v9, v61
	v_fma_f32 v63, -v227, v9, v63
	v_fma_f32 v65, -v228, v9, v65
	v_fma_f32 v67, -v229, v9, v67
	ds_read_b128 v[242:245], v3 offset:17104
	s_waitcnt lgkmcnt(3)
	v_fma_f32 v61, -v230, v59, v61
	v_fma_f32 v63, -v231, v59, v63
	v_fma_f32 v65, -v232, v59, v65
	v_fma_f32 v67, -v233, v59, v67
	s_waitcnt lgkmcnt(2)
	v_fma_f32 v63, -v235, v61, v63
	v_fma_f32 v65, -v236, v61, v65
	v_fma_f32 v67, -v237, v61, v67
	s_waitcnt lgkmcnt(1)
	v_fma_f32 v65, -v240, v63, v65
	v_fma_f32 v67, -v241, v63, v67
	s_waitcnt lgkmcnt(0)
	v_fma_f32 v67, -v245, v65, v67
	s_nop 0
	ds_write_b32 v2, v6 offset:37248
	ds_write_b32 v2, v7 offset:38800
	ds_write_b32 v2, v9 offset:40352
	ds_write_b32 v2, v59 offset:41904
	ds_write_b32 v2, v61 offset:43456
	ds_write_b32 v2, v63 offset:45008
	ds_write_b32 v2, v65 offset:46560
	ds_write_b32 v2, v67 offset:48112
	s_branch .LBB0_972
